# conv per-channel parameters loaded once per phase instead of per tile
# speedup vs baseline: 1.0072x; 1.0072x over previous
; __device__ __forceinline__ void conv_phase(LAS unsigned char* lds, const bf16_t* U, bf16_t* C, const float* wdw, const float* bdw, const float* lng, const float* lnb,
;                                            int first, int stride, int end, int tid, int wave, int lane) {
;     ...
;     for (int tile = first; tile < end; tile += stride) {
;         const int t0 = tile * TT, tin = t0 % SEQ;
;         for (int idx = tid; idx < ROWS * 128; idx += NTHREADS) {
;             const int row = idx >> 7, ch = idx & 127;
;             u32x4 v = (u32x4){0u, 0u, 0u, 0u};
;             if (tin + row - (CW - 1) >= 0) v = *(const u32x4*)(U + (size_t)(t0 + row - (CW - 1)) * D + ch * 8);
;             *(LAS u32x4*)(lds + row * 2048 + ch * 16) = v;
;         }
;         asm volatile("s_waitcnt lgkmcnt(0)" ::: "memory"); __builtin_amdgcn_s_barrier(); asm volatile("" ::: "memory");
;         typedef float f32x2 __attribute__((ext_vector_type(2)));
;         f32x2 acc[2][4][4];
; #pragma unroll
;         for (int p = 0; p < 2; ++p) {
; #pragma unroll
;             for (int j = 0; j < 4; ++j)
; #pragma unroll
;                 for (int c = 0; c < 4; ++c) acc[p][j][c] = (f32x2){0.f, 0.f};
;             f32x4 wt[8][2];
;             typedef const __attribute__((address_space(1))) f32x4 gf32x4;
;             const gf32x4* wq = (const gf32x4*)(wdw + p * 512 + lane * 8);
; #pragma unroll
;             for (int t = 0; t < 4; ++t) { wt[t][0] = wq[0]; wt[t][1] = wq[1]; wq += D / 4; asm volatile("" : "+v"(wq)); }
; #pragma unroll
;             for (int r = 0; r < TT / NWAVES + CW - 1; ++r) {
;                 if (r + 4 < CW) { wt[(r + 4) & 7][0] = wq[0]; wt[(r + 4) & 7][1] = wq[1]; wq += D / 4; asm volatile("" : "+v"(wq)); }
;                 const u32x4 xv = *(const LAS u32x4*)(lds + (4 * wave + r) * 2048 + p * 1024 + lane * 16);
;                 f32x2 x[4];
; #pragma unroll
;                 for (int i = 0; i < 4; ++i) x[i] = (f32x2){__uint_as_float(xv[i] << 16), __uint_as_float(xv[i] & 0xffff0000u)};
; #pragma unroll
;                 for (int j = 0; j < 4; ++j) { const int w = r - j;
;                     if (w >= 0 && w < CW) {
; #pragma unroll
;                         for (int c = 0; c < 4; ++c) { const f32x4 wv = wt[w & 7][c >> 1]; const f32x2 w2 = (c & 1) ? (f32x2){wv.z, wv.w} : (f32x2){wv.x, wv.y}; acc[p][j][c] = __builtin_elementwise_fma(w2, x[c], acc[p][j][c]); } } }
.LBB0_85:
	s_ashr_i32 s30, s40, 6
	v_and_b32_e32 v232, 63, v132
	v_writelane_b32 v255, s30, 25
	s_and_b64 vcc, exec, s[28:29]
	s_cbranch_vccz .LBB0_111
	v_readlane_b32 s4, v255, 23
	v_mov_b32_e32 v0, s90
	v_readlane_b32 s5, v255, 24
	v_cndmask_b32_e64 v133, v233, v0, s[38:39]
	s_andn2_b64 vcc, exec, s[4:5]
	s_mov_b64 s[4:5], -1
	s_cbranch_vccnz .LBB0_97
	v_readlane_b32 s4, v253, 57
	s_add_i32 s37, s37, s4
	s_and_b64 s[4:5], s[38:39], exec
	v_readlane_b32 s4, v253, 40
	v_readlane_b32 s5, v253, 58
	s_cselect_b32 s4, s4, s37
	s_cselect_b32 s37, 0x400, s5
	s_cmp_ge_i32 s4, s37
	s_cbranch_scc1 .LBB0_96
	s_movk_i32 s5, 0x1f00
	v_readlane_b32 s48, v253, 2
	v_readlane_b32 s28, v255, 25
	v_cmp_gt_i32_e32 vcc, s5, v132
	v_lshlrev_b32_e32 v176, 5, v232
	v_readlane_b32 s49, v253, 3
	v_readlane_b32 s50, v253, 4
	v_readlane_b32 s51, v253, 5
	v_readlane_b32 s52, v253, 6
	v_readlane_b32 s53, v253, 7
	v_readlane_b32 s54, v253, 8
	v_readlane_b32 s55, v253, 9
	v_readlane_b32 s56, v253, 10
	v_readlane_b32 s57, v253, 11
	v_readlane_b32 s58, v253, 12
	v_readlane_b32 s59, v253, 13
	v_readlane_b32 s60, v253, 14
	v_readlane_b32 s61, v253, 15
	v_readlane_b32 s62, v253, 16
	v_readlane_b32 s63, v253, 17
	s_lshl_b32 s5, s28, 13
	s_add_i32 s5, s5, 0
	v_lshl_add_u64 v[84:85], s[62:63], 0, v[176:177]
	v_readlane_b32 s48, v253, 18
	v_lshlrev_b32_e32 v0, 4, v232
	v_mov_b32_e32 v1, v177
	v_readlane_b32 s49, v253, 19
	v_readlane_b32 s50, v253, 20
	v_readlane_b32 s51, v253, 21
	v_readlane_b32 s52, v253, 22
	v_readlane_b32 s53, v253, 23
	v_add_u32_e32 v134, s5, v0
	v_lshl_add_u64 v[92:93], s[26:27], 0, v[0:1]
	v_lshlrev_b32_e32 v0, 4, v132
	v_lshl_add_u64 v[86:87], s[48:49], 0, v[176:177]
	v_lshl_add_u64 v[88:89], s[50:51], 0, v[176:177]
	v_lshl_add_u64 v[90:91], s[52:53], 0, v[176:177]
	s_lshl_b32 s48, s28, 2
	v_and_b32_e32 v176, 0x7f0, v0
	s_mov_b64 s[28:29], 0x1800
	v_lshl_add_u64 v[94:95], s[24:25], 0, v[176:177]
	v_add_u32_e32 v135, 0, v176
	v_lshl_add_u64 v[96:97], v[84:85], 0, s[0:1]
	v_add_u32_e32 v136, 0x10000, v134
	v_add_u32_e32 v137, 0x10800, v134
	v_lshl_add_u64 v[98:99], v[84:85], 0, s[28:29]
	v_add_u32_e32 v138, 0x10400, v134
	v_add_u32_e32 v139, 0x10c00, v134
	s_mov_b64 s[46:47], 0
	v_mov_b32_e32 v140, s4
	v_readlane_b32 s54, v253, 24
	v_readlane_b32 s55, v253, 25
	v_readlane_b32 s56, v253, 26
	v_readlane_b32 s57, v253, 27
	v_readlane_b32 s58, v253, 28
	v_readlane_b32 s59, v253, 29
	v_readlane_b32 s60, v253, 30
	v_readlane_b32 s61, v253, 31
	v_readlane_b32 s62, v253, 32
	v_readlane_b32 s63, v253, 33
	global_load_dwordx4 v[180:183], v[86:87], off offset:16
	global_load_dwordx4 v[184:187], v[86:87], off
	global_load_dwordx4 v[188:191], v[86:87], off offset:2064
	global_load_dwordx4 v[192:195], v[86:87], off offset:2048
	global_load_dwordx4 v[196:199], v[88:89], off offset:16
	global_load_dwordx4 v[200:203], v[88:89], off
	global_load_dwordx4 v[204:207], v[90:91], off offset:16
	global_load_dwordx4 v[208:211], v[90:91], off
	global_load_dwordx4 v[212:215], v[88:89], off offset:2064
	global_load_dwordx4 v[236:239], v[88:89], off offset:2048
	global_load_dwordx4 v[240:243], v[90:91], off offset:2064
	global_load_dwordx4 v[244:247], v[90:91], off offset:2048
	s_branch .LBB0_90
.LBB0_89:
	s_or_b64 exec, exec, s[4:5]
	s_waitcnt lgkmcnt(0)
	s_barrier
	global_load_dwordx4 v[56:59], v[84:85], off offset:16
	global_load_dwordx4 v[60:63], v[84:85], off
	v_mov_b64_e32 v[0:1], v[96:97]
	global_load_dwordx4 v[48:51], v[0:1], off offset:16
	global_load_dwordx4 v[52:55], v[0:1], off
	v_lshl_add_u64 v[0:1], v[0:1], 0, s[0:1]
	global_load_dwordx4 v[40:43], v[0:1], off offset:16
	global_load_dwordx4 v[44:47], v[0:1], off
	v_lshl_add_u64 v[0:1], v[0:1], 0, s[0:1]
	global_load_dwordx4 v[24:27], v[0:1], off offset:16
	global_load_dwordx4 v[28:31], v[0:1], off
	v_lshl_add_u64 v[8:9], v[0:1], 0, s[0:1]
	global_load_dwordx4 v[0:3], v[8:9], off offset:16
	global_load_dwordx4 v[4:7], v[8:9], off
	v_lshl_add_u64 v[16:17], v[8:9], 0, s[0:1]
	ds_read_b128 v[8:11], v134
	v_lshl_add_u64 v[36:37], v[16:17], 0, s[0:1]
	v_cmp_lt_i32_e64 s[40:41], v226, v225
	s_mov_b32 s4, 0x3727c5ac
	s_waitcnt lgkmcnt(0)
	v_lshlrev_b32_e32 v12, 16, v11
	v_and_b32_e32 v13, 0xffff0000, v11
	v_lshlrev_b32_e32 v14, 16, v10
	v_and_b32_e32 v15, 0xffff0000, v10
	v_lshlrev_b32_e32 v10, 16, v9
	v_and_b32_e32 v11, 0xffff0000, v9
	v_lshlrev_b32_e32 v18, 16, v8
	v_and_b32_e32 v19, 0xffff0000, v8
	v_add_u32_e32 v140, v140, v133
	s_waitcnt vmcnt(9)
	v_pk_fma_f32 v[32:33], v[56:57], v[14:15], 0 op_sel_hi:[1,1,0]
	s_waitcnt vmcnt(8)
	v_pk_fma_f32 v[20:21], v[60:61], v[18:19], 0 op_sel_hi:[1,1,0]
	v_pk_fma_f32 v[22:23], v[62:63], v[10:11], 0 op_sel_hi:[1,1,0]
	v_pk_fma_f32 v[34:35], v[58:59], v[12:13], 0 op_sel_hi:[1,1,0]
	global_load_dwordx4 v[8:11], v[16:17], off offset:16
	global_load_dwordx4 v[12:15], v[16:17], off
	ds_read_b128 v[16:19], v134 offset:2048
	v_lshl_add_u64 v[104:105], v[36:37], 0, s[0:1]
	s_waitcnt lgkmcnt(0)
	v_lshlrev_b32_e32 v38, 16, v16
	v_and_b32_e32 v39, 0xffff0000, v16
	v_lshlrev_b32_e32 v16, 16, v17
	v_and_b32_e32 v17, 0xffff0000, v17
	v_lshlrev_b32_e32 v64, 16, v18
	v_and_b32_e32 v65, 0xffff0000, v18
	v_lshlrev_b32_e32 v18, 16, v19
	v_and_b32_e32 v19, 0xffff0000, v19
	s_waitcnt vmcnt(8)
	v_pk_fma_f32 v[66:67], v[52:53], v[38:39], v[20:21]
	v_pk_fma_f32 v[68:69], v[54:55], v[16:17], v[22:23]
	v_pk_fma_f32 v[72:73], v[50:51], v[18:19], v[34:35]
	v_pk_fma_f32 v[74:75], v[62:63], v[16:17], 0 op_sel_hi:[1,1,0]
	v_pk_fma_f32 v[78:79], v[58:59], v[18:19], 0 op_sel_hi:[1,1,0]
	global_load_dwordx4 v[16:19], v[36:37], off offset:16
	global_load_dwordx4 v[20:23], v[36:37], off
	v_pk_fma_f32 v[70:71], v[48:49], v[64:65], v[32:33]
	ds_read_b128 v[32:35], v134 offset:4096
	v_pk_fma_f32 v[38:39], v[60:61], v[38:39], 0 op_sel_hi:[1,1,0]
	v_pk_fma_f32 v[76:77], v[56:57], v[64:65], 0 op_sel_hi:[1,1,0]
	v_lshl_add_u64 v[108:109], v[104:105], 0, s[0:1]
	s_waitcnt lgkmcnt(0)
; #define LAS __attribute__((address_space(3)))
; __device__ __forceinline__ void conv_phase(LAS unsigned char* lds, const bf16_t* U, bf16_t* C, const float* wdw, const float* bdw, const float* lng, const float* lnb,
;                                            int first, int stride, int end, int tid, int wave, int lane) {
;     ...
; #pragma unroll
;             for (int t = 0; t < 4; ++t) { wt[t][0] = wq[0]; wt[t][1] = wq[1]; wq += D / 4; asm volatile("" : "+v"(wq)); }
; #pragma unroll
;             for (int r = 0; r < TT / NWAVES + CW - 1; ++r) {
;                 if (r + 4 < CW) { wt[(r + 4) & 7][0] = wq[0]; wt[(r + 4) & 7][1] = wq[1]; wq += D / 4; asm volatile("" : "+v"(wq)); }
;                 const u32x4 xv = *(const LAS u32x4*)(lds + (4 * wave + r) * 2048 + p * 1024 + lane * 16);
;                 f32x2 x[4];
; #pragma unroll
;                 for (int i = 0; i < 4; ++i) x[i] = (f32x2){__uint_as_float(xv[i] << 16), __uint_as_float(xv[i] & 0xffff0000u)};
; #pragma unroll
;                 for (int j = 0; j < 4; ++j) { const int w = r - j;
;                     if (w >= 0 && w < CW) {
; #pragma unroll
;                         for (int c = 0; c < 4; ++c) { const f32x4 wv = wt[w & 7][c >> 1]; const f32x2 w2 = (c & 1) ? (f32x2){wv.z, wv.w} : (f32x2){wv.x, wv.y}; acc[p][j][c] = __builtin_elementwise_fma(w2, x[c], acc[p][j][c]); } } }
;                 asm volatile("" ::: "memory");
;             }
	v_lshlrev_b32_e32 v36, 16, v32
	v_and_b32_e32 v37, 0xffff0000, v32
	v_lshlrev_b32_e32 v32, 16, v33
	v_and_b32_e32 v33, 0xffff0000, v33
	v_lshlrev_b32_e32 v80, 16, v34
	v_and_b32_e32 v81, 0xffff0000, v34
	v_lshlrev_b32_e32 v34, 16, v35
	v_and_b32_e32 v35, 0xffff0000, v35
	s_waitcnt vmcnt(8)
	v_pk_fma_f32 v[102:103], v[44:45], v[36:37], v[66:67]
	v_pk_fma_f32 v[100:101], v[46:47], v[32:33], v[68:69]
	v_pk_fma_f32 v[82:83], v[40:41], v[80:81], v[70:71]
	v_pk_fma_f32 v[64:65], v[42:43], v[34:35], v[72:73]
	v_pk_fma_f32 v[66:67], v[52:53], v[36:37], v[38:39]
	v_pk_fma_f32 v[68:69], v[54:55], v[32:33], v[74:75]
	v_pk_fma_f32 v[70:71], v[48:49], v[80:81], v[76:77]
	v_pk_fma_f32 v[72:73], v[50:51], v[34:35], v[78:79]
	v_pk_fma_f32 v[74:75], v[60:61], v[36:37], 0 op_sel_hi:[1,1,0]
	v_pk_fma_f32 v[76:77], v[62:63], v[32:33], 0 op_sel_hi:[1,1,0]
	v_pk_fma_f32 v[78:79], v[56:57], v[80:81], 0 op_sel_hi:[1,1,0]
	v_pk_fma_f32 v[80:81], v[58:59], v[34:35], 0 op_sel_hi:[1,1,0]
	global_load_dwordx4 v[32:35], v[104:105], off offset:16
	global_load_dwordx4 v[36:39], v[104:105], off
	ds_read_b128 v[104:107], v134 offset:6144
	s_waitcnt lgkmcnt(0)
	v_lshlrev_b32_e32 v110, 16, v104
	v_and_b32_e32 v111, 0xffff0000, v104
	v_lshlrev_b32_e32 v104, 16, v105
	v_and_b32_e32 v105, 0xffff0000, v105
	v_lshlrev_b32_e32 v112, 16, v106
	v_and_b32_e32 v113, 0xffff0000, v106
	v_lshlrev_b32_e32 v106, 16, v107
	v_and_b32_e32 v107, 0xffff0000, v107
	s_waitcnt vmcnt(8)
	v_pk_fma_f32 v[102:103], v[28:29], v[110:111], v[102:103]
	v_pk_fma_f32 v[100:101], v[30:31], v[104:105], v[100:101]
	v_pk_fma_f32 v[82:83], v[24:25], v[112:113], v[82:83]
	v_pk_fma_f32 v[114:115], v[26:27], v[106:107], v[64:65]
	v_pk_fma_f32 v[116:117], v[44:45], v[110:111], v[66:67]
	v_pk_fma_f32 v[68:69], v[46:47], v[104:105], v[68:69]
	v_pk_fma_f32 v[70:71], v[40:41], v[112:113], v[70:71]
	v_pk_fma_f32 v[72:73], v[42:43], v[106:107], v[72:73]
	v_pk_fma_f32 v[74:75], v[52:53], v[110:111], v[74:75]
	v_pk_fma_f32 v[76:77], v[54:55], v[104:105], v[76:77]
	v_pk_fma_f32 v[78:79], v[48:49], v[112:113], v[78:79]
	v_pk_fma_f32 v[80:81], v[50:51], v[106:107], v[80:81]
	v_pk_fma_f32 v[110:111], v[60:61], v[110:111], 0 op_sel_hi:[1,1,0]
	v_pk_fma_f32 v[104:105], v[62:63], v[104:105], 0 op_sel_hi:[1,1,0]
	v_pk_fma_f32 v[112:113], v[56:57], v[112:113], 0 op_sel_hi:[1,1,0]
	v_pk_fma_f32 v[106:107], v[58:59], v[106:107], 0 op_sel_hi:[1,1,0]
	global_load_dwordx4 v[56:59], v[108:109], off offset:16
	global_load_dwordx4 v[60:63], v[108:109], off
	v_lshl_add_u64 v[108:109], v[108:109], 0, s[0:1]
	ds_read_b128 v[64:67], v134 offset:8192
	s_waitcnt lgkmcnt(0)
	v_lshlrev_b32_e32 v118, 16, v64
	v_and_b32_e32 v119, 0xffff0000, v64
	v_lshlrev_b32_e32 v64, 16, v65
	v_and_b32_e32 v65, 0xffff0000, v65
	v_lshlrev_b32_e32 v120, 16, v66
	v_and_b32_e32 v121, 0xffff0000, v66
	v_lshlrev_b32_e32 v66, 16, v67
	v_and_b32_e32 v67, 0xffff0000, v67
	v_pk_fma_f32 v[110:111], v[52:53], v[118:119], v[110:111]
	v_pk_fma_f32 v[104:105], v[54:55], v[64:65], v[104:105]
	v_pk_fma_f32 v[112:113], v[48:49], v[120:121], v[112:113]
	v_pk_fma_f32 v[106:107], v[50:51], v[66:67], v[106:107]
	global_load_dwordx4 v[48:51], v[108:109], off offset:16
	global_load_dwordx4 v[52:55], v[108:109], off
	v_lshl_add_u64 v[108:109], v[108:109], 0, s[0:1]
	s_waitcnt vmcnt(10)
	v_pk_fma_f32 v[100:101], v[6:7], v[64:65], v[100:101]
	v_pk_fma_f32 v[114:115], v[2:3], v[66:67], v[114:115]
	v_pk_fma_f32 v[68:69], v[30:31], v[64:65], v[68:69]
	v_pk_fma_f32 v[72:73], v[26:27], v[66:67], v[72:73]
	v_pk_fma_f32 v[76:77], v[46:47], v[64:65], v[76:77]
	v_pk_fma_f32 v[80:81], v[42:43], v[66:67], v[80:81]
	ds_read_b128 v[64:67], v134 offset:10240
	v_pk_fma_f32 v[102:103], v[4:5], v[118:119], v[102:103]
	v_pk_fma_f32 v[82:83], v[0:1], v[120:121], v[82:83]
	v_pk_fma_f32 v[116:117], v[28:29], v[118:119], v[116:117]
	v_pk_fma_f32 v[70:71], v[24:25], v[120:121], v[70:71]
	v_pk_fma_f32 v[74:75], v[44:45], v[118:119], v[74:75]
	v_pk_fma_f32 v[78:79], v[40:41], v[120:121], v[78:79]
	s_waitcnt lgkmcnt(0)
	v_lshlrev_b32_e32 v118, 16, v64
	v_and_b32_e32 v119, 0xffff0000, v64
	v_lshlrev_b32_e32 v64, 16, v65
	v_and_b32_e32 v65, 0xffff0000, v65
	v_lshlrev_b32_e32 v120, 16, v66
	v_and_b32_e32 v121, 0xffff0000, v66
	v_lshlrev_b32_e32 v66, 16, v67
	v_and_b32_e32 v67, 0xffff0000, v67
	v_pk_fma_f32 v[110:111], v[44:45], v[118:119], v[110:111]
	v_pk_fma_f32 v[104:105], v[46:47], v[64:65], v[104:105]
	v_pk_fma_f32 v[112:113], v[40:41], v[120:121], v[112:113]
	v_pk_fma_f32 v[106:107], v[42:43], v[66:67], v[106:107]
	global_load_dwordx4 v[40:43], v[108:109], off offset:16
	global_load_dwordx4 v[44:47], v[108:109], off
	v_lshl_add_u64 v[108:109], v[108:109], 0, s[0:1]
	s_waitcnt vmcnt(10)
	v_pk_fma_f32 v[100:101], v[14:15], v[64:65], v[100:101]
	v_pk_fma_f32 v[114:115], v[10:11], v[66:67], v[114:115]
	v_pk_fma_f32 v[68:69], v[6:7], v[64:65], v[68:69]
	v_pk_fma_f32 v[72:73], v[2:3], v[66:67], v[72:73]
	v_pk_fma_f32 v[76:77], v[30:31], v[64:65], v[76:77]
	v_pk_fma_f32 v[80:81], v[26:27], v[66:67], v[80:81]
	ds_read_b128 v[64:67], v134 offset:12288
	v_pk_fma_f32 v[102:103], v[12:13], v[118:119], v[102:103]
	v_pk_fma_f32 v[82:83], v[8:9], v[120:121], v[82:83]
	v_pk_fma_f32 v[116:117], v[4:5], v[118:119], v[116:117]
	v_pk_fma_f32 v[70:71], v[0:1], v[120:121], v[70:71]
	v_pk_fma_f32 v[74:75], v[28:29], v[118:119], v[74:75]
	v_pk_fma_f32 v[78:79], v[24:25], v[120:121], v[78:79]
	s_waitcnt lgkmcnt(0)
	v_lshlrev_b32_e32 v118, 16, v64
	v_and_b32_e32 v119, 0xffff0000, v64
	v_lshlrev_b32_e32 v64, 16, v65
	v_and_b32_e32 v65, 0xffff0000, v65
	v_lshlrev_b32_e32 v120, 16, v66
	v_and_b32_e32 v121, 0xffff0000, v66
	v_lshlrev_b32_e32 v66, 16, v67
	v_and_b32_e32 v67, 0xffff0000, v67
	s_waitcnt vmcnt(8)
; #define LAS __attribute__((address_space(3)))
; __device__ __forceinline__ void conv_phase(LAS unsigned char* lds, const bf16_t* U, bf16_t* C, const float* wdw, const float* bdw, const float* lng, const float* lnb,
;                                            int first, int stride, int end, int tid, int wave, int lane) {
;     ...
; #pragma unroll
;             for (int t = 0; t < 4; ++t) { wt[t][0] = wq[0]; wt[t][1] = wq[1]; wq += D / 4; asm volatile("" : "+v"(wq)); }
; #pragma unroll
;             for (int r = 0; r < TT / NWAVES + CW - 1; ++r) {
;                 if (r + 4 < CW) { wt[(r + 4) & 7][0] = wq[0]; wt[(r + 4) & 7][1] = wq[1]; wq += D / 4; asm volatile("" : "+v"(wq)); }
;                 const u32x4 xv = *(const LAS u32x4*)(lds + (4 * wave + r) * 2048 + p * 1024 + lane * 16);
;                 f32x2 x[4];
; #pragma unroll
;                 for (int i = 0; i < 4; ++i) x[i] = (f32x2){__uint_as_float(xv[i] << 16), __uint_as_float(xv[i] & 0xffff0000u)};
; #pragma unroll
;                 for (int j = 0; j < 4; ++j) { const int w = r - j;
;                     if (w >= 0 && w < CW) {
; #pragma unroll
;                         for (int c = 0; c < 4; ++c) { const f32x4 wv = wt[w & 7][c >> 1]; const f32x2 w2 = (c & 1) ? (f32x2){wv.z, wv.w} : (f32x2){wv.x, wv.y}; acc[p][j][c] = __builtin_elementwise_fma(w2, x[c], acc[p][j][c]); } } }
;                 asm volatile("" ::: "memory");
;             }
	v_pk_fma_f32 v[100:101], v[22:23], v[64:65], v[100:101]
	v_pk_fma_f32 v[114:115], v[18:19], v[66:67], v[114:115]
	v_pk_fma_f32 v[68:69], v[14:15], v[64:65], v[68:69]
	v_pk_fma_f32 v[72:73], v[10:11], v[66:67], v[72:73]
	v_pk_fma_f32 v[76:77], v[6:7], v[64:65], v[76:77]
	v_pk_fma_f32 v[80:81], v[2:3], v[66:67], v[80:81]
	v_pk_fma_f32 v[104:105], v[30:31], v[64:65], v[104:105]
	v_pk_fma_f32 v[112:113], v[24:25], v[120:121], v[112:113]
	v_pk_fma_f32 v[106:107], v[26:27], v[66:67], v[106:107]
	global_load_dwordx4 v[24:27], v[108:109], off offset:16
	global_load_dwordx4 v[64:67], v[108:109], off
	v_lshl_add_u64 v[108:109], v[108:109], 0, s[0:1]
	v_pk_fma_f32 v[110:111], v[28:29], v[118:119], v[110:111]
	ds_read_b128 v[28:31], v134 offset:14336
	v_pk_fma_f32 v[102:103], v[20:21], v[118:119], v[102:103]
	v_pk_fma_f32 v[82:83], v[16:17], v[120:121], v[82:83]
	v_pk_fma_f32 v[116:117], v[12:13], v[118:119], v[116:117]
	v_pk_fma_f32 v[70:71], v[8:9], v[120:121], v[70:71]
	v_pk_fma_f32 v[74:75], v[4:5], v[118:119], v[74:75]
	v_pk_fma_f32 v[78:79], v[0:1], v[120:121], v[78:79]
	s_waitcnt lgkmcnt(0)
	v_lshlrev_b32_e32 v118, 16, v28
	v_and_b32_e32 v119, 0xffff0000, v28
	v_lshlrev_b32_e32 v28, 16, v29
	v_and_b32_e32 v29, 0xffff0000, v29
	v_lshlrev_b32_e32 v120, 16, v30
	v_and_b32_e32 v121, 0xffff0000, v30
	v_lshlrev_b32_e32 v30, 16, v31
	v_and_b32_e32 v31, 0xffff0000, v31
	s_waitcnt vmcnt(8)
	v_pk_fma_f32 v[100:101], v[38:39], v[28:29], v[100:101]
	v_pk_fma_f32 v[114:115], v[34:35], v[30:31], v[114:115]
	v_pk_fma_f32 v[122:123], v[22:23], v[28:29], v[68:69]
	v_pk_fma_f32 v[124:125], v[16:17], v[120:121], v[70:71]
	v_pk_fma_f32 v[72:73], v[18:19], v[30:31], v[72:73]
	v_pk_fma_f32 v[76:77], v[14:15], v[28:29], v[76:77]
	v_pk_fma_f32 v[80:81], v[10:11], v[30:31], v[80:81]
	v_pk_fma_f32 v[28:29], v[6:7], v[28:29], v[104:105]
	v_pk_fma_f32 v[104:105], v[0:1], v[120:121], v[112:113]
	v_pk_fma_f32 v[30:31], v[2:3], v[30:31], v[106:107]
	global_load_dwordx4 v[0:3], v[108:109], off offset:16
	global_load_dwordx4 v[68:71], v[108:109], off
	v_lshl_add_u64 v[106:107], v[108:109], 0, s[0:1]
	v_pk_fma_f32 v[110:111], v[4:5], v[118:119], v[110:111]
	ds_read_b128 v[4:7], v134 offset:16384
	v_pk_fma_f32 v[74:75], v[12:13], v[118:119], v[74:75]
	v_pk_fma_f32 v[102:103], v[36:37], v[118:119], v[102:103]
	v_pk_fma_f32 v[82:83], v[32:33], v[120:121], v[82:83]
	s_waitcnt lgkmcnt(0)
	v_lshlrev_b32_e32 v108, 16, v4
	v_and_b32_e32 v109, 0xffff0000, v4
	v_lshlrev_b32_e32 v4, 16, v5
	v_and_b32_e32 v5, 0xffff0000, v5
	v_lshlrev_b32_e32 v112, 16, v6
	v_and_b32_e32 v113, 0xffff0000, v6
	v_lshlrev_b32_e32 v6, 16, v7
	v_and_b32_e32 v7, 0xffff0000, v7
	v_pk_fma_f32 v[116:117], v[20:21], v[118:119], v[116:117]
	v_pk_fma_f32 v[78:79], v[8:9], v[120:121], v[78:79]
	s_waitcnt vmcnt(8)
	v_pk_fma_f32 v[100:101], v[62:63], v[4:5], v[100:101]
	v_pk_fma_f32 v[114:115], v[58:59], v[6:7], v[114:115]
	v_pk_fma_f32 v[118:119], v[38:39], v[4:5], v[122:123]
	v_pk_fma_f32 v[120:121], v[32:33], v[112:113], v[124:125]
	v_pk_fma_f32 v[122:123], v[34:35], v[6:7], v[72:73]
	v_pk_fma_f32 v[124:125], v[20:21], v[108:109], v[74:75]
	v_pk_fma_f32 v[76:77], v[22:23], v[4:5], v[76:77]
	v_pk_fma_f32 v[80:81], v[18:19], v[6:7], v[80:81]
	v_pk_fma_f32 v[14:15], v[14:15], v[4:5], v[28:29]
	v_pk_fma_f32 v[30:31], v[10:11], v[6:7], v[30:31]
	global_load_dwordx4 v[4:7], v[106:107], off offset:16
	global_load_dwordx4 v[72:75], v[106:107], off
	v_pk_fma_f32 v[28:29], v[8:9], v[112:113], v[104:105]
	v_lshl_add_u64 v[104:105], v[106:107], 0, s[0:1]
	ds_read_b128 v[8:11], v134 offset:18432
	v_pk_fma_f32 v[102:103], v[60:61], v[108:109], v[102:103]
	v_pk_fma_f32 v[116:117], v[36:37], v[108:109], v[116:117]
	v_pk_fma_f32 v[78:79], v[16:17], v[112:113], v[78:79]
	v_pk_fma_f32 v[12:13], v[12:13], v[108:109], v[110:111]
	s_waitcnt lgkmcnt(0)
	v_lshlrev_b32_e32 v106, 16, v8
	v_and_b32_e32 v107, 0xffff0000, v8
	v_lshlrev_b32_e32 v8, 16, v9
	v_and_b32_e32 v9, 0xffff0000, v9
	v_lshlrev_b32_e32 v108, 16, v10
	v_and_b32_e32 v109, 0xffff0000, v10
	v_lshlrev_b32_e32 v10, 16, v11
	v_and_b32_e32 v11, 0xffff0000, v11
	v_pk_fma_f32 v[82:83], v[56:57], v[112:113], v[82:83]
	s_waitcnt vmcnt(8)
	v_pk_fma_f32 v[100:101], v[54:55], v[8:9], v[100:101]
	v_pk_fma_f32 v[110:111], v[50:51], v[10:11], v[114:115]
	v_pk_fma_f32 v[112:113], v[60:61], v[106:107], v[116:117]
	v_pk_fma_f32 v[114:115], v[62:63], v[8:9], v[118:119]
	v_pk_fma_f32 v[116:117], v[56:57], v[108:109], v[120:121]
	v_pk_fma_f32 v[118:119], v[58:59], v[10:11], v[122:123]
	v_pk_fma_f32 v[120:121], v[36:37], v[106:107], v[124:125]
	v_pk_fma_f32 v[122:123], v[38:39], v[8:9], v[76:77]
	v_pk_fma_f32 v[124:125], v[32:33], v[108:109], v[78:79]
	v_pk_fma_f32 v[80:81], v[34:35], v[10:11], v[80:81]
	v_pk_fma_f32 v[22:23], v[22:23], v[8:9], v[14:15]
	v_pk_fma_f32 v[16:17], v[16:17], v[108:109], v[28:29]
	v_pk_fma_f32 v[18:19], v[18:19], v[10:11], v[30:31]
	global_load_dwordx4 v[8:11], v[104:105], off offset:16
	global_load_dwordx4 v[76:79], v[104:105], off
	v_lshl_add_u64 v[28:29], v[104:105], 0, s[0:1]
	v_pk_fma_f32 v[20:21], v[20:21], v[106:107], v[12:13]
	ds_read_b128 v[12:15], v134 offset:20480
	v_pk_fma_f32 v[102:103], v[52:53], v[106:107], v[102:103]
	v_pk_fma_f32 v[82:83], v[48:49], v[108:109], v[82:83]
	s_waitcnt lgkmcnt(0)
	v_lshlrev_b32_e32 v30, 16, v12
	v_and_b32_e32 v31, 0xffff0000, v12
	v_lshlrev_b32_e32 v12, 16, v13
	v_and_b32_e32 v13, 0xffff0000, v13
	v_lshlrev_b32_e32 v104, 16, v14
	v_and_b32_e32 v105, 0xffff0000, v14
	v_lshlrev_b32_e32 v14, 16, v15
	v_and_b32_e32 v15, 0xffff0000, v15
	s_waitcnt vmcnt(8)
; #define LAS __attribute__((address_space(3)))
; __device__ __forceinline__ void conv_phase(LAS unsigned char* lds, const bf16_t* U, bf16_t* C, const float* wdw, const float* bdw, const float* lng, const float* lnb,
;                                            int first, int stride, int end, int tid, int wave, int lane) {
;     ...
; #pragma unroll
;             for (int t = 0; t < 4; ++t) { wt[t][0] = wq[0]; wt[t][1] = wq[1]; wq += D / 4; asm volatile("" : "+v"(wq)); }
; #pragma unroll
;             for (int r = 0; r < TT / NWAVES + CW - 1; ++r) {
;                 if (r + 4 < CW) { wt[(r + 4) & 7][0] = wq[0]; wt[(r + 4) & 7][1] = wq[1]; wq += D / 4; asm volatile("" : "+v"(wq)); }
;                 const u32x4 xv = *(const LAS u32x4*)(lds + (4 * wave + r) * 2048 + p * 1024 + lane * 16);
;                 f32x2 x[4];
; #pragma unroll
;                 for (int i = 0; i < 4; ++i) x[i] = (f32x2){__uint_as_float(xv[i] << 16), __uint_as_float(xv[i] & 0xffff0000u)};
; #pragma unroll
;                 for (int j = 0; j < 4; ++j) { const int w = r - j;
;                     if (w >= 0 && w < CW) {
; #pragma unroll
;                         for (int c = 0; c < 4; ++c) { const f32x4 wv = wt[w & 7][c >> 1]; const f32x2 w2 = (c & 1) ? (f32x2){wv.z, wv.w} : (f32x2){wv.x, wv.y}; acc[p][j][c] = __builtin_elementwise_fma(w2, x[c], acc[p][j][c]); } } }
;                 asm volatile("" ::: "memory");
;             }
	v_pk_fma_f32 v[102:103], v[44:45], v[30:31], v[102:103]
	v_pk_fma_f32 v[100:101], v[46:47], v[12:13], v[100:101]
	v_pk_fma_f32 v[106:107], v[42:43], v[14:15], v[110:111]
	v_pk_fma_f32 v[108:109], v[52:53], v[30:31], v[112:113]
	v_pk_fma_f32 v[110:111], v[54:55], v[12:13], v[114:115]
	v_pk_fma_f32 v[112:113], v[48:49], v[104:105], v[116:117]
	v_pk_fma_f32 v[114:115], v[50:51], v[14:15], v[118:119]
	v_pk_fma_f32 v[116:117], v[60:61], v[30:31], v[120:121]
	v_pk_fma_f32 v[118:119], v[62:63], v[12:13], v[122:123]
	v_pk_fma_f32 v[80:81], v[58:59], v[14:15], v[80:81]
	v_pk_fma_f32 v[20:21], v[36:37], v[30:31], v[20:21]
	v_pk_fma_f32 v[22:23], v[38:39], v[12:13], v[22:23]
	v_pk_fma_f32 v[30:31], v[32:33], v[104:105], v[16:17]
	v_pk_fma_f32 v[32:33], v[34:35], v[14:15], v[18:19]
	global_load_dwordx4 v[12:15], v[28:29], off offset:16
	global_load_dwordx4 v[36:39], v[28:29], off
	v_lshl_add_u64 v[28:29], v[28:29], 0, s[0:1]
	ds_read_b128 v[16:19], v134 offset:22528
	v_pk_fma_f32 v[82:83], v[40:41], v[104:105], v[82:83]
	v_pk_fma_f32 v[120:121], v[56:57], v[104:105], v[124:125]
	s_waitcnt lgkmcnt(0)
	v_lshlrev_b32_e32 v34, 16, v16
	v_and_b32_e32 v35, 0xffff0000, v16
	v_lshlrev_b32_e32 v16, 16, v17
	v_and_b32_e32 v17, 0xffff0000, v17
	v_lshlrev_b32_e32 v104, 16, v18
	v_and_b32_e32 v105, 0xffff0000, v18
	v_lshlrev_b32_e32 v18, 16, v19
	v_and_b32_e32 v19, 0xffff0000, v19
	s_waitcnt vmcnt(8)
	v_pk_fma_f32 v[102:103], v[64:65], v[34:35], v[102:103]
	v_pk_fma_f32 v[100:101], v[66:67], v[16:17], v[100:101]
	v_pk_fma_f32 v[106:107], v[26:27], v[18:19], v[106:107]
	v_pk_fma_f32 v[108:109], v[44:45], v[34:35], v[108:109]
	v_pk_fma_f32 v[110:111], v[46:47], v[16:17], v[110:111]
	v_pk_fma_f32 v[114:115], v[42:43], v[18:19], v[114:115]
	v_pk_fma_f32 v[116:117], v[52:53], v[34:35], v[116:117]
	v_pk_fma_f32 v[118:119], v[54:55], v[16:17], v[118:119]
	v_pk_fma_f32 v[80:81], v[50:51], v[18:19], v[80:81]
	v_pk_fma_f32 v[34:35], v[60:61], v[34:35], v[20:21]
	v_pk_fma_f32 v[60:61], v[62:63], v[16:17], v[22:23]
	v_pk_fma_f32 v[30:31], v[56:57], v[104:105], v[30:31]
	v_pk_fma_f32 v[32:33], v[58:59], v[18:19], v[32:33]
	global_load_dwordx4 v[16:19], v[28:29], off offset:16
	global_load_dwordx4 v[56:59], v[28:29], off
	v_lshl_add_u64 v[28:29], v[28:29], 0, s[0:1]
	ds_read_b128 v[20:23], v134 offset:24576
	v_pk_fma_f32 v[82:83], v[24:25], v[104:105], v[82:83]
	v_pk_fma_f32 v[112:113], v[40:41], v[104:105], v[112:113]
	v_pk_fma_f32 v[120:121], v[48:49], v[104:105], v[120:121]
	s_waitcnt lgkmcnt(0)
	v_lshlrev_b32_e32 v62, 16, v20
	v_and_b32_e32 v63, 0xffff0000, v20
	v_lshlrev_b32_e32 v20, 16, v21
	v_and_b32_e32 v21, 0xffff0000, v21
	v_lshlrev_b32_e32 v104, 16, v22
	v_and_b32_e32 v105, 0xffff0000, v22
	v_lshlrev_b32_e32 v22, 16, v23
	v_and_b32_e32 v23, 0xffff0000, v23
	s_waitcnt vmcnt(8)
	v_pk_fma_f32 v[100:101], v[70:71], v[20:21], v[100:101]
	v_pk_fma_f32 v[106:107], v[2:3], v[22:23], v[106:107]
	v_pk_fma_f32 v[110:111], v[66:67], v[20:21], v[110:111]
	v_pk_fma_f32 v[114:115], v[26:27], v[22:23], v[114:115]
	v_pk_fma_f32 v[118:119], v[46:47], v[20:21], v[118:119]
	v_pk_fma_f32 v[80:81], v[42:43], v[22:23], v[80:81]
	v_pk_fma_f32 v[34:35], v[52:53], v[62:63], v[34:35]
	v_pk_fma_f32 v[52:53], v[54:55], v[20:21], v[60:61]
	v_pk_fma_f32 v[54:55], v[48:49], v[104:105], v[30:31]
	v_pk_fma_f32 v[32:33], v[50:51], v[22:23], v[32:33]
	global_load_dwordx4 v[20:23], v[28:29], off offset:16
	global_load_dwordx4 v[48:51], v[28:29], off
	v_lshl_add_u64 v[60:61], v[28:29], 0, s[0:1]
	ds_read_b128 v[28:31], v134 offset:26624
	v_pk_fma_f32 v[102:103], v[68:69], v[62:63], v[102:103]
	v_pk_fma_f32 v[82:83], v[0:1], v[104:105], v[82:83]
	v_pk_fma_f32 v[108:109], v[64:65], v[62:63], v[108:109]
	v_pk_fma_f32 v[112:113], v[24:25], v[104:105], v[112:113]
	v_pk_fma_f32 v[116:117], v[44:45], v[62:63], v[116:117]
	v_pk_fma_f32 v[120:121], v[40:41], v[104:105], v[120:121]
	s_waitcnt lgkmcnt(0)
	v_lshlrev_b32_e32 v62, 16, v28
	v_and_b32_e32 v63, 0xffff0000, v28
	v_lshlrev_b32_e32 v28, 16, v29
	v_and_b32_e32 v29, 0xffff0000, v29
	v_lshlrev_b32_e32 v104, 16, v30
	v_and_b32_e32 v105, 0xffff0000, v30
	v_lshlrev_b32_e32 v30, 16, v31
	v_and_b32_e32 v31, 0xffff0000, v31
	s_waitcnt vmcnt(8)
	v_pk_fma_f32 v[100:101], v[74:75], v[28:29], v[100:101]
	v_pk_fma_f32 v[106:107], v[6:7], v[30:31], v[106:107]
	v_pk_fma_f32 v[110:111], v[70:71], v[28:29], v[110:111]
	v_pk_fma_f32 v[114:115], v[2:3], v[30:31], v[114:115]
	v_pk_fma_f32 v[118:119], v[66:67], v[28:29], v[118:119]
	v_pk_fma_f32 v[80:81], v[26:27], v[30:31], v[80:81]
	v_pk_fma_f32 v[46:47], v[46:47], v[28:29], v[52:53]
	v_pk_fma_f32 v[52:53], v[40:41], v[104:105], v[54:55]
	v_pk_fma_f32 v[54:55], v[42:43], v[30:31], v[32:33]
	global_load_dwordx4 v[28:31], v[60:61], off offset:16
	global_load_dwordx4 v[40:43], v[60:61], off
	v_lshl_add_u64 v[60:61], v[60:61], 0, s[0:1]
	v_pk_fma_f32 v[44:45], v[44:45], v[62:63], v[34:35]
	ds_read_b128 v[32:35], v134 offset:28672
	v_pk_fma_f32 v[102:103], v[72:73], v[62:63], v[102:103]
	v_pk_fma_f32 v[82:83], v[4:5], v[104:105], v[82:83]
	v_pk_fma_f32 v[108:109], v[68:69], v[62:63], v[108:109]
	v_pk_fma_f32 v[112:113], v[0:1], v[104:105], v[112:113]
	v_pk_fma_f32 v[116:117], v[64:65], v[62:63], v[116:117]
	v_pk_fma_f32 v[120:121], v[24:25], v[104:105], v[120:121]
	s_waitcnt lgkmcnt(0)
	v_lshlrev_b32_e32 v62, 16, v32
	v_and_b32_e32 v63, 0xffff0000, v32
	v_lshlrev_b32_e32 v32, 16, v33
	v_and_b32_e32 v33, 0xffff0000, v33
	v_lshlrev_b32_e32 v104, 16, v34
	v_and_b32_e32 v105, 0xffff0000, v34
	v_lshlrev_b32_e32 v34, 16, v35
	v_and_b32_e32 v35, 0xffff0000, v35
	s_waitcnt vmcnt(8)
; #define LAS __attribute__((address_space(3)))
; __device__ __forceinline__ void conv_phase(LAS unsigned char* lds, const bf16_t* U, bf16_t* C, const float* wdw, const float* bdw, const float* lng, const float* lnb,
;                                            int first, int stride, int end, int tid, int wave, int lane) {
;     ...
; #pragma unroll
;             for (int t = 0; t < 4; ++t) { wt[t][0] = wq[0]; wt[t][1] = wq[1]; wq += D / 4; asm volatile("" : "+v"(wq)); }
; #pragma unroll
;             for (int r = 0; r < TT / NWAVES + CW - 1; ++r) {
;                 if (r + 4 < CW) { wt[(r + 4) & 7][0] = wq[0]; wt[(r + 4) & 7][1] = wq[1]; wq += D / 4; asm volatile("" : "+v"(wq)); }
;                 const u32x4 xv = *(const LAS u32x4*)(lds + (4 * wave + r) * 2048 + p * 1024 + lane * 16);
;                 f32x2 x[4];
; #pragma unroll
;                 for (int i = 0; i < 4; ++i) x[i] = (f32x2){__uint_as_float(xv[i] << 16), __uint_as_float(xv[i] & 0xffff0000u)};
; #pragma unroll
;                 for (int j = 0; j < 4; ++j) { const int w = r - j;
;                     if (w >= 0 && w < CW) {
; #pragma unroll
;                         for (int c = 0; c < 4; ++c) { const f32x4 wv = wt[w & 7][c >> 1]; const f32x2 w2 = (c & 1) ? (f32x2){wv.z, wv.w} : (f32x2){wv.x, wv.y}; acc[p][j][c] = __builtin_elementwise_fma(w2, x[c], acc[p][j][c]); } } }
;                 asm volatile("" ::: "memory");
;             }
	v_pk_fma_f32 v[102:103], v[76:77], v[62:63], v[102:103]
	v_pk_fma_f32 v[108:109], v[72:73], v[62:63], v[108:109]
	v_pk_fma_f32 v[116:117], v[68:69], v[62:63], v[116:117]
	v_pk_fma_f32 v[62:63], v[64:65], v[62:63], v[44:45]
	v_pk_fma_f32 v[64:65], v[66:67], v[32:33], v[46:47]
	v_pk_fma_f32 v[52:53], v[24:25], v[104:105], v[52:53]
	v_pk_fma_f32 v[54:55], v[26:27], v[34:35], v[54:55]
	global_load_dwordx4 v[24:27], v[60:61], off offset:16
	global_load_dwordx4 v[44:47], v[60:61], off
	v_lshl_add_u64 v[60:61], v[60:61], 0, s[0:1]
	v_pk_fma_f32 v[100:101], v[78:79], v[32:33], v[100:101]
	v_pk_fma_f32 v[106:107], v[10:11], v[34:35], v[106:107]
	v_pk_fma_f32 v[110:111], v[74:75], v[32:33], v[110:111]
	v_pk_fma_f32 v[114:115], v[6:7], v[34:35], v[114:115]
	v_pk_fma_f32 v[118:119], v[70:71], v[32:33], v[118:119]
	v_pk_fma_f32 v[80:81], v[2:3], v[34:35], v[80:81]
	ds_read_b128 v[32:35], v134 offset:30720
	v_pk_fma_f32 v[82:83], v[8:9], v[104:105], v[82:83]
	v_pk_fma_f32 v[112:113], v[4:5], v[104:105], v[112:113]
	v_pk_fma_f32 v[120:121], v[0:1], v[104:105], v[120:121]
	s_waitcnt lgkmcnt(0)
	v_lshlrev_b32_e32 v66, 16, v32
	v_and_b32_e32 v67, 0xffff0000, v32
	v_lshlrev_b32_e32 v104, 16, v34
	v_and_b32_e32 v105, 0xffff0000, v34
	v_lshlrev_b32_e32 v34, 16, v35
	v_and_b32_e32 v35, 0xffff0000, v35
	s_waitcnt vmcnt(8)
	v_pk_fma_f32 v[102:103], v[36:37], v[66:67], v[102:103]
	v_pk_fma_f32 v[108:109], v[76:77], v[66:67], v[108:109]
	v_pk_fma_f32 v[116:117], v[72:73], v[66:67], v[116:117]
	v_pk_fma_f32 v[62:63], v[68:69], v[66:67], v[62:63]
	v_pk_fma_f32 v[66:67], v[0:1], v[104:105], v[52:53]
	v_pk_fma_f32 v[68:69], v[2:3], v[34:35], v[54:55]
	global_load_dwordx4 v[0:3], v[60:61], off offset:16
	global_load_dwordx4 v[52:55], v[60:61], off
	v_lshlrev_b32_e32 v32, 16, v33
	v_and_b32_e32 v33, 0xffff0000, v33
	v_pk_fma_f32 v[64:65], v[70:71], v[32:33], v[64:65]
	v_lshl_add_u64 v[70:71], v[60:61], 0, s[0:1]
	v_pk_fma_f32 v[100:101], v[38:39], v[32:33], v[100:101]
	v_pk_fma_f32 v[106:107], v[14:15], v[34:35], v[106:107]
	v_pk_fma_f32 v[110:111], v[78:79], v[32:33], v[110:111]
	v_pk_fma_f32 v[114:115], v[10:11], v[34:35], v[114:115]
	v_pk_fma_f32 v[118:119], v[74:75], v[32:33], v[118:119]
	v_pk_fma_f32 v[80:81], v[6:7], v[34:35], v[80:81]
	ds_read_b128 v[32:35], v134 offset:32768
	v_pk_fma_f32 v[82:83], v[12:13], v[104:105], v[82:83]
	v_pk_fma_f32 v[112:113], v[8:9], v[104:105], v[112:113]
	v_pk_fma_f32 v[120:121], v[4:5], v[104:105], v[120:121]
	s_waitcnt lgkmcnt(0)
	v_lshlrev_b32_e32 v60, 16, v32
	v_and_b32_e32 v61, 0xffff0000, v32
	v_lshlrev_b32_e32 v104, 16, v34
	v_and_b32_e32 v105, 0xffff0000, v34
	v_lshlrev_b32_e32 v34, 16, v35
	v_and_b32_e32 v35, 0xffff0000, v35
	v_lshlrev_b32_e32 v32, 16, v33
	v_and_b32_e32 v33, 0xffff0000, v33
	s_waitcnt vmcnt(8)
	v_pk_fma_f32 v[102:103], v[56:57], v[60:61], v[102:103]
	v_pk_fma_f32 v[108:109], v[36:37], v[60:61], v[108:109]
	v_pk_fma_f32 v[116:117], v[76:77], v[60:61], v[116:117]
	v_pk_fma_f32 v[72:73], v[72:73], v[60:61], v[62:63]
	v_pk_fma_f32 v[66:67], v[4:5], v[104:105], v[66:67]
	v_pk_fma_f32 v[68:69], v[6:7], v[34:35], v[68:69]
	global_load_dwordx4 v[4:7], v[70:71], off offset:16
	global_load_dwordx4 v[60:63], v[70:71], off
	v_lshl_add_u64 v[70:71], v[70:71], 0, s[0:1]
	v_pk_fma_f32 v[100:101], v[58:59], v[32:33], v[100:101]
	v_pk_fma_f32 v[106:107], v[18:19], v[34:35], v[106:107]
	v_pk_fma_f32 v[110:111], v[38:39], v[32:33], v[110:111]
	v_pk_fma_f32 v[114:115], v[14:15], v[34:35], v[114:115]
	v_pk_fma_f32 v[118:119], v[78:79], v[32:33], v[118:119]
	v_pk_fma_f32 v[80:81], v[10:11], v[34:35], v[80:81]
	v_pk_fma_f32 v[64:65], v[74:75], v[32:33], v[64:65]
	ds_read_b128 v[32:35], v134 offset:34816
	v_pk_fma_f32 v[82:83], v[16:17], v[104:105], v[82:83]
	v_pk_fma_f32 v[112:113], v[12:13], v[104:105], v[112:113]
	v_pk_fma_f32 v[120:121], v[8:9], v[104:105], v[120:121]
	s_waitcnt lgkmcnt(0)
	v_lshlrev_b32_e32 v74, 16, v32
	v_and_b32_e32 v75, 0xffff0000, v32
	v_lshlrev_b32_e32 v32, 16, v33
	v_and_b32_e32 v33, 0xffff0000, v33
	v_lshlrev_b32_e32 v104, 16, v34
	v_and_b32_e32 v105, 0xffff0000, v34
	v_lshlrev_b32_e32 v34, 16, v35
	v_and_b32_e32 v35, 0xffff0000, v35
	s_waitcnt vmcnt(8)
	v_pk_fma_f32 v[102:103], v[48:49], v[74:75], v[102:103]
	v_pk_fma_f32 v[108:109], v[56:57], v[74:75], v[108:109]
	v_pk_fma_f32 v[116:117], v[36:37], v[74:75], v[116:117]
	v_pk_fma_f32 v[72:73], v[76:77], v[74:75], v[72:73]
	v_pk_fma_f32 v[74:75], v[78:79], v[32:33], v[64:65]
	v_lshl_add_u64 v[78:79], v[70:71], 0, s[0:1]
	v_pk_fma_f32 v[100:101], v[50:51], v[32:33], v[100:101]
	v_pk_fma_f32 v[106:107], v[22:23], v[34:35], v[106:107]
	v_pk_fma_f32 v[110:111], v[58:59], v[32:33], v[110:111]
	v_pk_fma_f32 v[114:115], v[18:19], v[34:35], v[114:115]
	v_pk_fma_f32 v[118:119], v[38:39], v[32:33], v[118:119]
	v_pk_fma_f32 v[80:81], v[14:15], v[34:35], v[80:81]
	v_pk_fma_f32 v[76:77], v[8:9], v[104:105], v[66:67]
	v_pk_fma_f32 v[68:69], v[10:11], v[34:35], v[68:69]
	global_load_dwordx4 v[32:35], v[70:71], off offset:16
	global_load_dwordx4 v[64:67], v[70:71], off
	ds_read_b128 v[8:11], v134 offset:36864
	v_pk_fma_f32 v[82:83], v[20:21], v[104:105], v[82:83]
	v_pk_fma_f32 v[112:113], v[16:17], v[104:105], v[112:113]
	v_pk_fma_f32 v[120:121], v[12:13], v[104:105], v[120:121]
	s_waitcnt lgkmcnt(0)
	v_lshlrev_b32_e32 v70, 16, v8
	v_and_b32_e32 v71, 0xffff0000, v8
	v_lshlrev_b32_e32 v8, 16, v9
	v_and_b32_e32 v9, 0xffff0000, v9
	v_lshlrev_b32_e32 v104, 16, v10
	v_and_b32_e32 v105, 0xffff0000, v10
	v_lshlrev_b32_e32 v10, 16, v11
	v_and_b32_e32 v11, 0xffff0000, v11
	s_waitcnt vmcnt(8)
; #define LAS __attribute__((address_space(3)))
; __device__ __forceinline__ void conv_phase(LAS unsigned char* lds, const bf16_t* U, bf16_t* C, const float* wdw, const float* bdw, const float* lng, const float* lnb,
;                                            int first, int stride, int end, int tid, int wave, int lane) {
;     ...
; #pragma unroll
;             for (int t = 0; t < 4; ++t) { wt[t][0] = wq[0]; wt[t][1] = wq[1]; wq += D / 4; asm volatile("" : "+v"(wq)); }
; #pragma unroll
;             for (int r = 0; r < TT / NWAVES + CW - 1; ++r) {
;                 if (r + 4 < CW) { wt[(r + 4) & 7][0] = wq[0]; wt[(r + 4) & 7][1] = wq[1]; wq += D / 4; asm volatile("" : "+v"(wq)); }
;                 const u32x4 xv = *(const LAS u32x4*)(lds + (4 * wave + r) * 2048 + p * 1024 + lane * 16);
;                 f32x2 x[4];
; #pragma unroll
;                 for (int i = 0; i < 4; ++i) x[i] = (f32x2){__uint_as_float(xv[i] << 16), __uint_as_float(xv[i] & 0xffff0000u)};
; #pragma unroll
;                 for (int j = 0; j < 4; ++j) { const int w = r - j;
;                     if (w >= 0 && w < CW) {
; #pragma unroll
;                         for (int c = 0; c < 4; ++c) { const f32x4 wv = wt[w & 7][c >> 1]; const f32x2 w2 = (c & 1) ? (f32x2){wv.z, wv.w} : (f32x2){wv.x, wv.y}; acc[p][j][c] = __builtin_elementwise_fma(w2, x[c], acc[p][j][c]); } } }
;                 asm volatile("" ::: "memory");
;             }
	v_pk_fma_f32 v[102:103], v[40:41], v[70:71], v[102:103]
	v_pk_fma_f32 v[108:109], v[48:49], v[70:71], v[108:109]
	v_pk_fma_f32 v[116:117], v[56:57], v[70:71], v[116:117]
	v_pk_fma_f32 v[72:73], v[36:37], v[70:71], v[72:73]
	v_pk_fma_f32 v[74:75], v[38:39], v[8:9], v[74:75]
	v_pk_fma_f32 v[14:15], v[14:15], v[10:11], v[68:69]
	global_load_dwordx4 v[36:39], v[78:79], off offset:16
	global_load_dwordx4 v[68:71], v[78:79], off
	v_pk_fma_f32 v[12:13], v[12:13], v[104:105], v[76:77]
	v_lshl_add_u64 v[76:77], v[78:79], 0, s[0:1]
	v_pk_fma_f32 v[100:101], v[42:43], v[8:9], v[100:101]
	v_pk_fma_f32 v[106:107], v[30:31], v[10:11], v[106:107]
	v_pk_fma_f32 v[110:111], v[50:51], v[8:9], v[110:111]
	v_pk_fma_f32 v[114:115], v[22:23], v[10:11], v[114:115]
	v_pk_fma_f32 v[118:119], v[58:59], v[8:9], v[118:119]
	v_pk_fma_f32 v[80:81], v[18:19], v[10:11], v[80:81]
	ds_read_b128 v[8:11], v134 offset:38912
	v_pk_fma_f32 v[82:83], v[28:29], v[104:105], v[82:83]
	v_pk_fma_f32 v[112:113], v[20:21], v[104:105], v[112:113]
	v_pk_fma_f32 v[120:121], v[16:17], v[104:105], v[120:121]
	s_waitcnt lgkmcnt(0)
	v_lshlrev_b32_e32 v78, 16, v8
	v_and_b32_e32 v79, 0xffff0000, v8
	v_lshlrev_b32_e32 v8, 16, v9
	v_and_b32_e32 v9, 0xffff0000, v9
	v_lshlrev_b32_e32 v104, 16, v10
	v_and_b32_e32 v105, 0xffff0000, v10
	v_lshlrev_b32_e32 v10, 16, v11
	v_and_b32_e32 v11, 0xffff0000, v11
	s_waitcnt vmcnt(8)
	v_pk_fma_f32 v[102:103], v[44:45], v[78:79], v[102:103]
	v_pk_fma_f32 v[108:109], v[40:41], v[78:79], v[108:109]
	v_pk_fma_f32 v[116:117], v[48:49], v[78:79], v[116:117]
	v_pk_fma_f32 v[78:79], v[56:57], v[78:79], v[72:73]
	v_pk_fma_f32 v[122:123], v[58:59], v[8:9], v[74:75]
	v_pk_fma_f32 v[12:13], v[16:17], v[104:105], v[12:13]
	global_load_dwordx4 v[56:59], v[76:77], off offset:16
	global_load_dwordx4 v[72:75], v[76:77], off
	v_lshl_add_u64 v[16:17], v[76:77], 0, s[0:1]
	v_pk_fma_f32 v[100:101], v[46:47], v[8:9], v[100:101]
	v_pk_fma_f32 v[106:107], v[26:27], v[10:11], v[106:107]
	v_pk_fma_f32 v[110:111], v[42:43], v[8:9], v[110:111]
	v_pk_fma_f32 v[114:115], v[30:31], v[10:11], v[114:115]
	v_pk_fma_f32 v[118:119], v[50:51], v[8:9], v[118:119]
	v_pk_fma_f32 v[80:81], v[22:23], v[10:11], v[80:81]
	v_pk_fma_f32 v[14:15], v[18:19], v[10:11], v[14:15]
	ds_read_b128 v[8:11], v134 offset:40960
	v_pk_fma_f32 v[82:83], v[24:25], v[104:105], v[82:83]
	v_pk_fma_f32 v[112:113], v[28:29], v[104:105], v[112:113]
	v_pk_fma_f32 v[120:121], v[20:21], v[104:105], v[120:121]
	s_waitcnt lgkmcnt(0)
	v_lshlrev_b32_e32 v18, 16, v8
	v_and_b32_e32 v19, 0xffff0000, v8
	v_lshlrev_b32_e32 v8, 16, v9
	v_and_b32_e32 v9, 0xffff0000, v9
	v_lshlrev_b32_e32 v76, 16, v10
	v_and_b32_e32 v77, 0xffff0000, v10
	v_lshlrev_b32_e32 v10, 16, v11
	v_and_b32_e32 v11, 0xffff0000, v11
	s_waitcnt vmcnt(8)
	v_pk_fma_f32 v[102:103], v[52:53], v[18:19], v[102:103]
	v_pk_fma_f32 v[82:83], v[0:1], v[76:77], v[82:83]
	v_pk_fma_f32 v[104:105], v[2:3], v[10:11], v[106:107]
	v_pk_fma_f32 v[106:107], v[44:45], v[18:19], v[108:109]
	v_pk_fma_f32 v[108:109], v[46:47], v[8:9], v[110:111]
	v_pk_fma_f32 v[110:111], v[24:25], v[76:77], v[112:113]
	v_pk_fma_f32 v[112:113], v[26:27], v[10:11], v[114:115]
	v_pk_fma_f32 v[114:115], v[40:41], v[18:19], v[116:117]
	v_pk_fma_f32 v[116:117], v[42:43], v[8:9], v[118:119]
	v_pk_fma_f32 v[118:119], v[28:29], v[76:77], v[120:121]
	v_pk_fma_f32 v[18:19], v[48:49], v[18:19], v[78:79]
	v_pk_fma_f32 v[120:121], v[50:51], v[8:9], v[122:123]
	v_pk_fma_f32 v[12:13], v[20:21], v[76:77], v[12:13]
	global_load_dwordx4 v[48:51], v[16:17], off offset:16
	global_load_dwordx4 v[76:79], v[16:17], off
	v_lshl_add_u64 v[16:17], v[16:17], 0, s[0:1]
	v_pk_fma_f32 v[100:101], v[54:55], v[8:9], v[100:101]
	v_pk_fma_f32 v[80:81], v[30:31], v[10:11], v[80:81]
	v_pk_fma_f32 v[14:15], v[22:23], v[10:11], v[14:15]
	ds_read_b128 v[8:11], v134 offset:43008
	s_waitcnt lgkmcnt(0)
	v_lshlrev_b32_e32 v20, 16, v8
	v_and_b32_e32 v21, 0xffff0000, v8
	v_lshlrev_b32_e32 v8, 16, v9
	v_and_b32_e32 v9, 0xffff0000, v9
	v_lshlrev_b32_e32 v22, 16, v10
	v_and_b32_e32 v23, 0xffff0000, v10
	v_lshlrev_b32_e32 v10, 16, v11
	v_and_b32_e32 v11, 0xffff0000, v11
	s_waitcnt vmcnt(8)
	v_pk_fma_f32 v[102:103], v[60:61], v[20:21], v[102:103]
	v_pk_fma_f32 v[106:107], v[52:53], v[20:21], v[106:107]
	v_pk_fma_f32 v[114:115], v[44:45], v[20:21], v[114:115]
	v_pk_fma_f32 v[18:19], v[40:41], v[20:21], v[18:19]
	v_pk_fma_f32 v[20:21], v[42:43], v[8:9], v[120:121]
	v_pk_fma_f32 v[12:13], v[28:29], v[22:23], v[12:13]
	v_pk_fma_f32 v[14:15], v[30:31], v[10:11], v[14:15]
	global_load_dwordx4 v[28:31], v[16:17], off offset:16
	global_load_dwordx4 v[40:43], v[16:17], off
	v_lshl_add_u64 v[16:17], v[16:17], 0, s[0:1]
	v_pk_fma_f32 v[100:101], v[62:63], v[8:9], v[100:101]
	v_pk_fma_f32 v[104:105], v[6:7], v[10:11], v[104:105]
	v_pk_fma_f32 v[108:109], v[54:55], v[8:9], v[108:109]
	v_pk_fma_f32 v[112:113], v[2:3], v[10:11], v[112:113]
	v_pk_fma_f32 v[116:117], v[46:47], v[8:9], v[116:117]
	v_pk_fma_f32 v[80:81], v[26:27], v[10:11], v[80:81]
	ds_read_b128 v[8:11], v134 offset:45056
	v_pk_fma_f32 v[82:83], v[4:5], v[22:23], v[82:83]
	v_pk_fma_f32 v[110:111], v[0:1], v[22:23], v[110:111]
	v_pk_fma_f32 v[118:119], v[24:25], v[22:23], v[118:119]
	s_waitcnt lgkmcnt(0)
	v_lshlrev_b32_e32 v120, 16, v10
	v_and_b32_e32 v121, 0xffff0000, v10
	v_lshlrev_b32_e32 v22, 16, v8
	v_and_b32_e32 v23, 0xffff0000, v8
	v_lshlrev_b32_e32 v8, 16, v9
	v_and_b32_e32 v9, 0xffff0000, v9
	v_lshlrev_b32_e32 v10, 16, v11
	v_and_b32_e32 v11, 0xffff0000, v11
	s_waitcnt vmcnt(9)
; #define LAS __attribute__((address_space(3)))
; __device__ __forceinline__ void conv_phase(LAS unsigned char* lds, const bf16_t* U, bf16_t* C, const float* wdw, const float* bdw, const float* lng, const float* lnb,
;                                            int first, int stride, int end, int tid, int wave, int lane) {
;     ...
; #pragma unroll
;             for (int t = 0; t < 4; ++t) { wt[t][0] = wq[0]; wt[t][1] = wq[1]; wq += D / 4; asm volatile("" : "+v"(wq)); }
; #pragma unroll
;             for (int r = 0; r < TT / NWAVES + CW - 1; ++r) {
;                 if (r + 4 < CW) { wt[(r + 4) & 7][0] = wq[0]; wt[(r + 4) & 7][1] = wq[1]; wq += D / 4; asm volatile("" : "+v"(wq)); }
;                 const u32x4 xv = *(const LAS u32x4*)(lds + (4 * wave + r) * 2048 + p * 1024 + lane * 16);
;                 f32x2 x[4];
; #pragma unroll
;                 for (int i = 0; i < 4; ++i) x[i] = (f32x2){__uint_as_float(xv[i] << 16), __uint_as_float(xv[i] & 0xffff0000u)};
; #pragma unroll
;                 for (int j = 0; j < 4; ++j) { const int w = r - j;
;                     if (w >= 0 && w < CW) {
; #pragma unroll
;                         for (int c = 0; c < 4; ++c) { const f32x4 wv = wt[w & 7][c >> 1]; const f32x2 w2 = (c & 1) ? (f32x2){wv.z, wv.w} : (f32x2){wv.x, wv.y}; acc[p][j][c] = __builtin_elementwise_fma(w2, x[c], acc[p][j][c]); } } }
;                 asm volatile("" ::: "memory");
;             }
	v_pk_fma_f32 v[82:83], v[32:33], v[120:121], v[82:83]
	v_pk_fma_f32 v[110:111], v[4:5], v[120:121], v[110:111]
	v_pk_fma_f32 v[118:119], v[0:1], v[120:121], v[118:119]
	v_pk_fma_f32 v[12:13], v[24:25], v[120:121], v[12:13]
	v_lshl_add_u64 v[120:121], v[16:17], 0, s[0:1]
	s_waitcnt vmcnt(8)
	v_pk_fma_f32 v[100:101], v[66:67], v[8:9], v[100:101]
	v_pk_fma_f32 v[104:105], v[34:35], v[10:11], v[104:105]
	v_pk_fma_f32 v[108:109], v[62:63], v[8:9], v[108:109]
	v_pk_fma_f32 v[112:113], v[6:7], v[10:11], v[112:113]
	v_pk_fma_f32 v[116:117], v[54:55], v[8:9], v[116:117]
	v_pk_fma_f32 v[80:81], v[2:3], v[10:11], v[80:81]
	v_pk_fma_f32 v[18:19], v[44:45], v[22:23], v[18:19]
	v_pk_fma_f32 v[20:21], v[46:47], v[8:9], v[20:21]
	v_pk_fma_f32 v[14:15], v[26:27], v[10:11], v[14:15]
	global_load_dwordx4 v[24:27], v[16:17], off offset:16
	global_load_dwordx4 v[44:47], v[16:17], off
	ds_read_b128 v[8:11], v134 offset:47104
	v_pk_fma_f32 v[102:103], v[64:65], v[22:23], v[102:103]
	v_pk_fma_f32 v[106:107], v[60:61], v[22:23], v[106:107]
	v_pk_fma_f32 v[114:115], v[52:53], v[22:23], v[114:115]
	s_waitcnt lgkmcnt(0)
	v_lshlrev_b32_e32 v16, 16, v8
	v_and_b32_e32 v17, 0xffff0000, v8
	v_lshlrev_b32_e32 v8, 16, v9
	v_and_b32_e32 v9, 0xffff0000, v9
	v_lshlrev_b32_e32 v22, 16, v10
	v_and_b32_e32 v23, 0xffff0000, v10
	s_waitcnt vmcnt(8)
	v_pk_fma_f32 v[102:103], v[68:69], v[16:17], v[102:103]
	v_pk_fma_f32 v[100:101], v[70:71], v[8:9], v[100:101]
	v_pk_fma_f32 v[82:83], v[36:37], v[22:23], v[82:83]
	v_pk_fma_f32 v[106:107], v[64:65], v[16:17], v[106:107]
	v_pk_fma_f32 v[108:109], v[66:67], v[8:9], v[108:109]
	v_pk_fma_f32 v[110:111], v[32:33], v[22:23], v[110:111]
	v_pk_fma_f32 v[114:115], v[60:61], v[16:17], v[114:115]
	v_pk_fma_f32 v[116:117], v[62:63], v[8:9], v[116:117]
	v_pk_fma_f32 v[118:119], v[4:5], v[22:23], v[118:119]
	v_pk_fma_f32 v[52:53], v[52:53], v[16:17], v[18:19]
	v_pk_fma_f32 v[8:9], v[54:55], v[8:9], v[20:21]
	v_pk_fma_f32 v[12:13], v[0:1], v[22:23], v[12:13]
	global_load_dwordx4 v[16:19], v[120:121], off offset:16
	global_load_dwordx4 v[20:23], v[120:121], off
	v_lshlrev_b32_e32 v10, 16, v11
	v_and_b32_e32 v11, 0xffff0000, v11
	v_lshl_add_u64 v[54:55], v[120:121], 0, s[0:1]
	v_pk_fma_f32 v[104:105], v[38:39], v[10:11], v[104:105]
	v_pk_fma_f32 v[112:113], v[34:35], v[10:11], v[112:113]
	v_pk_fma_f32 v[80:81], v[6:7], v[10:11], v[80:81]
	v_pk_fma_f32 v[10:11], v[2:3], v[10:11], v[14:15]
	ds_read_b128 v[0:3], v134 offset:49152
	s_waitcnt lgkmcnt(0)
	v_lshlrev_b32_e32 v14, 16, v0
	v_and_b32_e32 v15, 0xffff0000, v0
	v_lshlrev_b32_e32 v0, 16, v1
	v_and_b32_e32 v1, 0xffff0000, v1
	v_lshlrev_b32_e32 v120, 16, v2
	v_and_b32_e32 v121, 0xffff0000, v2
	v_lshlrev_b32_e32 v2, 16, v3
	v_and_b32_e32 v3, 0xffff0000, v3
	s_waitcnt vmcnt(8)
	v_pk_fma_f32 v[102:103], v[72:73], v[14:15], v[102:103]
	v_pk_fma_f32 v[106:107], v[68:69], v[14:15], v[106:107]
	v_pk_fma_f32 v[114:115], v[64:65], v[14:15], v[114:115]
	v_pk_fma_f32 v[52:53], v[60:61], v[14:15], v[52:53]
	v_pk_fma_f32 v[60:61], v[62:63], v[0:1], v[8:9]
	v_pk_fma_f32 v[4:5], v[4:5], v[120:121], v[12:13]
	v_pk_fma_f32 v[6:7], v[6:7], v[2:3], v[10:11]
	global_load_dwordx4 v[8:11], v[54:55], off offset:16
	global_load_dwordx4 v[12:15], v[54:55], off
	v_lshl_add_u64 v[54:55], v[54:55], 0, s[0:1]
	v_pk_fma_f32 v[100:101], v[74:75], v[0:1], v[100:101]
	v_pk_fma_f32 v[104:105], v[58:59], v[2:3], v[104:105]
	v_pk_fma_f32 v[108:109], v[70:71], v[0:1], v[108:109]
	v_pk_fma_f32 v[112:113], v[38:39], v[2:3], v[112:113]
	v_pk_fma_f32 v[116:117], v[66:67], v[0:1], v[116:117]
	v_pk_fma_f32 v[80:81], v[34:35], v[2:3], v[80:81]
	ds_read_b128 v[0:3], v134 offset:51200
	v_pk_fma_f32 v[82:83], v[56:57], v[120:121], v[82:83]
	v_pk_fma_f32 v[110:111], v[36:37], v[120:121], v[110:111]
	v_pk_fma_f32 v[118:119], v[32:33], v[120:121], v[118:119]
	s_waitcnt lgkmcnt(0)
	v_lshlrev_b32_e32 v62, 16, v0
	v_and_b32_e32 v63, 0xffff0000, v0
	v_lshlrev_b32_e32 v0, 16, v1
	v_and_b32_e32 v1, 0xffff0000, v1
	v_lshlrev_b32_e32 v120, 16, v2
	v_and_b32_e32 v121, 0xffff0000, v2
	v_lshlrev_b32_e32 v2, 16, v3
	v_and_b32_e32 v3, 0xffff0000, v3
	s_waitcnt vmcnt(8)
	v_pk_fma_f32 v[102:103], v[76:77], v[62:63], v[102:103]
	v_pk_fma_f32 v[100:101], v[78:79], v[0:1], v[100:101]
	v_pk_fma_f32 v[104:105], v[50:51], v[2:3], v[104:105]
	v_pk_fma_f32 v[106:107], v[72:73], v[62:63], v[106:107]
	v_pk_fma_f32 v[108:109], v[74:75], v[0:1], v[108:109]
	v_pk_fma_f32 v[112:113], v[58:59], v[2:3], v[112:113]
	v_pk_fma_f32 v[114:115], v[68:69], v[62:63], v[114:115]
	v_pk_fma_f32 v[116:117], v[70:71], v[0:1], v[116:117]
	v_pk_fma_f32 v[80:81], v[38:39], v[2:3], v[80:81]
	v_pk_fma_f32 v[52:53], v[64:65], v[62:63], v[52:53]
	v_pk_fma_f32 v[60:61], v[66:67], v[0:1], v[60:61]
	v_pk_fma_f32 v[62:63], v[32:33], v[120:121], v[4:5]
	v_pk_fma_f32 v[64:65], v[34:35], v[2:3], v[6:7]
	global_load_dwordx4 v[4:7], v[54:55], off offset:16
	global_load_dwordx4 v[0:3], v[54:55], off
	v_lshl_add_u64 v[32:33], v[54:55], 0, s[0:1]
	ds_read_b128 v[32:35], v134 offset:53248
	v_pk_fma_f32 v[82:83], v[48:49], v[120:121], v[82:83]
	v_pk_fma_f32 v[110:111], v[56:57], v[120:121], v[110:111]
	v_pk_fma_f32 v[118:119], v[36:37], v[120:121], v[118:119]
	s_waitcnt lgkmcnt(0)
	v_lshlrev_b32_e32 v54, 16, v32
	v_and_b32_e32 v55, 0xffff0000, v32
	v_lshlrev_b32_e32 v32, 16, v33
	v_and_b32_e32 v33, 0xffff0000, v33
	v_lshlrev_b32_e32 v66, 16, v34
	v_and_b32_e32 v67, 0xffff0000, v34
	v_lshlrev_b32_e32 v34, 16, v35
	v_and_b32_e32 v35, 0xffff0000, v35
	s_waitcnt vmcnt(8)
; #define LAS __attribute__((address_space(3)))
; __device__ __forceinline__ void conv_phase(LAS unsigned char* lds, const bf16_t* U, bf16_t* C, const float* wdw, const float* bdw, const float* lng, const float* lnb,
;                                            int first, int stride, int end, int tid, int wave, int lane) {
;     ...
; #pragma unroll
;             for (int t = 0; t < 4; ++t) { wt[t][0] = wq[0]; wt[t][1] = wq[1]; wq += D / 4; asm volatile("" : "+v"(wq)); }
; #pragma unroll
;             for (int r = 0; r < TT / NWAVES + CW - 1; ++r) {
;                 if (r + 4 < CW) { wt[(r + 4) & 7][0] = wq[0]; wt[(r + 4) & 7][1] = wq[1]; wq += D / 4; asm volatile("" : "+v"(wq)); }
;                 const u32x4 xv = *(const LAS u32x4*)(lds + (4 * wave + r) * 2048 + p * 1024 + lane * 16);
;                 f32x2 x[4];
; #pragma unroll
;                 for (int i = 0; i < 4; ++i) x[i] = (f32x2){__uint_as_float(xv[i] << 16), __uint_as_float(xv[i] & 0xffff0000u)};
; #pragma unroll
;                 for (int j = 0; j < 4; ++j) { const int w = r - j;
;                     if (w >= 0 && w < CW) {
; #pragma unroll
;                         for (int c = 0; c < 4; ++c) { const f32x4 wv = wt[w & 7][c >> 1]; const f32x2 w2 = (c & 1) ? (f32x2){wv.z, wv.w} : (f32x2){wv.x, wv.y}; acc[p][j][c] = __builtin_elementwise_fma(w2, x[c], acc[p][j][c]); } } }
;                 asm volatile("" ::: "memory");
;             }
	v_pk_fma_f32 v[102:103], v[40:41], v[54:55], v[102:103]
	v_pk_fma_f32 v[100:101], v[42:43], v[32:33], v[100:101]
	v_pk_fma_f32 v[104:105], v[30:31], v[34:35], v[104:105]
	v_pk_fma_f32 v[106:107], v[76:77], v[54:55], v[106:107]
	v_pk_fma_f32 v[108:109], v[78:79], v[32:33], v[108:109]
	v_pk_fma_f32 v[112:113], v[50:51], v[34:35], v[112:113]
	v_pk_fma_f32 v[114:115], v[72:73], v[54:55], v[114:115]
	v_pk_fma_f32 v[116:117], v[74:75], v[32:33], v[116:117]
	v_pk_fma_f32 v[80:81], v[58:59], v[34:35], v[80:81]
	v_pk_fma_f32 v[52:53], v[68:69], v[54:55], v[52:53]
	v_pk_fma_f32 v[54:55], v[70:71], v[32:33], v[60:61]
	v_pk_fma_f32 v[38:39], v[38:39], v[34:35], v[64:65]
	ds_read_b128 v[32:35], v134 offset:55296
	v_pk_fma_f32 v[36:37], v[36:37], v[66:67], v[62:63]
	v_pk_fma_f32 v[82:83], v[28:29], v[66:67], v[82:83]
	v_pk_fma_f32 v[110:111], v[48:49], v[66:67], v[110:111]
	s_waitcnt lgkmcnt(0)
	v_lshlrev_b32_e32 v60, 16, v32
	v_and_b32_e32 v61, 0xffff0000, v32
	v_lshlrev_b32_e32 v32, 16, v33
	v_and_b32_e32 v33, 0xffff0000, v33
	v_lshlrev_b32_e32 v62, 16, v34
	v_and_b32_e32 v63, 0xffff0000, v34
	v_lshlrev_b32_e32 v34, 16, v35
	v_and_b32_e32 v35, 0xffff0000, v35
	v_pk_fma_f32 v[118:119], v[56:57], v[66:67], v[118:119]
	s_waitcnt vmcnt(6)
	v_pk_fma_f32 v[66:67], v[46:47], v[32:33], v[100:101]
	v_pk_fma_f32 v[70:71], v[26:27], v[34:35], v[104:105]
	v_pk_fma_f32 v[100:101], v[42:43], v[32:33], v[108:109]
	v_pk_fma_f32 v[104:105], v[30:31], v[34:35], v[112:113]
	v_pk_fma_f32 v[108:109], v[78:79], v[32:33], v[116:117]
	v_pk_fma_f32 v[80:81], v[50:51], v[34:35], v[80:81]
	v_pk_fma_f32 v[54:55], v[74:75], v[32:33], v[54:55]
	v_pk_fma_f32 v[38:39], v[58:59], v[34:35], v[38:39]
	ds_read_b128 v[32:35], v134 offset:57344
	v_pk_fma_f32 v[36:37], v[56:57], v[62:63], v[36:37]
	v_pk_fma_f32 v[64:65], v[44:45], v[60:61], v[102:103]
	v_pk_fma_f32 v[68:69], v[24:25], v[62:63], v[82:83]
	s_waitcnt lgkmcnt(0)
	v_lshlrev_b32_e32 v56, 16, v32
	v_and_b32_e32 v57, 0xffff0000, v32
	v_lshlrev_b32_e32 v32, 16, v33
	v_and_b32_e32 v33, 0xffff0000, v33
	v_lshlrev_b32_e32 v58, 16, v34
	v_and_b32_e32 v59, 0xffff0000, v34
	v_lshlrev_b32_e32 v34, 16, v35
	v_and_b32_e32 v35, 0xffff0000, v35
	v_pk_fma_f32 v[102:103], v[28:29], v[62:63], v[110:111]
	v_pk_fma_f32 v[110:111], v[48:49], v[62:63], v[118:119]
	s_waitcnt vmcnt(4)
	v_pk_fma_f32 v[62:63], v[22:23], v[32:33], v[66:67]
	v_pk_fma_f32 v[66:67], v[18:19], v[34:35], v[70:71]
	v_pk_fma_f32 v[70:71], v[46:47], v[32:33], v[100:101]
	v_pk_fma_f32 v[74:75], v[26:27], v[34:35], v[104:105]
	v_pk_fma_f32 v[100:101], v[42:43], v[32:33], v[108:109]
	v_pk_fma_f32 v[80:81], v[30:31], v[34:35], v[80:81]
	v_pk_fma_f32 v[54:55], v[78:79], v[32:33], v[54:55]
	v_pk_fma_f32 v[38:39], v[50:51], v[34:35], v[38:39]
	ds_read_b128 v[32:35], v134 offset:59392
	v_pk_fma_f32 v[36:37], v[48:49], v[58:59], v[36:37]
	v_pk_fma_f32 v[52:53], v[72:73], v[60:61], v[52:53]
	v_pk_fma_f32 v[72:73], v[24:25], v[58:59], v[102:103]
	s_waitcnt lgkmcnt(0)
	v_lshlrev_b32_e32 v50, 16, v34
	v_and_b32_e32 v51, 0xffff0000, v34
	v_lshlrev_b32_e32 v34, 16, v35
	v_and_b32_e32 v35, 0xffff0000, v35
	v_pk_fma_f32 v[102:103], v[28:29], v[58:59], v[110:111]
	v_pk_fma_f32 v[36:37], v[28:29], v[50:51], v[36:37]
	v_pk_fma_f32 v[38:39], v[30:31], v[34:35], v[38:39]
	ds_read_b128 v[28:31], v134 offset:61440
	v_pk_fma_f32 v[82:83], v[40:41], v[60:61], v[106:107]
	v_pk_fma_f32 v[106:107], v[76:77], v[60:61], v[114:115]
	v_pk_fma_f32 v[60:61], v[20:21], v[56:57], v[64:65]
	v_pk_fma_f32 v[64:65], v[16:17], v[58:59], v[68:69]
	v_pk_fma_f32 v[68:69], v[44:45], v[56:57], v[82:83]
	v_pk_fma_f32 v[82:83], v[40:41], v[56:57], v[106:107]
	v_pk_fma_f32 v[52:53], v[76:77], v[56:57], v[52:53]
	v_lshlrev_b32_e32 v48, 16, v32
	v_and_b32_e32 v49, 0xffff0000, v32
	v_lshlrev_b32_e32 v32, 16, v33
	v_and_b32_e32 v33, 0xffff0000, v33
	s_waitcnt vmcnt(2)
	v_pk_fma_f32 v[56:57], v[12:13], v[48:49], v[60:61]
	v_pk_fma_f32 v[60:61], v[8:9], v[50:51], v[64:65]
	v_pk_fma_f32 v[64:65], v[20:21], v[48:49], v[68:69]
	v_pk_fma_f32 v[68:69], v[16:17], v[50:51], v[72:73]
	v_pk_fma_f32 v[72:73], v[44:45], v[48:49], v[82:83]
	v_pk_fma_f32 v[76:77], v[24:25], v[50:51], v[102:103]
	v_pk_fma_f32 v[40:41], v[40:41], v[48:49], v[52:53]
	v_pk_fma_f32 v[42:43], v[42:43], v[32:33], v[54:55]
	s_waitcnt lgkmcnt(0)
	v_lshlrev_b32_e32 v48, 16, v28
	v_and_b32_e32 v49, 0xffff0000, v28
	v_lshlrev_b32_e32 v50, 16, v29
	v_and_b32_e32 v51, 0xffff0000, v29
	v_lshlrev_b32_e32 v52, 16, v30
	v_and_b32_e32 v53, 0xffff0000, v30
	v_lshlrev_b32_e32 v54, 16, v31
	v_and_b32_e32 v55, 0xffff0000, v31
	v_pk_fma_f32 v[58:59], v[14:15], v[32:33], v[62:63]
	v_pk_fma_f32 v[62:63], v[10:11], v[34:35], v[66:67]
	v_pk_fma_f32 v[66:67], v[22:23], v[32:33], v[70:71]
	v_pk_fma_f32 v[70:71], v[18:19], v[34:35], v[74:75]
	v_pk_fma_f32 v[74:75], v[46:47], v[32:33], v[100:101]
	v_pk_fma_f32 v[78:79], v[26:27], v[34:35], v[80:81]
	v_pk_fma_f32 v[40:41], v[44:45], v[48:49], v[40:41]
	v_pk_fma_f32 v[42:43], v[46:47], v[50:51], v[42:43]
	v_pk_fma_f32 v[44:45], v[24:25], v[52:53], v[36:37]
	v_pk_fma_f32 v[46:47], v[26:27], v[54:55], v[38:39]
	ds_read_b128 v[24:27], v134 offset:63488
	s_waitcnt vmcnt(0)
	v_pk_fma_f32 v[28:29], v[0:1], v[48:49], v[56:57]
	v_pk_fma_f32 v[30:31], v[2:3], v[50:51], v[58:59]
	v_pk_fma_f32 v[32:33], v[4:5], v[52:53], v[60:61]
	v_pk_fma_f32 v[34:35], v[6:7], v[54:55], v[62:63]
	v_pk_fma_f32 v[56:57], v[12:13], v[48:49], v[64:65]
	v_pk_fma_f32 v[58:59], v[14:15], v[50:51], v[66:67]
	v_pk_fma_f32 v[60:61], v[8:9], v[52:53], v[68:69]
	v_pk_fma_f32 v[62:63], v[10:11], v[54:55], v[70:71]
	v_pk_fma_f32 v[64:65], v[20:21], v[48:49], v[72:73]
	v_pk_fma_f32 v[66:67], v[22:23], v[50:51], v[74:75]
	v_pk_fma_f32 v[68:69], v[16:17], v[52:53], v[76:77]
	v_pk_fma_f32 v[70:71], v[18:19], v[54:55], v[78:79]
	s_waitcnt lgkmcnt(0)
; #define LAS __attribute__((address_space(3)))
; __device__ __forceinline__ void conv_phase(LAS unsigned char* lds, const bf16_t* U, bf16_t* C, const float* wdw, const float* bdw, const float* lng, const float* lnb,
;                                            int first, int stride, int end, int tid, int wave, int lane) {
;     ...
;             for (int r = 0; r < TT / NWAVES + CW - 1; ++r) {
;                 if (r + 4 < CW) { wt[(r + 4) & 7][0] = wq[0]; wt[(r + 4) & 7][1] = wq[1]; wq += D / 4; asm volatile("" : "+v"(wq)); }
;                 const u32x4 xv = *(const LAS u32x4*)(lds + (4 * wave + r) * 2048 + p * 1024 + lane * 16);
;                 f32x2 x[4];
; #pragma unroll
;                 for (int i = 0; i < 4; ++i) x[i] = (f32x2){__uint_as_float(xv[i] << 16), __uint_as_float(xv[i] & 0xffff0000u)};
; #pragma unroll
;                 for (int j = 0; j < 4; ++j) { const int w = r - j;
;                     if (w >= 0 && w < CW) {
; #pragma unroll
;                         for (int c = 0; c < 4; ++c) { const f32x4 wv = wt[w & 7][c >> 1]; const f32x2 w2 = (c & 1) ? (f32x2){wv.z, wv.w} : (f32x2){wv.x, wv.y}; acc[p][j][c] = __builtin_elementwise_fma(w2, x[c], acc[p][j][c]); } } }
;                 asm volatile("" ::: "memory");
;             }
;             const f32x4 b0 = *(const f32x4*)(bdw + p * 512 + lane * 8), b1 = *(const f32x4*)(bdw + p * 512 + lane * 8 + 4);
; #pragma unroll
;             for (int j = 0; j < 4; ++j) { acc[p][j][0] += (f32x2){b0.x, b0.y}; acc[p][j][1] += (f32x2){b0.z, b0.w}; acc[p][j][2] += (f32x2){b1.x, b1.y}; acc[p][j][3] += (f32x2){b1.z, b1.w}; }
	v_lshlrev_b32_e32 v48, 16, v24
	v_and_b32_e32 v49, 0xffff0000, v24
	v_lshlrev_b32_e32 v50, 16, v25
	v_and_b32_e32 v51, 0xffff0000, v25
	v_lshlrev_b32_e32 v52, 16, v26
	v_and_b32_e32 v53, 0xffff0000, v26
	v_lshlrev_b32_e32 v54, 16, v27
	v_and_b32_e32 v55, 0xffff0000, v27
	v_pk_fma_f32 v[20:21], v[20:21], v[48:49], v[40:41]
	v_pk_fma_f32 v[22:23], v[22:23], v[50:51], v[42:43]
	v_pk_fma_f32 v[40:41], v[16:17], v[52:53], v[44:45]
	v_pk_fma_f32 v[42:43], v[18:19], v[54:55], v[46:47]
	ds_read_b128 v[16:19], v136
	v_pk_fma_f32 v[26:27], v[2:3], v[50:51], v[58:59]
	v_pk_fma_f32 v[38:39], v[6:7], v[54:55], v[62:63]
	v_pk_fma_f32 v[58:59], v[14:15], v[50:51], v[66:67]
	v_pk_fma_f32 v[62:63], v[10:11], v[54:55], v[70:71]
	s_waitcnt lgkmcnt(0)
	v_lshlrev_b32_e32 v44, 16, v16
	v_and_b32_e32 v45, 0xffff0000, v16
	v_lshlrev_b32_e32 v16, 16, v17
	v_and_b32_e32 v17, 0xffff0000, v17
	v_lshlrev_b32_e32 v46, 16, v18
	v_and_b32_e32 v47, 0xffff0000, v18
	v_lshlrev_b32_e32 v18, 16, v19
	v_and_b32_e32 v19, 0xffff0000, v19
	v_pk_fma_f32 v[36:37], v[4:5], v[52:53], v[60:61]
	v_pk_fma_f32 v[60:61], v[8:9], v[52:53], v[68:69]
	v_pk_fma_f32 v[50:51], v[2:3], v[16:17], v[58:59]
	v_pk_fma_f32 v[54:55], v[6:7], v[18:19], v[62:63]
	v_pk_fma_f32 v[14:15], v[14:15], v[16:17], v[22:23]
	v_pk_fma_f32 v[16:17], v[8:9], v[46:47], v[40:41]
	v_pk_fma_f32 v[18:19], v[10:11], v[18:19], v[42:43]
	ds_read_b128 v[8:11], v137
	v_pk_fma_f32 v[24:25], v[0:1], v[48:49], v[56:57]
	v_pk_fma_f32 v[56:57], v[12:13], v[48:49], v[64:65]
	v_pk_fma_f32 v[12:13], v[12:13], v[44:45], v[20:21]
	s_waitcnt lgkmcnt(0)
	v_lshlrev_b32_e32 v20, 16, v8
	v_and_b32_e32 v21, 0xffff0000, v8
	v_lshlrev_b32_e32 v8, 16, v9
	v_and_b32_e32 v9, 0xffff0000, v9
	v_lshlrev_b32_e32 v22, 16, v10
	v_and_b32_e32 v23, 0xffff0000, v10
	v_lshlrev_b32_e32 v10, 16, v11
	v_and_b32_e32 v11, 0xffff0000, v11
	v_pk_fma_f32 v[48:49], v[0:1], v[44:45], v[56:57]
	v_pk_fma_f32 v[52:53], v[4:5], v[46:47], v[60:61]
	v_pk_fma_f32 v[10:11], v[6:7], v[10:11], v[18:19]
	v_pk_fma_f32 v[16:17], v[4:5], v[22:23], v[16:17]
	v_pk_fma_f32 v[8:9], v[2:3], v[8:9], v[14:15]
	v_pk_fma_f32 v[12:13], v[0:1], v[20:21], v[12:13]
	v_mov_b64_e32 v[0:1], v[180:181]
	v_mov_b64_e32 v[2:3], v[182:183]
	v_mov_b64_e32 v[4:5], v[184:185]
	v_mov_b64_e32 v[6:7], v[186:187]
	s_waitcnt vmcnt(1)
	v_pk_add_f32 v[118:119], v[36:37], v[0:1]
	s_waitcnt vmcnt(0)
	v_pk_add_f32 v[128:129], v[28:29], v[4:5]
	v_pk_add_f32 v[130:131], v[30:31], v[6:7]
	v_pk_add_f32 v[120:121], v[24:25], v[4:5]
	v_pk_add_f32 v[122:123], v[26:27], v[6:7]
	v_pk_add_f32 v[116:117], v[38:39], v[2:3]
	v_pk_add_f32 v[112:113], v[4:5], v[48:49]
	v_pk_add_f32 v[114:115], v[6:7], v[50:51]
	v_pk_add_f32 v[104:105], v[4:5], v[12:13]
	v_pk_add_f32 v[106:107], v[6:7], v[8:9]
	global_load_dwordx4 v[4:7], v[84:85], off offset:2064
	global_load_dwordx4 v[36:39], v[84:85], off offset:2048
	v_pk_add_f32 v[126:127], v[32:33], v[0:1]
	v_pk_add_f32 v[110:111], v[0:1], v[52:53]
	v_pk_add_f32 v[102:103], v[0:1], v[16:17]
	v_mov_b64_e32 v[0:1], v[98:99]
	v_pk_add_f32 v[100:101], v[2:3], v[10:11]
	global_load_dwordx4 v[8:11], v[0:1], off offset:16
	global_load_dwordx4 v[12:15], v[0:1], off
	v_lshl_add_u64 v[0:1], v[0:1], 0, s[0:1]
	global_load_dwordx4 v[44:47], v[0:1], off offset:16
	global_load_dwordx4 v[64:67], v[0:1], off
	v_lshl_add_u64 v[0:1], v[0:1], 0, s[0:1]
	global_load_dwordx4 v[16:19], v[0:1], off offset:16
	global_load_dwordx4 v[48:51], v[0:1], off
	v_lshl_add_u64 v[0:1], v[0:1], 0, s[0:1]
	v_pk_add_f32 v[108:109], v[2:3], v[54:55]
	global_load_dwordx4 v[20:23], v[0:1], off offset:16
	global_load_dwordx4 v[52:55], v[0:1], off
	v_lshl_add_u64 v[28:29], v[0:1], 0, s[0:1]
	v_pk_add_f32 v[124:125], v[34:35], v[2:3]
	ds_read_b128 v[0:3], v134 offset:1024
	v_lshl_add_u64 v[42:43], v[28:29], 0, s[0:1]
	s_waitcnt lgkmcnt(0)
	v_lshlrev_b32_e32 v24, 16, v3
	v_and_b32_e32 v25, 0xffff0000, v3
	v_lshlrev_b32_e32 v26, 16, v2
	v_and_b32_e32 v27, 0xffff0000, v2
	v_lshlrev_b32_e32 v2, 16, v1
	v_and_b32_e32 v3, 0xffff0000, v1
	v_lshlrev_b32_e32 v30, 16, v0
	v_and_b32_e32 v31, 0xffff0000, v0
	s_waitcnt vmcnt(9)
	v_pk_fma_f32 v[34:35], v[4:5], v[26:27], 0 op_sel_hi:[1,1,0]
	v_pk_fma_f32 v[40:41], v[6:7], v[24:25], 0 op_sel_hi:[1,1,0]
	global_load_dwordx4 v[24:27], v[28:29], off offset:16
	global_load_dwordx4 v[56:59], v[28:29], off
	s_waitcnt vmcnt(10)
	v_pk_fma_f32 v[32:33], v[38:39], v[2:3], 0 op_sel_hi:[1,1,0]
	ds_read_b128 v[0:3], v134 offset:3072
	v_pk_fma_f32 v[30:31], v[36:37], v[30:31], 0 op_sel_hi:[1,1,0]
	s_waitcnt lgkmcnt(0)
	v_lshlrev_b32_e32 v28, 16, v0
	v_and_b32_e32 v29, 0xffff0000, v0
	v_lshlrev_b32_e32 v60, 16, v2
	v_and_b32_e32 v61, 0xffff0000, v2
	v_lshlrev_b32_e32 v0, 16, v1
	v_and_b32_e32 v1, 0xffff0000, v1
	v_lshlrev_b32_e32 v2, 16, v3
	v_and_b32_e32 v3, 0xffff0000, v3
	s_waitcnt vmcnt(8)
	v_pk_fma_f32 v[68:69], v[12:13], v[28:29], v[30:31]
	v_pk_fma_f32 v[34:35], v[8:9], v[60:61], v[34:35]
	v_pk_fma_f32 v[70:71], v[36:37], v[28:29], 0 op_sel_hi:[1,1,0]
	v_pk_fma_f32 v[74:75], v[4:5], v[60:61], 0 op_sel_hi:[1,1,0]
	global_load_dwordx4 v[28:31], v[42:43], off offset:16
	global_load_dwordx4 v[60:63], v[42:43], off
	v_lshl_add_u64 v[42:43], v[42:43], 0, s[0:1]
	v_pk_fma_f32 v[32:33], v[14:15], v[0:1], v[32:33]
	v_pk_fma_f32 v[40:41], v[10:11], v[2:3], v[40:41]
	v_pk_fma_f32 v[72:73], v[38:39], v[0:1], 0 op_sel_hi:[1,1,0]
	v_pk_fma_f32 v[76:77], v[6:7], v[2:3], 0 op_sel_hi:[1,1,0]
	ds_read_b128 v[0:3], v134 offset:5120
	v_lshl_add_u64 v[150:151], v[42:43], 0, s[0:1]
	s_waitcnt lgkmcnt(0)
; #define LAS __attribute__((address_space(3)))
; __device__ __forceinline__ void conv_phase(LAS unsigned char* lds, const bf16_t* U, bf16_t* C, const float* wdw, const float* bdw, const float* lng, const float* lnb,
;                                            int first, int stride, int end, int tid, int wave, int lane) {
;     ...
;             for (int r = 0; r < TT / NWAVES + CW - 1; ++r) {
;                 if (r + 4 < CW) { wt[(r + 4) & 7][0] = wq[0]; wt[(r + 4) & 7][1] = wq[1]; wq += D / 4; asm volatile("" : "+v"(wq)); }
;                 const u32x4 xv = *(const LAS u32x4*)(lds + (4 * wave + r) * 2048 + p * 1024 + lane * 16);
;                 f32x2 x[4];
; #pragma unroll
;                 for (int i = 0; i < 4; ++i) x[i] = (f32x2){__uint_as_float(xv[i] << 16), __uint_as_float(xv[i] & 0xffff0000u)};
; #pragma unroll
;                 for (int j = 0; j < 4; ++j) { const int w = r - j;
;                     if (w >= 0 && w < CW) {
; #pragma unroll
;                         for (int c = 0; c < 4; ++c) { const f32x4 wv = wt[w & 7][c >> 1]; const f32x2 w2 = (c & 1) ? (f32x2){wv.z, wv.w} : (f32x2){wv.x, wv.y}; acc[p][j][c] = __builtin_elementwise_fma(w2, x[c], acc[p][j][c]); } } }
;                 asm volatile("" ::: "memory");
	v_lshlrev_b32_e32 v78, 16, v0
	v_and_b32_e32 v79, 0xffff0000, v0
	v_lshlrev_b32_e32 v0, 16, v1
	v_and_b32_e32 v1, 0xffff0000, v1
	v_lshlrev_b32_e32 v80, 16, v2
	v_and_b32_e32 v81, 0xffff0000, v2
	v_lshlrev_b32_e32 v2, 16, v3
	v_and_b32_e32 v3, 0xffff0000, v3
	s_waitcnt vmcnt(8)
	v_pk_fma_f32 v[82:83], v[66:67], v[0:1], v[32:33]
	v_pk_fma_f32 v[142:143], v[44:45], v[80:81], v[34:35]
	v_pk_fma_f32 v[144:145], v[46:47], v[2:3], v[40:41]
	v_pk_fma_f32 v[72:73], v[14:15], v[0:1], v[72:73]
	v_pk_fma_f32 v[76:77], v[10:11], v[2:3], v[76:77]
	v_pk_fma_f32 v[146:147], v[38:39], v[0:1], 0 op_sel_hi:[1,1,0]
	v_pk_fma_f32 v[148:149], v[6:7], v[2:3], 0 op_sel_hi:[1,1,0]
	global_load_dwordx4 v[0:3], v[42:43], off offset:16
	global_load_dwordx4 v[32:35], v[42:43], off
	ds_read_b128 v[40:43], v134 offset:7168
	v_pk_fma_f32 v[68:69], v[64:65], v[78:79], v[68:69]
	v_pk_fma_f32 v[70:71], v[12:13], v[78:79], v[70:71]
	v_pk_fma_f32 v[74:75], v[8:9], v[80:81], v[74:75]
	v_pk_fma_f32 v[78:79], v[36:37], v[78:79], 0 op_sel_hi:[1,1,0]
	v_pk_fma_f32 v[80:81], v[4:5], v[80:81], 0 op_sel_hi:[1,1,0]
	s_waitcnt lgkmcnt(0)
	v_lshlrev_b32_e32 v152, 16, v40
	v_and_b32_e32 v153, 0xffff0000, v40
	v_lshlrev_b32_e32 v40, 16, v41
	v_and_b32_e32 v41, 0xffff0000, v41
	v_lshlrev_b32_e32 v154, 16, v42
	v_and_b32_e32 v155, 0xffff0000, v42
	v_lshlrev_b32_e32 v42, 16, v43
	v_and_b32_e32 v43, 0xffff0000, v43
	s_waitcnt vmcnt(8)
	v_pk_fma_f32 v[68:69], v[48:49], v[152:153], v[68:69]
	v_pk_fma_f32 v[142:143], v[16:17], v[154:155], v[142:143]
	v_pk_fma_f32 v[70:71], v[64:65], v[152:153], v[70:71]
	v_pk_fma_f32 v[74:75], v[44:45], v[154:155], v[74:75]
	v_pk_fma_f32 v[78:79], v[12:13], v[152:153], v[78:79]
	v_pk_fma_f32 v[80:81], v[8:9], v[154:155], v[80:81]
	v_pk_fma_f32 v[152:153], v[36:37], v[152:153], 0 op_sel_hi:[1,1,0]
	v_pk_fma_f32 v[156:157], v[38:39], v[40:41], 0 op_sel_hi:[1,1,0]
	v_pk_fma_f32 v[154:155], v[4:5], v[154:155], 0 op_sel_hi:[1,1,0]
	v_pk_fma_f32 v[158:159], v[6:7], v[42:43], 0 op_sel_hi:[1,1,0]
	global_load_dwordx4 v[4:7], v[150:151], off offset:16
	global_load_dwordx4 v[36:39], v[150:151], off
	v_lshl_add_u64 v[150:151], v[150:151], 0, s[0:1]
	v_pk_fma_f32 v[82:83], v[50:51], v[40:41], v[82:83]
	v_pk_fma_f32 v[144:145], v[18:19], v[42:43], v[144:145]
	v_pk_fma_f32 v[72:73], v[66:67], v[40:41], v[72:73]
	v_pk_fma_f32 v[76:77], v[46:47], v[42:43], v[76:77]
	v_pk_fma_f32 v[146:147], v[14:15], v[40:41], v[146:147]
	v_pk_fma_f32 v[148:149], v[10:11], v[42:43], v[148:149]
	ds_read_b128 v[40:43], v134 offset:9216
	s_waitcnt lgkmcnt(0)
	v_lshlrev_b32_e32 v160, 16, v40
	v_and_b32_e32 v161, 0xffff0000, v40
	v_lshlrev_b32_e32 v40, 16, v41
	v_and_b32_e32 v41, 0xffff0000, v41
	v_lshlrev_b32_e32 v162, 16, v42
	v_and_b32_e32 v163, 0xffff0000, v42
	v_lshlrev_b32_e32 v42, 16, v43
	v_and_b32_e32 v43, 0xffff0000, v43
	s_waitcnt vmcnt(8)
	v_pk_fma_f32 v[82:83], v[54:55], v[40:41], v[82:83]
	v_pk_fma_f32 v[144:145], v[22:23], v[42:43], v[144:145]
	v_pk_fma_f32 v[72:73], v[50:51], v[40:41], v[72:73]
	v_pk_fma_f32 v[76:77], v[18:19], v[42:43], v[76:77]
	v_pk_fma_f32 v[146:147], v[66:67], v[40:41], v[146:147]
	v_pk_fma_f32 v[148:149], v[46:47], v[42:43], v[148:149]
	v_pk_fma_f32 v[156:157], v[14:15], v[40:41], v[156:157]
	v_pk_fma_f32 v[154:155], v[8:9], v[162:163], v[154:155]
	v_pk_fma_f32 v[158:159], v[10:11], v[42:43], v[158:159]
	global_load_dwordx4 v[8:11], v[150:151], off offset:16
	global_load_dwordx4 v[40:43], v[150:151], off
	v_lshl_add_u64 v[150:151], v[150:151], 0, s[0:1]
	v_pk_fma_f32 v[152:153], v[12:13], v[160:161], v[152:153]
	ds_read_b128 v[12:15], v134 offset:11264
	v_pk_fma_f32 v[68:69], v[52:53], v[160:161], v[68:69]
	v_pk_fma_f32 v[142:143], v[20:21], v[162:163], v[142:143]
	v_pk_fma_f32 v[70:71], v[48:49], v[160:161], v[70:71]
	v_pk_fma_f32 v[74:75], v[16:17], v[162:163], v[74:75]
	v_pk_fma_f32 v[78:79], v[64:65], v[160:161], v[78:79]
	v_pk_fma_f32 v[80:81], v[44:45], v[162:163], v[80:81]
	s_waitcnt lgkmcnt(0)
	v_lshlrev_b32_e32 v160, 16, v12
	v_and_b32_e32 v161, 0xffff0000, v12
	v_lshlrev_b32_e32 v12, 16, v13
	v_and_b32_e32 v13, 0xffff0000, v13
	v_lshlrev_b32_e32 v162, 16, v14
	v_and_b32_e32 v163, 0xffff0000, v14
	v_lshlrev_b32_e32 v14, 16, v15
	v_and_b32_e32 v15, 0xffff0000, v15
	s_waitcnt vmcnt(8)
	v_pk_fma_f32 v[82:83], v[58:59], v[12:13], v[82:83]
	v_pk_fma_f32 v[144:145], v[26:27], v[14:15], v[144:145]
	v_pk_fma_f32 v[72:73], v[54:55], v[12:13], v[72:73]
	v_pk_fma_f32 v[76:77], v[22:23], v[14:15], v[76:77]
	v_pk_fma_f32 v[146:147], v[50:51], v[12:13], v[146:147]
	v_pk_fma_f32 v[148:149], v[18:19], v[14:15], v[148:149]
	v_pk_fma_f32 v[156:157], v[66:67], v[12:13], v[156:157]
	v_pk_fma_f32 v[154:155], v[44:45], v[162:163], v[154:155]
	v_pk_fma_f32 v[158:159], v[46:47], v[14:15], v[158:159]
	global_load_dwordx4 v[12:15], v[150:151], off offset:16
	global_load_dwordx4 v[44:47], v[150:151], off
	v_lshl_add_u64 v[150:151], v[150:151], 0, s[0:1]
	v_pk_fma_f32 v[152:153], v[64:65], v[160:161], v[152:153]
	ds_read_b128 v[64:67], v134 offset:13312
	v_pk_fma_f32 v[68:69], v[56:57], v[160:161], v[68:69]
	v_pk_fma_f32 v[142:143], v[24:25], v[162:163], v[142:143]
	v_pk_fma_f32 v[70:71], v[52:53], v[160:161], v[70:71]
	v_pk_fma_f32 v[74:75], v[20:21], v[162:163], v[74:75]
	v_pk_fma_f32 v[78:79], v[48:49], v[160:161], v[78:79]
	v_pk_fma_f32 v[80:81], v[16:17], v[162:163], v[80:81]
	s_waitcnt lgkmcnt(0)
; #define LAS __attribute__((address_space(3)))
; __device__ __forceinline__ void conv_phase(LAS unsigned char* lds, const bf16_t* U, bf16_t* C, const float* wdw, const float* bdw, const float* lng, const float* lnb,
;                                            int first, int stride, int end, int tid, int wave, int lane) {
;     ...
;             for (int r = 0; r < TT / NWAVES + CW - 1; ++r) {
;                 if (r + 4 < CW) { wt[(r + 4) & 7][0] = wq[0]; wt[(r + 4) & 7][1] = wq[1]; wq += D / 4; asm volatile("" : "+v"(wq)); }
;                 const u32x4 xv = *(const LAS u32x4*)(lds + (4 * wave + r) * 2048 + p * 1024 + lane * 16);
;                 f32x2 x[4];
; #pragma unroll
;                 for (int i = 0; i < 4; ++i) x[i] = (f32x2){__uint_as_float(xv[i] << 16), __uint_as_float(xv[i] & 0xffff0000u)};
; #pragma unroll
;                 for (int j = 0; j < 4; ++j) { const int w = r - j;
;                     if (w >= 0 && w < CW) {
; #pragma unroll
;                         for (int c = 0; c < 4; ++c) { const f32x4 wv = wt[w & 7][c >> 1]; const f32x2 w2 = (c & 1) ? (f32x2){wv.z, wv.w} : (f32x2){wv.x, wv.y}; acc[p][j][c] = __builtin_elementwise_fma(w2, x[c], acc[p][j][c]); } } }
;                 asm volatile("" ::: "memory");
	v_lshlrev_b32_e32 v160, 16, v64
	v_and_b32_e32 v161, 0xffff0000, v64
	v_lshlrev_b32_e32 v64, 16, v65
	v_and_b32_e32 v65, 0xffff0000, v65
	v_lshlrev_b32_e32 v162, 16, v66
	v_and_b32_e32 v163, 0xffff0000, v66
	v_lshlrev_b32_e32 v66, 16, v67
	v_and_b32_e32 v67, 0xffff0000, v67
	v_pk_fma_f32 v[152:153], v[48:49], v[160:161], v[152:153]
	v_pk_fma_f32 v[156:157], v[50:51], v[64:65], v[156:157]
	v_pk_fma_f32 v[154:155], v[16:17], v[162:163], v[154:155]
	v_pk_fma_f32 v[158:159], v[18:19], v[66:67], v[158:159]
	global_load_dwordx4 v[16:19], v[150:151], off offset:16
	global_load_dwordx4 v[48:51], v[150:151], off
	v_lshl_add_u64 v[150:151], v[150:151], 0, s[0:1]
	s_waitcnt vmcnt(10)
	v_pk_fma_f32 v[82:83], v[62:63], v[64:65], v[82:83]
	v_pk_fma_f32 v[144:145], v[30:31], v[66:67], v[144:145]
	v_pk_fma_f32 v[72:73], v[58:59], v[64:65], v[72:73]
	v_pk_fma_f32 v[76:77], v[26:27], v[66:67], v[76:77]
	v_pk_fma_f32 v[146:147], v[54:55], v[64:65], v[146:147]
	v_pk_fma_f32 v[148:149], v[22:23], v[66:67], v[148:149]
	ds_read_b128 v[64:67], v134 offset:15360
	v_pk_fma_f32 v[68:69], v[60:61], v[160:161], v[68:69]
	v_pk_fma_f32 v[142:143], v[28:29], v[162:163], v[142:143]
	v_pk_fma_f32 v[70:71], v[56:57], v[160:161], v[70:71]
	v_pk_fma_f32 v[74:75], v[24:25], v[162:163], v[74:75]
	v_pk_fma_f32 v[78:79], v[52:53], v[160:161], v[78:79]
	v_pk_fma_f32 v[80:81], v[20:21], v[162:163], v[80:81]
	s_waitcnt lgkmcnt(0)
	v_lshlrev_b32_e32 v160, 16, v64
	v_and_b32_e32 v161, 0xffff0000, v64
	v_lshlrev_b32_e32 v64, 16, v65
	v_and_b32_e32 v65, 0xffff0000, v65
	v_lshlrev_b32_e32 v162, 16, v66
	v_and_b32_e32 v163, 0xffff0000, v66
	v_lshlrev_b32_e32 v66, 16, v67
	v_and_b32_e32 v67, 0xffff0000, v67
	v_pk_fma_f32 v[152:153], v[52:53], v[160:161], v[152:153]
	v_pk_fma_f32 v[156:157], v[54:55], v[64:65], v[156:157]
	v_pk_fma_f32 v[154:155], v[20:21], v[162:163], v[154:155]
	v_pk_fma_f32 v[158:159], v[22:23], v[66:67], v[158:159]
	global_load_dwordx4 v[20:23], v[150:151], off offset:16
	global_load_dwordx4 v[52:55], v[150:151], off
	v_lshl_add_u64 v[150:151], v[150:151], 0, s[0:1]
	s_waitcnt vmcnt(10)
	v_pk_fma_f32 v[82:83], v[34:35], v[64:65], v[82:83]
	v_pk_fma_f32 v[144:145], v[2:3], v[66:67], v[144:145]
	v_pk_fma_f32 v[72:73], v[62:63], v[64:65], v[72:73]
	v_pk_fma_f32 v[76:77], v[30:31], v[66:67], v[76:77]
	v_pk_fma_f32 v[146:147], v[58:59], v[64:65], v[146:147]
	v_pk_fma_f32 v[148:149], v[26:27], v[66:67], v[148:149]
	ds_read_b128 v[64:67], v134 offset:17408
	v_pk_fma_f32 v[68:69], v[32:33], v[160:161], v[68:69]
	v_pk_fma_f32 v[142:143], v[0:1], v[162:163], v[142:143]
	v_pk_fma_f32 v[70:71], v[60:61], v[160:161], v[70:71]
	v_pk_fma_f32 v[74:75], v[28:29], v[162:163], v[74:75]
	v_pk_fma_f32 v[78:79], v[56:57], v[160:161], v[78:79]
	v_pk_fma_f32 v[80:81], v[24:25], v[162:163], v[80:81]
	s_waitcnt lgkmcnt(0)
	v_lshlrev_b32_e32 v160, 16, v64
	v_and_b32_e32 v161, 0xffff0000, v64
	v_lshlrev_b32_e32 v64, 16, v65
	v_and_b32_e32 v65, 0xffff0000, v65
	v_lshlrev_b32_e32 v162, 16, v66
	v_and_b32_e32 v163, 0xffff0000, v66
	v_lshlrev_b32_e32 v66, 16, v67
	v_and_b32_e32 v67, 0xffff0000, v67
	v_pk_fma_f32 v[152:153], v[56:57], v[160:161], v[152:153]
	v_pk_fma_f32 v[156:157], v[58:59], v[64:65], v[156:157]
	v_pk_fma_f32 v[154:155], v[24:25], v[162:163], v[154:155]
	v_pk_fma_f32 v[158:159], v[26:27], v[66:67], v[158:159]
	global_load_dwordx4 v[24:27], v[150:151], off offset:16
	global_load_dwordx4 v[56:59], v[150:151], off
	v_lshl_add_u64 v[150:151], v[150:151], 0, s[0:1]
	s_waitcnt vmcnt(10)
	v_pk_fma_f32 v[82:83], v[38:39], v[64:65], v[82:83]
	v_pk_fma_f32 v[144:145], v[6:7], v[66:67], v[144:145]
	v_pk_fma_f32 v[72:73], v[34:35], v[64:65], v[72:73]
	v_pk_fma_f32 v[76:77], v[2:3], v[66:67], v[76:77]
	v_pk_fma_f32 v[146:147], v[62:63], v[64:65], v[146:147]
	v_pk_fma_f32 v[148:149], v[30:31], v[66:67], v[148:149]
	ds_read_b128 v[64:67], v134 offset:19456
	v_pk_fma_f32 v[68:69], v[36:37], v[160:161], v[68:69]
	v_pk_fma_f32 v[142:143], v[4:5], v[162:163], v[142:143]
	v_pk_fma_f32 v[70:71], v[32:33], v[160:161], v[70:71]
	v_pk_fma_f32 v[74:75], v[0:1], v[162:163], v[74:75]
	v_pk_fma_f32 v[78:79], v[60:61], v[160:161], v[78:79]
	v_pk_fma_f32 v[80:81], v[28:29], v[162:163], v[80:81]
	s_waitcnt lgkmcnt(0)
	v_lshlrev_b32_e32 v160, 16, v64
	v_and_b32_e32 v161, 0xffff0000, v64
	v_lshlrev_b32_e32 v64, 16, v65
	v_and_b32_e32 v65, 0xffff0000, v65
	v_lshlrev_b32_e32 v162, 16, v66
	v_and_b32_e32 v163, 0xffff0000, v66
	v_lshlrev_b32_e32 v66, 16, v67
	v_and_b32_e32 v67, 0xffff0000, v67
	v_pk_fma_f32 v[152:153], v[60:61], v[160:161], v[152:153]
	v_pk_fma_f32 v[156:157], v[62:63], v[64:65], v[156:157]
	v_pk_fma_f32 v[154:155], v[28:29], v[162:163], v[154:155]
	v_pk_fma_f32 v[158:159], v[30:31], v[66:67], v[158:159]
	global_load_dwordx4 v[28:31], v[150:151], off offset:16
	global_load_dwordx4 v[60:63], v[150:151], off
	v_lshl_add_u64 v[150:151], v[150:151], 0, s[0:1]
	s_waitcnt vmcnt(10)
	v_pk_fma_f32 v[82:83], v[42:43], v[64:65], v[82:83]
	v_pk_fma_f32 v[144:145], v[10:11], v[66:67], v[144:145]
	v_pk_fma_f32 v[72:73], v[38:39], v[64:65], v[72:73]
	v_pk_fma_f32 v[76:77], v[6:7], v[66:67], v[76:77]
	v_pk_fma_f32 v[146:147], v[34:35], v[64:65], v[146:147]
	v_pk_fma_f32 v[148:149], v[2:3], v[66:67], v[148:149]
	ds_read_b128 v[64:67], v134 offset:21504
	v_pk_fma_f32 v[68:69], v[40:41], v[160:161], v[68:69]
	v_pk_fma_f32 v[142:143], v[8:9], v[162:163], v[142:143]
	v_pk_fma_f32 v[70:71], v[36:37], v[160:161], v[70:71]
	v_pk_fma_f32 v[74:75], v[4:5], v[162:163], v[74:75]
	v_pk_fma_f32 v[78:79], v[32:33], v[160:161], v[78:79]
	v_pk_fma_f32 v[80:81], v[0:1], v[162:163], v[80:81]
	s_waitcnt lgkmcnt(0)
; #define LAS __attribute__((address_space(3)))
; __device__ __forceinline__ void conv_phase(LAS unsigned char* lds, const bf16_t* U, bf16_t* C, const float* wdw, const float* bdw, const float* lng, const float* lnb,
;                                            int first, int stride, int end, int tid, int wave, int lane) {
;     ...
;             for (int r = 0; r < TT / NWAVES + CW - 1; ++r) {
;                 if (r + 4 < CW) { wt[(r + 4) & 7][0] = wq[0]; wt[(r + 4) & 7][1] = wq[1]; wq += D / 4; asm volatile("" : "+v"(wq)); }
;                 const u32x4 xv = *(const LAS u32x4*)(lds + (4 * wave + r) * 2048 + p * 1024 + lane * 16);
;                 f32x2 x[4];
; #pragma unroll
;                 for (int i = 0; i < 4; ++i) x[i] = (f32x2){__uint_as_float(xv[i] << 16), __uint_as_float(xv[i] & 0xffff0000u)};
; #pragma unroll
;                 for (int j = 0; j < 4; ++j) { const int w = r - j;
;                     if (w >= 0 && w < CW) {
; #pragma unroll
;                         for (int c = 0; c < 4; ++c) { const f32x4 wv = wt[w & 7][c >> 1]; const f32x2 w2 = (c & 1) ? (f32x2){wv.z, wv.w} : (f32x2){wv.x, wv.y}; acc[p][j][c] = __builtin_elementwise_fma(w2, x[c], acc[p][j][c]); } } }
;                 asm volatile("" ::: "memory");
	v_lshlrev_b32_e32 v160, 16, v64
	v_and_b32_e32 v161, 0xffff0000, v64
	v_lshlrev_b32_e32 v64, 16, v65
	v_and_b32_e32 v65, 0xffff0000, v65
	v_lshlrev_b32_e32 v162, 16, v66
	v_and_b32_e32 v163, 0xffff0000, v66
	v_lshlrev_b32_e32 v66, 16, v67
	v_and_b32_e32 v67, 0xffff0000, v67
	v_pk_fma_f32 v[152:153], v[32:33], v[160:161], v[152:153]
	v_pk_fma_f32 v[156:157], v[34:35], v[64:65], v[156:157]
	v_pk_fma_f32 v[154:155], v[0:1], v[162:163], v[154:155]
	v_pk_fma_f32 v[158:159], v[2:3], v[66:67], v[158:159]
	global_load_dwordx4 v[0:3], v[150:151], off offset:16
	global_load_dwordx4 v[32:35], v[150:151], off
	v_lshl_add_u64 v[150:151], v[150:151], 0, s[0:1]
	s_waitcnt vmcnt(10)
	v_pk_fma_f32 v[82:83], v[46:47], v[64:65], v[82:83]
	v_pk_fma_f32 v[144:145], v[14:15], v[66:67], v[144:145]
	v_pk_fma_f32 v[72:73], v[42:43], v[64:65], v[72:73]
	v_pk_fma_f32 v[76:77], v[10:11], v[66:67], v[76:77]
	v_pk_fma_f32 v[146:147], v[38:39], v[64:65], v[146:147]
	v_pk_fma_f32 v[148:149], v[6:7], v[66:67], v[148:149]
	ds_read_b128 v[64:67], v134 offset:23552
	v_pk_fma_f32 v[68:69], v[44:45], v[160:161], v[68:69]
	v_pk_fma_f32 v[142:143], v[12:13], v[162:163], v[142:143]
	v_pk_fma_f32 v[70:71], v[40:41], v[160:161], v[70:71]
	v_pk_fma_f32 v[74:75], v[8:9], v[162:163], v[74:75]
	v_pk_fma_f32 v[78:79], v[36:37], v[160:161], v[78:79]
	v_pk_fma_f32 v[80:81], v[4:5], v[162:163], v[80:81]
	s_waitcnt lgkmcnt(0)
	v_lshlrev_b32_e32 v160, 16, v64
	v_and_b32_e32 v161, 0xffff0000, v64
	v_lshlrev_b32_e32 v64, 16, v65
	v_and_b32_e32 v65, 0xffff0000, v65
	v_lshlrev_b32_e32 v162, 16, v66
	v_and_b32_e32 v163, 0xffff0000, v66
	v_lshlrev_b32_e32 v66, 16, v67
	v_and_b32_e32 v67, 0xffff0000, v67
	v_pk_fma_f32 v[152:153], v[36:37], v[160:161], v[152:153]
	v_pk_fma_f32 v[156:157], v[38:39], v[64:65], v[156:157]
	v_pk_fma_f32 v[154:155], v[4:5], v[162:163], v[154:155]
	v_pk_fma_f32 v[158:159], v[6:7], v[66:67], v[158:159]
	global_load_dwordx4 v[4:7], v[150:151], off offset:16
	global_load_dwordx4 v[36:39], v[150:151], off
	v_lshl_add_u64 v[150:151], v[150:151], 0, s[0:1]
	s_waitcnt vmcnt(10)
	v_pk_fma_f32 v[82:83], v[50:51], v[64:65], v[82:83]
	v_pk_fma_f32 v[144:145], v[18:19], v[66:67], v[144:145]
	v_pk_fma_f32 v[72:73], v[46:47], v[64:65], v[72:73]
	v_pk_fma_f32 v[76:77], v[14:15], v[66:67], v[76:77]
	v_pk_fma_f32 v[146:147], v[42:43], v[64:65], v[146:147]
	v_pk_fma_f32 v[148:149], v[10:11], v[66:67], v[148:149]
	ds_read_b128 v[64:67], v134 offset:25600
	v_pk_fma_f32 v[68:69], v[48:49], v[160:161], v[68:69]
	v_pk_fma_f32 v[142:143], v[16:17], v[162:163], v[142:143]
	v_pk_fma_f32 v[70:71], v[44:45], v[160:161], v[70:71]
	v_pk_fma_f32 v[74:75], v[12:13], v[162:163], v[74:75]
	v_pk_fma_f32 v[78:79], v[40:41], v[160:161], v[78:79]
	v_pk_fma_f32 v[80:81], v[8:9], v[162:163], v[80:81]
	s_waitcnt lgkmcnt(0)
	v_lshlrev_b32_e32 v160, 16, v64
	v_and_b32_e32 v161, 0xffff0000, v64
	v_lshlrev_b32_e32 v64, 16, v65
	v_and_b32_e32 v65, 0xffff0000, v65
	v_lshlrev_b32_e32 v162, 16, v66
	v_and_b32_e32 v163, 0xffff0000, v66
	v_lshlrev_b32_e32 v66, 16, v67
	v_and_b32_e32 v67, 0xffff0000, v67
	v_pk_fma_f32 v[152:153], v[40:41], v[160:161], v[152:153]
	v_pk_fma_f32 v[156:157], v[42:43], v[64:65], v[156:157]
	v_pk_fma_f32 v[154:155], v[8:9], v[162:163], v[154:155]
	v_pk_fma_f32 v[158:159], v[10:11], v[66:67], v[158:159]
	global_load_dwordx4 v[8:11], v[150:151], off offset:16
	global_load_dwordx4 v[40:43], v[150:151], off
	v_lshl_add_u64 v[150:151], v[150:151], 0, s[0:1]
	s_waitcnt vmcnt(10)
	v_pk_fma_f32 v[82:83], v[54:55], v[64:65], v[82:83]
	v_pk_fma_f32 v[144:145], v[22:23], v[66:67], v[144:145]
	v_pk_fma_f32 v[72:73], v[50:51], v[64:65], v[72:73]
	v_pk_fma_f32 v[76:77], v[18:19], v[66:67], v[76:77]
	v_pk_fma_f32 v[146:147], v[46:47], v[64:65], v[146:147]
	v_pk_fma_f32 v[148:149], v[14:15], v[66:67], v[148:149]
	ds_read_b128 v[64:67], v134 offset:27648
	v_pk_fma_f32 v[68:69], v[52:53], v[160:161], v[68:69]
	v_pk_fma_f32 v[142:143], v[20:21], v[162:163], v[142:143]
	v_pk_fma_f32 v[70:71], v[48:49], v[160:161], v[70:71]
	v_pk_fma_f32 v[74:75], v[16:17], v[162:163], v[74:75]
	v_pk_fma_f32 v[78:79], v[44:45], v[160:161], v[78:79]
	v_pk_fma_f32 v[80:81], v[12:13], v[162:163], v[80:81]
	s_waitcnt lgkmcnt(0)
	v_lshlrev_b32_e32 v160, 16, v64
	v_and_b32_e32 v161, 0xffff0000, v64
	v_lshlrev_b32_e32 v64, 16, v65
	v_and_b32_e32 v65, 0xffff0000, v65
	v_lshlrev_b32_e32 v162, 16, v66
	v_and_b32_e32 v163, 0xffff0000, v66
	v_lshlrev_b32_e32 v66, 16, v67
	v_and_b32_e32 v67, 0xffff0000, v67
	v_pk_fma_f32 v[152:153], v[44:45], v[160:161], v[152:153]
	v_pk_fma_f32 v[156:157], v[46:47], v[64:65], v[156:157]
	v_pk_fma_f32 v[154:155], v[12:13], v[162:163], v[154:155]
	v_pk_fma_f32 v[158:159], v[14:15], v[66:67], v[158:159]
	global_load_dwordx4 v[12:15], v[150:151], off offset:16
	global_load_dwordx4 v[44:47], v[150:151], off
	v_lshl_add_u64 v[150:151], v[150:151], 0, s[0:1]
	s_waitcnt vmcnt(10)
	v_pk_fma_f32 v[82:83], v[58:59], v[64:65], v[82:83]
	v_pk_fma_f32 v[144:145], v[26:27], v[66:67], v[144:145]
	v_pk_fma_f32 v[72:73], v[54:55], v[64:65], v[72:73]
	v_pk_fma_f32 v[76:77], v[22:23], v[66:67], v[76:77]
	v_pk_fma_f32 v[146:147], v[50:51], v[64:65], v[146:147]
	v_pk_fma_f32 v[148:149], v[18:19], v[66:67], v[148:149]
	ds_read_b128 v[64:67], v134 offset:29696
	v_pk_fma_f32 v[68:69], v[56:57], v[160:161], v[68:69]
	v_pk_fma_f32 v[142:143], v[24:25], v[162:163], v[142:143]
	v_pk_fma_f32 v[70:71], v[52:53], v[160:161], v[70:71]
	v_pk_fma_f32 v[74:75], v[20:21], v[162:163], v[74:75]
	v_pk_fma_f32 v[78:79], v[48:49], v[160:161], v[78:79]
	v_pk_fma_f32 v[80:81], v[16:17], v[162:163], v[80:81]
	s_waitcnt lgkmcnt(0)
; #define LAS __attribute__((address_space(3)))
; __device__ __forceinline__ void conv_phase(LAS unsigned char* lds, const bf16_t* U, bf16_t* C, const float* wdw, const float* bdw, const float* lng, const float* lnb,
;                                            int first, int stride, int end, int tid, int wave, int lane) {
;     ...
;             for (int r = 0; r < TT / NWAVES + CW - 1; ++r) {
;                 if (r + 4 < CW) { wt[(r + 4) & 7][0] = wq[0]; wt[(r + 4) & 7][1] = wq[1]; wq += D / 4; asm volatile("" : "+v"(wq)); }
;                 const u32x4 xv = *(const LAS u32x4*)(lds + (4 * wave + r) * 2048 + p * 1024 + lane * 16);
;                 f32x2 x[4];
; #pragma unroll
;                 for (int i = 0; i < 4; ++i) x[i] = (f32x2){__uint_as_float(xv[i] << 16), __uint_as_float(xv[i] & 0xffff0000u)};
; #pragma unroll
;                 for (int j = 0; j < 4; ++j) { const int w = r - j;
;                     if (w >= 0 && w < CW) {
; #pragma unroll
;                         for (int c = 0; c < 4; ++c) { const f32x4 wv = wt[w & 7][c >> 1]; const f32x2 w2 = (c & 1) ? (f32x2){wv.z, wv.w} : (f32x2){wv.x, wv.y}; acc[p][j][c] = __builtin_elementwise_fma(w2, x[c], acc[p][j][c]); } } }
;                 asm volatile("" ::: "memory");
	v_lshlrev_b32_e32 v160, 16, v64
	v_and_b32_e32 v161, 0xffff0000, v64
	v_lshlrev_b32_e32 v64, 16, v65
	v_and_b32_e32 v65, 0xffff0000, v65
	v_lshlrev_b32_e32 v162, 16, v66
	v_and_b32_e32 v163, 0xffff0000, v66
	v_lshlrev_b32_e32 v66, 16, v67
	v_and_b32_e32 v67, 0xffff0000, v67
	v_pk_fma_f32 v[152:153], v[48:49], v[160:161], v[152:153]
	v_pk_fma_f32 v[156:157], v[50:51], v[64:65], v[156:157]
	v_pk_fma_f32 v[154:155], v[16:17], v[162:163], v[154:155]
	v_pk_fma_f32 v[158:159], v[18:19], v[66:67], v[158:159]
	global_load_dwordx4 v[16:19], v[150:151], off offset:16
	global_load_dwordx4 v[48:51], v[150:151], off
	v_lshl_add_u64 v[150:151], v[150:151], 0, s[0:1]
	s_waitcnt vmcnt(10)
	v_pk_fma_f32 v[82:83], v[62:63], v[64:65], v[82:83]
	v_pk_fma_f32 v[144:145], v[30:31], v[66:67], v[144:145]
	v_pk_fma_f32 v[72:73], v[58:59], v[64:65], v[72:73]
	v_pk_fma_f32 v[76:77], v[26:27], v[66:67], v[76:77]
	v_pk_fma_f32 v[146:147], v[54:55], v[64:65], v[146:147]
	v_pk_fma_f32 v[148:149], v[22:23], v[66:67], v[148:149]
	ds_read_b128 v[64:67], v134 offset:31744
	v_pk_fma_f32 v[68:69], v[60:61], v[160:161], v[68:69]
	v_pk_fma_f32 v[142:143], v[28:29], v[162:163], v[142:143]
	v_pk_fma_f32 v[70:71], v[56:57], v[160:161], v[70:71]
	v_pk_fma_f32 v[74:75], v[24:25], v[162:163], v[74:75]
	v_pk_fma_f32 v[78:79], v[52:53], v[160:161], v[78:79]
	v_pk_fma_f32 v[80:81], v[20:21], v[162:163], v[80:81]
	s_waitcnt lgkmcnt(0)
	v_lshlrev_b32_e32 v160, 16, v64
	v_and_b32_e32 v161, 0xffff0000, v64
	v_lshlrev_b32_e32 v64, 16, v65
	v_and_b32_e32 v65, 0xffff0000, v65
	v_lshlrev_b32_e32 v162, 16, v66
	v_and_b32_e32 v163, 0xffff0000, v66
	v_lshlrev_b32_e32 v66, 16, v67
	v_and_b32_e32 v67, 0xffff0000, v67
	v_pk_fma_f32 v[152:153], v[52:53], v[160:161], v[152:153]
	v_pk_fma_f32 v[156:157], v[54:55], v[64:65], v[156:157]
	v_pk_fma_f32 v[154:155], v[20:21], v[162:163], v[154:155]
	v_pk_fma_f32 v[158:159], v[22:23], v[66:67], v[158:159]
	global_load_dwordx4 v[20:23], v[150:151], off offset:16
	global_load_dwordx4 v[52:55], v[150:151], off
	v_lshl_add_u64 v[150:151], v[150:151], 0, s[0:1]
	s_waitcnt vmcnt(10)
	v_pk_fma_f32 v[82:83], v[34:35], v[64:65], v[82:83]
	v_pk_fma_f32 v[144:145], v[2:3], v[66:67], v[144:145]
	v_pk_fma_f32 v[72:73], v[62:63], v[64:65], v[72:73]
	v_pk_fma_f32 v[76:77], v[30:31], v[66:67], v[76:77]
	v_pk_fma_f32 v[146:147], v[58:59], v[64:65], v[146:147]
	v_pk_fma_f32 v[148:149], v[26:27], v[66:67], v[148:149]
	ds_read_b128 v[64:67], v134 offset:33792
	v_pk_fma_f32 v[68:69], v[32:33], v[160:161], v[68:69]
	v_pk_fma_f32 v[142:143], v[0:1], v[162:163], v[142:143]
	v_pk_fma_f32 v[70:71], v[60:61], v[160:161], v[70:71]
	v_pk_fma_f32 v[74:75], v[28:29], v[162:163], v[74:75]
	v_pk_fma_f32 v[78:79], v[56:57], v[160:161], v[78:79]
	v_pk_fma_f32 v[80:81], v[24:25], v[162:163], v[80:81]
	s_waitcnt lgkmcnt(0)
	v_lshlrev_b32_e32 v160, 16, v64
	v_and_b32_e32 v161, 0xffff0000, v64
	v_lshlrev_b32_e32 v64, 16, v65
	v_and_b32_e32 v65, 0xffff0000, v65
	v_lshlrev_b32_e32 v162, 16, v66
	v_and_b32_e32 v163, 0xffff0000, v66
	v_lshlrev_b32_e32 v66, 16, v67
	v_and_b32_e32 v67, 0xffff0000, v67
	v_pk_fma_f32 v[152:153], v[56:57], v[160:161], v[152:153]
	v_pk_fma_f32 v[156:157], v[58:59], v[64:65], v[156:157]
	v_pk_fma_f32 v[154:155], v[24:25], v[162:163], v[154:155]
	v_pk_fma_f32 v[158:159], v[26:27], v[66:67], v[158:159]
	global_load_dwordx4 v[24:27], v[150:151], off offset:16
	global_load_dwordx4 v[56:59], v[150:151], off
	v_lshl_add_u64 v[150:151], v[150:151], 0, s[0:1]
	s_waitcnt vmcnt(10)
	v_pk_fma_f32 v[82:83], v[38:39], v[64:65], v[82:83]
	v_pk_fma_f32 v[144:145], v[6:7], v[66:67], v[144:145]
	v_pk_fma_f32 v[72:73], v[34:35], v[64:65], v[72:73]
	v_pk_fma_f32 v[76:77], v[2:3], v[66:67], v[76:77]
	v_pk_fma_f32 v[146:147], v[62:63], v[64:65], v[146:147]
	v_pk_fma_f32 v[148:149], v[30:31], v[66:67], v[148:149]
	ds_read_b128 v[64:67], v134 offset:35840
	v_pk_fma_f32 v[68:69], v[36:37], v[160:161], v[68:69]
	v_pk_fma_f32 v[142:143], v[4:5], v[162:163], v[142:143]
	v_pk_fma_f32 v[70:71], v[32:33], v[160:161], v[70:71]
	v_pk_fma_f32 v[74:75], v[0:1], v[162:163], v[74:75]
	v_pk_fma_f32 v[78:79], v[60:61], v[160:161], v[78:79]
	v_pk_fma_f32 v[80:81], v[28:29], v[162:163], v[80:81]
	s_waitcnt lgkmcnt(0)
	v_lshlrev_b32_e32 v160, 16, v64
	v_and_b32_e32 v161, 0xffff0000, v64
	v_lshlrev_b32_e32 v64, 16, v65
	v_and_b32_e32 v65, 0xffff0000, v65
	v_lshlrev_b32_e32 v162, 16, v66
	v_and_b32_e32 v163, 0xffff0000, v66
	v_lshlrev_b32_e32 v66, 16, v67
	v_and_b32_e32 v67, 0xffff0000, v67
	v_pk_fma_f32 v[152:153], v[60:61], v[160:161], v[152:153]
	v_pk_fma_f32 v[156:157], v[62:63], v[64:65], v[156:157]
	v_pk_fma_f32 v[154:155], v[28:29], v[162:163], v[154:155]
	v_pk_fma_f32 v[158:159], v[30:31], v[66:67], v[158:159]
	global_load_dwordx4 v[28:31], v[150:151], off offset:16
	global_load_dwordx4 v[60:63], v[150:151], off
	v_lshl_add_u64 v[150:151], v[150:151], 0, s[0:1]
	s_waitcnt vmcnt(10)
	v_pk_fma_f32 v[82:83], v[42:43], v[64:65], v[82:83]
	v_pk_fma_f32 v[144:145], v[10:11], v[66:67], v[144:145]
	v_pk_fma_f32 v[72:73], v[38:39], v[64:65], v[72:73]
	v_pk_fma_f32 v[76:77], v[6:7], v[66:67], v[76:77]
	v_pk_fma_f32 v[146:147], v[34:35], v[64:65], v[146:147]
	v_pk_fma_f32 v[148:149], v[2:3], v[66:67], v[148:149]
	ds_read_b128 v[64:67], v134 offset:37888
	v_pk_fma_f32 v[68:69], v[40:41], v[160:161], v[68:69]
	v_pk_fma_f32 v[142:143], v[8:9], v[162:163], v[142:143]
	v_pk_fma_f32 v[70:71], v[36:37], v[160:161], v[70:71]
	v_pk_fma_f32 v[74:75], v[4:5], v[162:163], v[74:75]
	v_pk_fma_f32 v[78:79], v[32:33], v[160:161], v[78:79]
	v_pk_fma_f32 v[80:81], v[0:1], v[162:163], v[80:81]
	s_waitcnt lgkmcnt(0)
; #define LAS __attribute__((address_space(3)))
; __device__ __forceinline__ void conv_phase(LAS unsigned char* lds, const bf16_t* U, bf16_t* C, const float* wdw, const float* bdw, const float* lng, const float* lnb,
;                                            int first, int stride, int end, int tid, int wave, int lane) {
;     ...
;             for (int r = 0; r < TT / NWAVES + CW - 1; ++r) {
;                 if (r + 4 < CW) { wt[(r + 4) & 7][0] = wq[0]; wt[(r + 4) & 7][1] = wq[1]; wq += D / 4; asm volatile("" : "+v"(wq)); }
;                 const u32x4 xv = *(const LAS u32x4*)(lds + (4 * wave + r) * 2048 + p * 1024 + lane * 16);
;                 f32x2 x[4];
; #pragma unroll
;                 for (int i = 0; i < 4; ++i) x[i] = (f32x2){__uint_as_float(xv[i] << 16), __uint_as_float(xv[i] & 0xffff0000u)};
; #pragma unroll
;                 for (int j = 0; j < 4; ++j) { const int w = r - j;
;                     if (w >= 0 && w < CW) {
; #pragma unroll
;                         for (int c = 0; c < 4; ++c) { const f32x4 wv = wt[w & 7][c >> 1]; const f32x2 w2 = (c & 1) ? (f32x2){wv.z, wv.w} : (f32x2){wv.x, wv.y}; acc[p][j][c] = __builtin_elementwise_fma(w2, x[c], acc[p][j][c]); } } }
;                 asm volatile("" ::: "memory");
	v_lshlrev_b32_e32 v160, 16, v64
	v_and_b32_e32 v161, 0xffff0000, v64
	v_lshlrev_b32_e32 v64, 16, v65
	v_and_b32_e32 v65, 0xffff0000, v65
	v_lshlrev_b32_e32 v162, 16, v66
	v_and_b32_e32 v163, 0xffff0000, v66
	v_lshlrev_b32_e32 v66, 16, v67
	v_and_b32_e32 v67, 0xffff0000, v67
	s_waitcnt vmcnt(8)
	v_pk_fma_f32 v[82:83], v[46:47], v[64:65], v[82:83]
	v_pk_fma_f32 v[144:145], v[14:15], v[66:67], v[144:145]
	v_pk_fma_f32 v[72:73], v[42:43], v[64:65], v[72:73]
	v_pk_fma_f32 v[76:77], v[10:11], v[66:67], v[76:77]
	v_pk_fma_f32 v[146:147], v[38:39], v[64:65], v[146:147]
	v_pk_fma_f32 v[148:149], v[6:7], v[66:67], v[148:149]
	v_pk_fma_f32 v[152:153], v[32:33], v[160:161], v[152:153]
	v_pk_fma_f32 v[156:157], v[34:35], v[64:65], v[156:157]
	v_pk_fma_f32 v[158:159], v[2:3], v[66:67], v[158:159]
	global_load_dwordx4 v[32:35], v[150:151], off offset:16
	global_load_dwordx4 v[64:67], v[150:151], off
	v_lshl_add_u64 v[150:151], v[150:151], 0, s[0:1]
	v_pk_fma_f32 v[154:155], v[0:1], v[162:163], v[154:155]
	ds_read_b128 v[0:3], v134 offset:39936
	v_pk_fma_f32 v[68:69], v[44:45], v[160:161], v[68:69]
	v_pk_fma_f32 v[70:71], v[40:41], v[160:161], v[70:71]
	v_pk_fma_f32 v[78:79], v[36:37], v[160:161], v[78:79]
	s_waitcnt lgkmcnt(0)
	v_lshlrev_b32_e32 v160, 16, v0
	v_and_b32_e32 v161, 0xffff0000, v0
	v_lshlrev_b32_e32 v0, 16, v1
	v_and_b32_e32 v1, 0xffff0000, v1
	v_pk_fma_f32 v[142:143], v[12:13], v[162:163], v[142:143]
	v_pk_fma_f32 v[74:75], v[8:9], v[162:163], v[74:75]
	v_pk_fma_f32 v[80:81], v[4:5], v[162:163], v[80:81]
	v_lshlrev_b32_e32 v162, 16, v2
	v_and_b32_e32 v163, 0xffff0000, v2
	v_lshlrev_b32_e32 v2, 16, v3
	v_and_b32_e32 v3, 0xffff0000, v3
	s_waitcnt vmcnt(8)
	v_pk_fma_f32 v[164:165], v[48:49], v[160:161], v[68:69]
	v_pk_fma_f32 v[166:167], v[44:45], v[160:161], v[70:71]
	v_pk_fma_f32 v[152:153], v[36:37], v[160:161], v[152:153]
	v_pk_fma_f32 v[156:157], v[38:39], v[0:1], v[156:157]
	global_load_dwordx4 v[36:39], v[150:151], off offset:16
	global_load_dwordx4 v[68:71], v[150:151], off
	v_lshl_add_u64 v[150:151], v[150:151], 0, s[0:1]
	v_pk_fma_f32 v[82:83], v[50:51], v[0:1], v[82:83]
	v_pk_fma_f32 v[144:145], v[18:19], v[2:3], v[144:145]
	v_pk_fma_f32 v[72:73], v[46:47], v[0:1], v[72:73]
	v_pk_fma_f32 v[76:77], v[14:15], v[2:3], v[76:77]
	v_pk_fma_f32 v[146:147], v[42:43], v[0:1], v[146:147]
	v_pk_fma_f32 v[148:149], v[10:11], v[2:3], v[148:149]
	v_pk_fma_f32 v[6:7], v[6:7], v[2:3], v[158:159]
	ds_read_b128 v[0:3], v134 offset:41984
	v_pk_fma_f32 v[74:75], v[12:13], v[162:163], v[74:75]
	v_pk_fma_f32 v[78:79], v[40:41], v[160:161], v[78:79]
	v_pk_fma_f32 v[4:5], v[4:5], v[162:163], v[154:155]
	s_waitcnt lgkmcnt(0)
	v_lshlrev_b32_e32 v154, 16, v0
	v_and_b32_e32 v155, 0xffff0000, v0
	v_lshlrev_b32_e32 v0, 16, v1
	v_and_b32_e32 v1, 0xffff0000, v1
	v_lshlrev_b32_e32 v158, 16, v2
	v_and_b32_e32 v159, 0xffff0000, v2
	v_pk_fma_f32 v[142:143], v[16:17], v[162:163], v[142:143]
	v_pk_fma_f32 v[80:81], v[8:9], v[162:163], v[80:81]
	s_waitcnt vmcnt(8)
	v_pk_fma_f32 v[160:161], v[52:53], v[154:155], v[164:165]
	v_pk_fma_f32 v[162:163], v[48:49], v[154:155], v[166:167]
	v_pk_fma_f32 v[164:165], v[50:51], v[0:1], v[72:73]
	v_pk_fma_f32 v[166:167], v[16:17], v[158:159], v[74:75]
	v_pk_fma_f32 v[78:79], v[44:45], v[154:155], v[78:79]
	v_pk_fma_f32 v[152:153], v[40:41], v[154:155], v[152:153]
	v_pk_fma_f32 v[154:155], v[42:43], v[0:1], v[156:157]
	global_load_dwordx4 v[40:43], v[150:151], off offset:16
	global_load_dwordx4 v[72:75], v[150:151], off
	v_lshlrev_b32_e32 v2, 16, v3
	v_and_b32_e32 v3, 0xffff0000, v3
	v_pk_fma_f32 v[4:5], v[8:9], v[158:159], v[4:5]
	v_lshl_add_u64 v[8:9], v[150:151], 0, s[0:1]
	v_pk_fma_f32 v[82:83], v[54:55], v[0:1], v[82:83]
	v_pk_fma_f32 v[144:145], v[22:23], v[2:3], v[144:145]
	v_pk_fma_f32 v[76:77], v[18:19], v[2:3], v[76:77]
	v_pk_fma_f32 v[146:147], v[46:47], v[0:1], v[146:147]
	v_pk_fma_f32 v[148:149], v[14:15], v[2:3], v[148:149]
	v_pk_fma_f32 v[6:7], v[10:11], v[2:3], v[6:7]
	ds_read_b128 v[0:3], v134 offset:44032
	v_pk_fma_f32 v[142:143], v[20:21], v[158:159], v[142:143]
	v_pk_fma_f32 v[80:81], v[12:13], v[158:159], v[80:81]
	s_waitcnt lgkmcnt(0)
	v_lshlrev_b32_e32 v10, 16, v0
	v_and_b32_e32 v11, 0xffff0000, v0
	v_lshlrev_b32_e32 v0, 16, v1
	v_and_b32_e32 v1, 0xffff0000, v1
	v_lshlrev_b32_e32 v150, 16, v2
	v_and_b32_e32 v151, 0xffff0000, v2
	v_lshlrev_b32_e32 v2, 16, v3
	v_and_b32_e32 v3, 0xffff0000, v3
	s_waitcnt vmcnt(8)
	v_pk_fma_f32 v[156:157], v[56:57], v[10:11], v[160:161]
	v_pk_fma_f32 v[158:159], v[52:53], v[10:11], v[162:163]
	v_pk_fma_f32 v[160:161], v[54:55], v[0:1], v[164:165]
	v_pk_fma_f32 v[162:163], v[20:21], v[150:151], v[166:167]
	v_pk_fma_f32 v[164:165], v[22:23], v[2:3], v[76:77]
	v_pk_fma_f32 v[166:167], v[48:49], v[10:11], v[78:79]
	v_pk_fma_f32 v[10:11], v[44:45], v[10:11], v[152:153]
	v_pk_fma_f32 v[152:153], v[46:47], v[0:1], v[154:155]
	global_load_dwordx4 v[44:47], v[8:9], off offset:16
	global_load_dwordx4 v[76:79], v[8:9], off
	v_lshl_add_u64 v[8:9], v[8:9], 0, s[0:1]
	v_pk_fma_f32 v[82:83], v[58:59], v[0:1], v[82:83]
	v_pk_fma_f32 v[144:145], v[26:27], v[2:3], v[144:145]
	v_pk_fma_f32 v[146:147], v[50:51], v[0:1], v[146:147]
	v_pk_fma_f32 v[148:149], v[18:19], v[2:3], v[148:149]
	v_pk_fma_f32 v[6:7], v[14:15], v[2:3], v[6:7]
	ds_read_b128 v[0:3], v134 offset:46080
	v_pk_fma_f32 v[80:81], v[16:17], v[150:151], v[80:81]
	v_pk_fma_f32 v[4:5], v[12:13], v[150:151], v[4:5]
	v_pk_fma_f32 v[142:143], v[24:25], v[150:151], v[142:143]
	s_waitcnt lgkmcnt(0)
	v_lshlrev_b32_e32 v12, 16, v0
	v_and_b32_e32 v13, 0xffff0000, v0
	v_lshlrev_b32_e32 v0, 16, v1
	v_and_b32_e32 v1, 0xffff0000, v1
	v_lshlrev_b32_e32 v14, 16, v2
	v_and_b32_e32 v15, 0xffff0000, v2
	v_lshlrev_b32_e32 v2, 16, v3
	v_and_b32_e32 v3, 0xffff0000, v3
	s_waitcnt vmcnt(8)
; #define LAS __attribute__((address_space(3)))
; __device__ __forceinline__ void conv_phase(LAS unsigned char* lds, const bf16_t* U, bf16_t* C, const float* wdw, const float* bdw, const float* lng, const float* lnb,
;                                            int first, int stride, int end, int tid, int wave, int lane) {
;     ...
;             for (int r = 0; r < TT / NWAVES + CW - 1; ++r) {
;                 if (r + 4 < CW) { wt[(r + 4) & 7][0] = wq[0]; wt[(r + 4) & 7][1] = wq[1]; wq += D / 4; asm volatile("" : "+v"(wq)); }
;                 const u32x4 xv = *(const LAS u32x4*)(lds + (4 * wave + r) * 2048 + p * 1024 + lane * 16);
;                 f32x2 x[4];
; #pragma unroll
;                 for (int i = 0; i < 4; ++i) x[i] = (f32x2){__uint_as_float(xv[i] << 16), __uint_as_float(xv[i] & 0xffff0000u)};
; #pragma unroll
;                 for (int j = 0; j < 4; ++j) { const int w = r - j;
;                     if (w >= 0 && w < CW) {
; #pragma unroll
;                         for (int c = 0; c < 4; ++c) { const f32x4 wv = wt[w & 7][c >> 1]; const f32x2 w2 = (c & 1) ? (f32x2){wv.z, wv.w} : (f32x2){wv.x, wv.y}; acc[p][j][c] = __builtin_elementwise_fma(w2, x[c], acc[p][j][c]); } } }
;                 asm volatile("" ::: "memory");
	v_pk_fma_f32 v[150:151], v[60:61], v[12:13], v[156:157]
	v_pk_fma_f32 v[154:155], v[62:63], v[0:1], v[82:83]
	v_pk_fma_f32 v[156:157], v[56:57], v[12:13], v[158:159]
	v_pk_fma_f32 v[158:159], v[58:59], v[0:1], v[160:161]
	v_pk_fma_f32 v[160:161], v[24:25], v[14:15], v[162:163]
	v_pk_fma_f32 v[162:163], v[26:27], v[2:3], v[164:165]
	v_pk_fma_f32 v[164:165], v[52:53], v[12:13], v[166:167]
	v_pk_fma_f32 v[166:167], v[20:21], v[14:15], v[80:81]
	v_pk_fma_f32 v[10:11], v[48:49], v[12:13], v[10:11]
	v_pk_fma_f32 v[12:13], v[50:51], v[0:1], v[152:153]
	global_load_dwordx4 v[48:51], v[8:9], off offset:16
	global_load_dwordx4 v[80:83], v[8:9], off
	v_lshl_add_u64 v[8:9], v[8:9], 0, s[0:1]
	v_pk_fma_f32 v[144:145], v[30:31], v[2:3], v[144:145]
	v_pk_fma_f32 v[146:147], v[54:55], v[0:1], v[146:147]
	v_pk_fma_f32 v[148:149], v[22:23], v[2:3], v[148:149]
	v_pk_fma_f32 v[6:7], v[18:19], v[2:3], v[6:7]
	ds_read_b128 v[0:3], v134 offset:48128
	v_pk_fma_f32 v[142:143], v[28:29], v[14:15], v[142:143]
	v_pk_fma_f32 v[4:5], v[16:17], v[14:15], v[4:5]
	s_waitcnt lgkmcnt(0)
	v_lshlrev_b32_e32 v14, 16, v0
	v_and_b32_e32 v15, 0xffff0000, v0
	v_lshlrev_b32_e32 v0, 16, v1
	v_and_b32_e32 v1, 0xffff0000, v1
	v_lshlrev_b32_e32 v16, 16, v2
	v_and_b32_e32 v17, 0xffff0000, v2
	v_lshlrev_b32_e32 v2, 16, v3
	v_and_b32_e32 v3, 0xffff0000, v3
	v_pk_fma_f32 v[10:11], v[52:53], v[14:15], v[10:11]
	v_lshl_add_u64 v[52:53], v[8:9], 0, s[0:1]
	s_waitcnt vmcnt(8)
	v_pk_fma_f32 v[152:153], v[66:67], v[0:1], v[154:155]
	v_pk_fma_f32 v[142:143], v[32:33], v[16:17], v[142:143]
	v_pk_fma_f32 v[144:145], v[34:35], v[2:3], v[144:145]
	v_pk_fma_f32 v[154:155], v[60:61], v[14:15], v[156:157]
	v_pk_fma_f32 v[156:157], v[62:63], v[0:1], v[158:159]
	v_pk_fma_f32 v[158:159], v[28:29], v[16:17], v[160:161]
	v_pk_fma_f32 v[160:161], v[30:31], v[2:3], v[162:163]
	v_pk_fma_f32 v[162:163], v[56:57], v[14:15], v[164:165]
	v_pk_fma_f32 v[146:147], v[58:59], v[0:1], v[146:147]
	v_pk_fma_f32 v[164:165], v[24:25], v[16:17], v[166:167]
	v_pk_fma_f32 v[148:149], v[26:27], v[2:3], v[148:149]
	v_pk_fma_f32 v[12:13], v[54:55], v[0:1], v[12:13]
	v_pk_fma_f32 v[4:5], v[20:21], v[16:17], v[4:5]
	v_pk_fma_f32 v[6:7], v[22:23], v[2:3], v[6:7]
	global_load_dwordx4 v[16:19], v[8:9], off offset:16
	global_load_dwordx4 v[20:23], v[8:9], off
	ds_read_b128 v[0:3], v134 offset:50176
	v_pk_fma_f32 v[150:151], v[64:65], v[14:15], v[150:151]
	s_waitcnt lgkmcnt(0)
	v_lshlrev_b32_e32 v14, 16, v2
	v_and_b32_e32 v15, 0xffff0000, v2
	v_lshlrev_b32_e32 v8, 16, v0
	v_and_b32_e32 v9, 0xffff0000, v0
	v_lshlrev_b32_e32 v0, 16, v1
	v_and_b32_e32 v1, 0xffff0000, v1
	v_lshlrev_b32_e32 v2, 16, v3
	v_and_b32_e32 v3, 0xffff0000, v3
	v_pk_fma_f32 v[4:5], v[24:25], v[14:15], v[4:5]
	v_lshl_add_u64 v[24:25], v[52:53], 0, s[0:1]
	s_waitcnt vmcnt(8)
	v_pk_fma_f32 v[54:55], v[68:69], v[8:9], v[150:151]
	v_pk_fma_f32 v[150:151], v[70:71], v[0:1], v[152:153]
	v_pk_fma_f32 v[142:143], v[36:37], v[14:15], v[142:143]
	v_pk_fma_f32 v[144:145], v[38:39], v[2:3], v[144:145]
	v_pk_fma_f32 v[152:153], v[64:65], v[8:9], v[154:155]
	v_pk_fma_f32 v[154:155], v[66:67], v[0:1], v[156:157]
	v_pk_fma_f32 v[156:157], v[32:33], v[14:15], v[158:159]
	v_pk_fma_f32 v[158:159], v[34:35], v[2:3], v[160:161]
	v_pk_fma_f32 v[160:161], v[60:61], v[8:9], v[162:163]
	v_pk_fma_f32 v[146:147], v[62:63], v[0:1], v[146:147]
	v_pk_fma_f32 v[162:163], v[28:29], v[14:15], v[164:165]
	v_pk_fma_f32 v[148:149], v[30:31], v[2:3], v[148:149]
	v_pk_fma_f32 v[56:57], v[56:57], v[8:9], v[10:11]
	v_pk_fma_f32 v[58:59], v[58:59], v[0:1], v[12:13]
	v_pk_fma_f32 v[6:7], v[26:27], v[2:3], v[6:7]
	global_load_dwordx4 v[8:11], v[52:53], off offset:16
	global_load_dwordx4 v[12:15], v[52:53], off
	ds_read_b128 v[0:3], v134 offset:52224
	s_waitcnt lgkmcnt(0)
	v_lshlrev_b32_e32 v26, 16, v0
	v_and_b32_e32 v27, 0xffff0000, v0
	v_lshlrev_b32_e32 v0, 16, v1
	v_and_b32_e32 v1, 0xffff0000, v1
	v_lshlrev_b32_e32 v52, 16, v2
	v_and_b32_e32 v53, 0xffff0000, v2
	v_lshlrev_b32_e32 v2, 16, v3
	v_and_b32_e32 v3, 0xffff0000, v3
	s_waitcnt vmcnt(8)
	v_pk_fma_f32 v[150:151], v[74:75], v[0:1], v[150:151]
	v_pk_fma_f32 v[144:145], v[42:43], v[2:3], v[144:145]
	v_pk_fma_f32 v[154:155], v[70:71], v[0:1], v[154:155]
	v_pk_fma_f32 v[158:159], v[38:39], v[2:3], v[158:159]
	v_pk_fma_f32 v[146:147], v[66:67], v[0:1], v[146:147]
	v_pk_fma_f32 v[148:149], v[34:35], v[2:3], v[148:149]
	v_pk_fma_f32 v[58:59], v[62:63], v[0:1], v[58:59]
	v_pk_fma_f32 v[28:29], v[28:29], v[52:53], v[4:5]
	v_pk_fma_f32 v[30:31], v[30:31], v[2:3], v[6:7]
	global_load_dwordx4 v[4:7], v[24:25], off offset:16
	global_load_dwordx4 v[0:3], v[24:25], off
	v_lshl_add_u64 v[24:25], v[24:25], 0, s[0:1]
	v_pk_fma_f32 v[54:55], v[72:73], v[26:27], v[54:55]
	v_pk_fma_f32 v[152:153], v[68:69], v[26:27], v[152:153]
	v_pk_fma_f32 v[160:161], v[64:65], v[26:27], v[160:161]
	v_pk_fma_f32 v[56:57], v[60:61], v[26:27], v[56:57]
	ds_read_b128 v[24:27], v134 offset:54272
	v_pk_fma_f32 v[142:143], v[40:41], v[52:53], v[142:143]
	v_pk_fma_f32 v[156:157], v[36:37], v[52:53], v[156:157]
	v_pk_fma_f32 v[162:163], v[32:33], v[52:53], v[162:163]
	s_waitcnt lgkmcnt(0)
	v_lshlrev_b32_e32 v52, 16, v24
	v_and_b32_e32 v53, 0xffff0000, v24
	v_lshlrev_b32_e32 v24, 16, v25
	v_and_b32_e32 v25, 0xffff0000, v25
	v_lshlrev_b32_e32 v60, 16, v26
	v_and_b32_e32 v61, 0xffff0000, v26
	v_lshlrev_b32_e32 v26, 16, v27
	v_and_b32_e32 v27, 0xffff0000, v27
	s_waitcnt vmcnt(8)
; #define LAS __attribute__((address_space(3)))
; __device__ __forceinline__ void conv_phase(LAS unsigned char* lds, const bf16_t* U, bf16_t* C, const float* wdw, const float* bdw, const float* lng, const float* lnb,
;                                            int first, int stride, int end, int tid, int wave, int lane) {
;     ...
;             for (int r = 0; r < TT / NWAVES + CW - 1; ++r) {
;                 if (r + 4 < CW) { wt[(r + 4) & 7][0] = wq[0]; wt[(r + 4) & 7][1] = wq[1]; wq += D / 4; asm volatile("" : "+v"(wq)); }
;                 const u32x4 xv = *(const LAS u32x4*)(lds + (4 * wave + r) * 2048 + p * 1024 + lane * 16);
;                 f32x2 x[4];
; #pragma unroll
;                 for (int i = 0; i < 4; ++i) x[i] = (f32x2){__uint_as_float(xv[i] << 16), __uint_as_float(xv[i] & 0xffff0000u)};
; #pragma unroll
;                 for (int j = 0; j < 4; ++j) { const int w = r - j;
;                     if (w >= 0 && w < CW) {
; #pragma unroll
;                         for (int c = 0; c < 4; ++c) { const f32x4 wv = wt[w & 7][c >> 1]; const f32x2 w2 = (c & 1) ? (f32x2){wv.z, wv.w} : (f32x2){wv.x, wv.y}; acc[p][j][c] = __builtin_elementwise_fma(w2, x[c], acc[p][j][c]); } } }
;                 asm volatile("" ::: "memory");
	v_pk_fma_f32 v[54:55], v[76:77], v[52:53], v[54:55]
	v_pk_fma_f32 v[62:63], v[78:79], v[24:25], v[150:151]
	v_pk_fma_f32 v[144:145], v[46:47], v[26:27], v[144:145]
	v_pk_fma_f32 v[150:151], v[72:73], v[52:53], v[152:153]
	v_pk_fma_f32 v[152:153], v[74:75], v[24:25], v[154:155]
	v_pk_fma_f32 v[154:155], v[40:41], v[60:61], v[156:157]
	v_pk_fma_f32 v[156:157], v[42:43], v[26:27], v[158:159]
	v_pk_fma_f32 v[158:159], v[68:69], v[52:53], v[160:161]
	v_pk_fma_f32 v[146:147], v[70:71], v[24:25], v[146:147]
	v_pk_fma_f32 v[148:149], v[38:39], v[26:27], v[148:149]
	v_pk_fma_f32 v[52:53], v[64:65], v[52:53], v[56:57]
	v_pk_fma_f32 v[56:57], v[66:67], v[24:25], v[58:59]
	v_pk_fma_f32 v[30:31], v[34:35], v[26:27], v[30:31]
	ds_read_b128 v[24:27], v134 offset:56320
	v_pk_fma_f32 v[28:29], v[32:33], v[60:61], v[28:29]
	v_pk_fma_f32 v[142:143], v[44:45], v[60:61], v[142:143]
	v_pk_fma_f32 v[160:161], v[36:37], v[60:61], v[162:163]
	s_waitcnt lgkmcnt(0)
	v_lshlrev_b32_e32 v32, 16, v24
	v_and_b32_e32 v33, 0xffff0000, v24
	v_lshlrev_b32_e32 v24, 16, v25
	v_and_b32_e32 v25, 0xffff0000, v25
	v_lshlrev_b32_e32 v34, 16, v26
	v_and_b32_e32 v35, 0xffff0000, v26
	v_lshlrev_b32_e32 v26, 16, v27
	v_and_b32_e32 v27, 0xffff0000, v27
	s_waitcnt vmcnt(6)
	v_pk_fma_f32 v[54:55], v[80:81], v[32:33], v[54:55]
	v_pk_fma_f32 v[58:59], v[82:83], v[24:25], v[62:63]
	v_pk_fma_f32 v[62:63], v[50:51], v[26:27], v[144:145]
	v_pk_fma_f32 v[64:65], v[76:77], v[32:33], v[150:151]
	v_pk_fma_f32 v[66:67], v[78:79], v[24:25], v[152:153]
	v_pk_fma_f32 v[144:145], v[46:47], v[26:27], v[156:157]
	v_pk_fma_f32 v[150:151], v[72:73], v[32:33], v[158:159]
	v_pk_fma_f32 v[146:147], v[74:75], v[24:25], v[146:147]
	v_pk_fma_f32 v[148:149], v[42:43], v[26:27], v[148:149]
	v_pk_fma_f32 v[32:33], v[68:69], v[32:33], v[52:53]
	v_pk_fma_f32 v[52:53], v[70:71], v[24:25], v[56:57]
	v_pk_fma_f32 v[30:31], v[38:39], v[26:27], v[30:31]
	ds_read_b128 v[24:27], v134 offset:58368
	v_pk_fma_f32 v[60:61], v[48:49], v[34:35], v[142:143]
	v_pk_fma_f32 v[142:143], v[44:45], v[34:35], v[154:155]
	v_pk_fma_f32 v[152:153], v[40:41], v[34:35], v[160:161]
	v_pk_fma_f32 v[28:29], v[36:37], v[34:35], v[28:29]
	s_waitcnt lgkmcnt(0)
	v_lshlrev_b32_e32 v34, 16, v24
	v_and_b32_e32 v35, 0xffff0000, v24
	v_lshlrev_b32_e32 v24, 16, v25
	v_and_b32_e32 v25, 0xffff0000, v25
	v_lshlrev_b32_e32 v36, 16, v26
	v_and_b32_e32 v37, 0xffff0000, v26
	v_lshlrev_b32_e32 v26, 16, v27
	v_and_b32_e32 v27, 0xffff0000, v27
	s_waitcnt vmcnt(4)
	v_pk_fma_f32 v[38:39], v[20:21], v[34:35], v[54:55]
	v_pk_fma_f32 v[54:55], v[22:23], v[24:25], v[58:59]
	v_pk_fma_f32 v[56:57], v[16:17], v[36:37], v[60:61]
	v_pk_fma_f32 v[58:59], v[18:19], v[26:27], v[62:63]
	v_pk_fma_f32 v[60:61], v[80:81], v[34:35], v[64:65]
	v_pk_fma_f32 v[62:63], v[82:83], v[24:25], v[66:67]
	v_pk_fma_f32 v[66:67], v[50:51], v[26:27], v[144:145]
	v_pk_fma_f32 v[68:69], v[76:77], v[34:35], v[150:151]
	v_pk_fma_f32 v[70:71], v[78:79], v[24:25], v[146:147]
	v_pk_fma_f32 v[144:145], v[46:47], v[26:27], v[148:149]
	v_pk_fma_f32 v[32:33], v[72:73], v[34:35], v[32:33]
	v_pk_fma_f32 v[34:35], v[74:75], v[24:25], v[52:53]
	v_pk_fma_f32 v[30:31], v[42:43], v[26:27], v[30:31]
	ds_read_b128 v[24:27], v134 offset:60416
	v_pk_fma_f32 v[64:65], v[48:49], v[36:37], v[142:143]
	v_pk_fma_f32 v[142:143], v[44:45], v[36:37], v[152:153]
	v_pk_fma_f32 v[28:29], v[40:41], v[36:37], v[28:29]
	s_waitcnt lgkmcnt(0)
	v_lshlrev_b32_e32 v36, 16, v24
	v_and_b32_e32 v37, 0xffff0000, v24
	v_lshlrev_b32_e32 v24, 16, v25
	v_and_b32_e32 v25, 0xffff0000, v25
	v_lshlrev_b32_e32 v40, 16, v26
	v_and_b32_e32 v41, 0xffff0000, v26
	v_lshlrev_b32_e32 v26, 16, v27
	v_and_b32_e32 v27, 0xffff0000, v27
	s_waitcnt vmcnt(2)
	v_pk_fma_f32 v[38:39], v[12:13], v[36:37], v[38:39]
	v_pk_fma_f32 v[42:43], v[14:15], v[24:25], v[54:55]
	v_pk_fma_f32 v[52:53], v[8:9], v[40:41], v[56:57]
	v_pk_fma_f32 v[54:55], v[10:11], v[26:27], v[58:59]
	v_pk_fma_f32 v[56:57], v[20:21], v[36:37], v[60:61]
	v_pk_fma_f32 v[58:59], v[22:23], v[24:25], v[62:63]
	v_pk_fma_f32 v[60:61], v[16:17], v[40:41], v[64:65]
	v_pk_fma_f32 v[62:63], v[18:19], v[26:27], v[66:67]
	v_pk_fma_f32 v[64:65], v[80:81], v[36:37], v[68:69]
	v_pk_fma_f32 v[66:67], v[82:83], v[24:25], v[70:71]
	v_pk_fma_f32 v[68:69], v[48:49], v[40:41], v[142:143]
	v_pk_fma_f32 v[70:71], v[50:51], v[26:27], v[144:145]
	v_pk_fma_f32 v[32:33], v[76:77], v[36:37], v[32:33]
	v_pk_fma_f32 v[34:35], v[78:79], v[24:25], v[34:35]
	v_pk_fma_f32 v[36:37], v[44:45], v[40:41], v[28:29]
	v_pk_fma_f32 v[40:41], v[46:47], v[26:27], v[30:31]
	ds_read_b128 v[24:27], v134 offset:62464
	s_waitcnt lgkmcnt(0)
	v_lshlrev_b32_e32 v44, 16, v24
	v_and_b32_e32 v45, 0xffff0000, v24
	v_lshlrev_b32_e32 v46, 16, v25
	v_and_b32_e32 v47, 0xffff0000, v25
	v_lshlrev_b32_e32 v72, 16, v26
	v_and_b32_e32 v73, 0xffff0000, v26
	v_lshlrev_b32_e32 v74, 16, v27
	v_and_b32_e32 v75, 0xffff0000, v27
	s_waitcnt vmcnt(0)
	v_pk_fma_f32 v[24:25], v[0:1], v[44:45], v[38:39]
	v_pk_fma_f32 v[26:27], v[2:3], v[46:47], v[42:43]
	v_pk_fma_f32 v[38:39], v[12:13], v[44:45], v[56:57]
	v_pk_fma_f32 v[42:43], v[14:15], v[46:47], v[58:59]
	v_pk_fma_f32 v[56:57], v[20:21], v[44:45], v[64:65]
	v_pk_fma_f32 v[58:59], v[22:23], v[46:47], v[66:67]
	v_pk_fma_f32 v[44:45], v[80:81], v[44:45], v[32:33]
	v_pk_fma_f32 v[46:47], v[82:83], v[46:47], v[34:35]
	ds_read_b128 v[32:35], v134 offset:64512
	v_pk_fma_f32 v[28:29], v[4:5], v[72:73], v[52:53]
	v_pk_fma_f32 v[52:53], v[8:9], v[72:73], v[60:61]
	v_pk_fma_f32 v[60:61], v[16:17], v[72:73], v[68:69]
	v_pk_fma_f32 v[48:49], v[48:49], v[72:73], v[36:37]
	v_pk_fma_f32 v[40:41], v[50:51], v[74:75], v[40:41]
	s_waitcnt lgkmcnt(0)
; #define LAS __attribute__((address_space(3)))
; __device__ __forceinline__ void conv_phase(LAS unsigned char* lds, const bf16_t* U, bf16_t* C, const float* wdw, const float* bdw, const float* lng, const float* lnb,
;                                            int first, int stride, int end, int tid, int wave, int lane) {
;     ...
;             for (int r = 0; r < TT / NWAVES + CW - 1; ++r) {
;                 if (r + 4 < CW) { wt[(r + 4) & 7][0] = wq[0]; wt[(r + 4) & 7][1] = wq[1]; wq += D / 4; asm volatile("" : "+v"(wq)); }
;                 const u32x4 xv = *(const LAS u32x4*)(lds + (4 * wave + r) * 2048 + p * 1024 + lane * 16);
;                 f32x2 x[4];
; #pragma unroll
;                 for (int i = 0; i < 4; ++i) x[i] = (f32x2){__uint_as_float(xv[i] << 16), __uint_as_float(xv[i] & 0xffff0000u)};
; #pragma unroll
;                 for (int j = 0; j < 4; ++j) { const int w = r - j;
;                     if (w >= 0 && w < CW) {
; #pragma unroll
;                         for (int c = 0; c < 4; ++c) { const f32x4 wv = wt[w & 7][c >> 1]; const f32x2 w2 = (c & 1) ? (f32x2){wv.z, wv.w} : (f32x2){wv.x, wv.y}; acc[p][j][c] = __builtin_elementwise_fma(w2, x[c], acc[p][j][c]); } } }
;                 asm volatile("" ::: "memory");
;             }
;             const f32x4 b0 = *(const f32x4*)(bdw + p * 512 + lane * 8), b1 = *(const f32x4*)(bdw + p * 512 + lane * 8 + 4);
; #pragma unroll
;             for (int j = 0; j < 4; ++j) { acc[p][j][0] += (f32x2){b0.x, b0.y}; acc[p][j][1] += (f32x2){b0.z, b0.w}; acc[p][j][2] += (f32x2){b1.x, b1.y}; acc[p][j][3] += (f32x2){b1.z, b1.w}; }
;         }
;         float mean[4], rstd[4];
; #pragma unroll
;         for (int j = 0; j < 4; ++j) { f32x2 s2 = (f32x2){0.f, 0.f};
; #pragma unroll
;             for (int p = 0; p < 2; ++p)
; #pragma unroll
;                 for (int c = 0; c < 4; ++c) s2 += acc[p][j][c];
;             mean[j] = wave_sum(s2.x + s2.y) * (1.f / D); f32x2 q2 = (f32x2){0.f, 0.f};
	v_lshlrev_b32_e32 v66, 16, v34
	v_and_b32_e32 v67, 0xffff0000, v34
	v_lshlrev_b32_e32 v68, 16, v35
	v_and_b32_e32 v69, 0xffff0000, v35
	v_pk_fma_f32 v[30:31], v[6:7], v[74:75], v[54:55]
	v_pk_fma_f32 v[54:55], v[10:11], v[74:75], v[62:63]
	v_pk_fma_f32 v[62:63], v[18:19], v[74:75], v[70:71]
	v_pk_fma_f32 v[48:49], v[16:17], v[66:67], v[48:49]
	v_pk_fma_f32 v[40:41], v[18:19], v[68:69], v[40:41]
	ds_read_b128 v[16:19], v138
	v_lshlrev_b32_e32 v50, 16, v32
	v_and_b32_e32 v51, 0xffff0000, v32
	v_lshlrev_b32_e32 v64, 16, v33
	v_and_b32_e32 v65, 0xffff0000, v33
	v_pk_fma_f32 v[32:33], v[0:1], v[50:51], v[38:39]
	v_pk_fma_f32 v[34:35], v[2:3], v[64:65], v[42:43]
	v_pk_fma_f32 v[38:39], v[6:7], v[68:69], v[54:55]
	v_pk_fma_f32 v[42:43], v[12:13], v[50:51], v[56:57]
	v_pk_fma_f32 v[54:55], v[8:9], v[66:67], v[60:61]
	v_pk_fma_f32 v[56:57], v[10:11], v[68:69], v[62:63]
	v_pk_fma_f32 v[44:45], v[20:21], v[50:51], v[44:45]
	s_waitcnt lgkmcnt(0)
	v_lshlrev_b32_e32 v50, 16, v16
	v_and_b32_e32 v51, 0xffff0000, v16
	v_lshlrev_b32_e32 v60, 16, v18
	v_and_b32_e32 v61, 0xffff0000, v18
	v_lshlrev_b32_e32 v62, 16, v19
	v_and_b32_e32 v63, 0xffff0000, v19
	v_pk_fma_f32 v[36:37], v[4:5], v[66:67], v[52:53]
	v_pk_fma_f32 v[52:53], v[14:15], v[64:65], v[58:59]
	v_lshlrev_b32_e32 v58, 16, v17
	v_and_b32_e32 v59, 0xffff0000, v17
	v_pk_fma_f32 v[16:17], v[0:1], v[50:51], v[42:43]
	v_pk_fma_f32 v[42:43], v[8:9], v[60:61], v[48:49]
	v_pk_fma_f32 v[40:41], v[10:11], v[62:63], v[40:41]
	ds_read_b128 v[8:11], v139
	v_pk_fma_f32 v[46:47], v[22:23], v[64:65], v[46:47]
	v_pk_fma_f32 v[12:13], v[12:13], v[50:51], v[44:45]
	v_pk_fma_f32 v[14:15], v[14:15], v[58:59], v[46:47]
	s_waitcnt lgkmcnt(0)
	v_lshlrev_b32_e32 v46, 16, v8
	v_and_b32_e32 v47, 0xffff0000, v8
	v_lshlrev_b32_e32 v8, 16, v9
	v_and_b32_e32 v9, 0xffff0000, v9
	v_lshlrev_b32_e32 v44, 16, v10
	v_and_b32_e32 v45, 0xffff0000, v10
	v_lshlrev_b32_e32 v10, 16, v11
	v_and_b32_e32 v11, 0xffff0000, v11
	v_pk_fma_f32 v[18:19], v[2:3], v[58:59], v[52:53]
	v_pk_fma_f32 v[20:21], v[4:5], v[60:61], v[54:55]
	v_pk_fma_f32 v[22:23], v[6:7], v[62:63], v[56:57]
	v_pk_fma_f32 v[40:41], v[6:7], v[10:11], v[40:41]
	v_pk_fma_f32 v[42:43], v[4:5], v[44:45], v[42:43]
	v_pk_fma_f32 v[44:45], v[2:3], v[8:9], v[14:15]
	v_pk_fma_f32 v[8:9], v[0:1], v[46:47], v[12:13]
	v_mov_b64_e32 v[0:1], v[188:189]
	v_mov_b64_e32 v[2:3], v[190:191]
	v_mov_b64_e32 v[4:5], v[192:193]
	v_mov_b64_e32 v[6:7], v[194:195]
	s_waitcnt vmcnt(1)
	v_pk_add_f32 v[50:51], v[28:29], v[0:1]
	s_waitcnt vmcnt(0)
	v_pk_add_f32 v[46:47], v[24:25], v[4:5]
	v_pk_add_f32 v[48:49], v[26:27], v[6:7]
	v_pk_add_f32 v[52:53], v[30:31], v[2:3]
	v_pk_add_f32 v[32:33], v[32:33], v[4:5]
	v_pk_add_f32 v[30:31], v[34:35], v[6:7]
	v_pk_add_f32 v[24:25], v[36:37], v[0:1]
	v_pk_add_f32 v[26:27], v[38:39], v[2:3]
	v_pk_add_f32 v[34:35], v[4:5], v[16:17]
	v_pk_add_f32 v[12:13], v[0:1], v[20:21]
	v_pk_add_f32 v[10:11], v[2:3], v[22:23]
	v_pk_add_f32 v[8:9], v[4:5], v[8:9]
	v_pk_add_f32 v[4:5], v[0:1], v[42:43]
	v_pk_add_f32 v[0:1], v[2:3], v[40:41]
	v_cndmask_b32_e64 v2, v224, v226, s[40:41]
	v_cmp_lt_i32_e64 s[40:41], v227, v225
	v_lshlrev_b32_e32 v41, 2, v2
	v_pk_add_f32 v[14:15], v[6:7], v[18:19]
	v_cndmask_b32_e64 v2, v224, v227, s[40:41]
	v_cmp_lt_i32_e64 s[40:41], v228, v225
	v_pk_add_f32 v[6:7], v[6:7], v[44:45]
	v_lshlrev_b32_e32 v44, 2, v2
	v_cndmask_b32_e64 v2, v224, v228, s[40:41]
	v_cmp_lt_i32_e64 s[40:41], v229, v225
	v_lshlrev_b32_e32 v45, 2, v2
	s_nop 0
	v_cndmask_b32_e64 v2, v224, v229, s[40:41]
	v_cmp_lt_i32_e64 s[40:41], v230, v225
	v_lshlrev_b32_e32 v54, 2, v2
	s_nop 0
	v_cndmask_b32_e64 v2, v224, v230, s[40:41]
	v_cmp_lt_i32_e64 s[40:41], v231, v225
	v_lshlrev_b32_e32 v55, 2, v2
	s_nop 0
	v_cndmask_b32_e64 v2, v224, v231, s[40:41]
	v_lshlrev_b32_e32 v76, 2, v2
	v_pk_add_f32 v[2:3], v[128:129], 0 op_sel_hi:[1,0]
	s_nop 0
	v_pk_add_f32 v[2:3], v[130:131], v[2:3]
	s_nop 0
	v_pk_add_f32 v[2:3], v[126:127], v[2:3]
	s_nop 0
	v_pk_add_f32 v[2:3], v[124:125], v[2:3]
	s_nop 0
	v_pk_add_f32 v[2:3], v[2:3], v[46:47]
	s_nop 0
	v_pk_add_f32 v[2:3], v[48:49], v[2:3]
	s_nop 0
	v_pk_add_f32 v[2:3], v[50:51], v[2:3]
	s_nop 0
	v_pk_add_f32 v[2:3], v[52:53], v[2:3]
	s_nop 0
	v_add_f32_e32 v2, v2, v3
	s_nop 1
	v_add_f32_dpp v2, v2, v2 quad_perm:[1,0,3,2] row_mask:0xf bank_mask:0xf
	s_nop 1
	v_add_f32_dpp v2, v2, v2 quad_perm:[2,3,0,1] row_mask:0xf bank_mask:0xf
	s_nop 1
	v_add_f32_dpp v2, v2, v2 row_half_mirror row_mask:0xf bank_mask:0xf
	s_nop 1
	v_add_f32_dpp v2, v2, v2 row_mirror row_mask:0xf bank_mask:0xf
	ds_bpermute_b32 v3, v55, v2
	s_waitcnt lgkmcnt(0)
	v_add_f32_e32 v2, v2, v3
	ds_bpermute_b32 v3, v76, v2
	s_waitcnt lgkmcnt(0)
; __device__ __forceinline__ void conv_phase(LAS unsigned char* lds, const bf16_t* U, bf16_t* C, const float* wdw, const float* bdw, const float* lng, const float* lnb,
;                                            int first, int stride, int end, int tid, int wave, int lane) {
;     ...
;         for (int j = 0; j < 4; ++j) { f32x2 s2 = (f32x2){0.f, 0.f};
; #pragma unroll
;             for (int p = 0; p < 2; ++p)
; #pragma unroll
;                 for (int c = 0; c < 4; ++c) s2 += acc[p][j][c];
;             mean[j] = wave_sum(s2.x + s2.y) * (1.f / D); f32x2 q2 = (f32x2){0.f, 0.f};
; #pragma unroll
;             for (int p = 0; p < 2; ++p)
; #pragma unroll
;                 for (int c = 0; c < 4; ++c) { const f32x2 d = acc[p][j][c] - mean[j]; q2 += d * d; }
;             rstd[j] = rsqrtf(wave_sum(q2.x + q2.y) * (1.f / D) + LN_EPS); }
	v_add_f32_e32 v2, v2, v3
	v_mul_f32_e32 v2, 0x3a800000, v2
	v_pk_add_f32 v[62:63], v[130:131], v[2:3] op_sel_hi:[1,0] neg_lo:[0,1] neg_hi:[0,1]
	v_pk_add_f32 v[66:67], v[128:129], v[2:3] op_sel_hi:[1,0] neg_lo:[0,1] neg_hi:[0,1]
	v_pk_mul_f32 v[16:17], v[62:63], v[62:63]
	v_pk_add_f32 v[58:59], v[126:127], v[2:3] op_sel_hi:[1,0] neg_lo:[0,1] neg_hi:[0,1]
	v_pk_fma_f32 v[16:17], v[66:67], v[66:67], v[16:17]
	v_pk_add_f32 v[56:57], v[124:125], v[2:3] op_sel_hi:[1,0] neg_lo:[0,1] neg_hi:[0,1]
	v_pk_fma_f32 v[16:17], v[58:59], v[58:59], v[16:17]
	v_pk_add_f32 v[28:29], v[46:47], v[2:3] op_sel_hi:[1,0] neg_lo:[0,1] neg_hi:[0,1]
	v_pk_fma_f32 v[16:17], v[56:57], v[56:57], v[16:17]
	v_pk_add_f32 v[22:23], v[48:49], v[2:3] op_sel_hi:[1,0] neg_lo:[0,1] neg_hi:[0,1]
	v_pk_fma_f32 v[16:17], v[28:29], v[28:29], v[16:17]
	v_pk_add_f32 v[18:19], v[50:51], v[2:3] op_sel_hi:[1,0] neg_lo:[0,1] neg_hi:[0,1]
	v_pk_fma_f32 v[16:17], v[22:23], v[22:23], v[16:17]
	s_nop 0
	v_pk_fma_f32 v[20:21], v[18:19], v[18:19], v[16:17]
	v_pk_add_f32 v[16:17], v[52:53], v[2:3] op_sel_hi:[1,0] neg_lo:[0,1] neg_hi:[0,1]
	s_nop 0
	v_pk_fma_f32 v[2:3], v[16:17], v[16:17], v[20:21]
	v_pk_add_f32 v[20:21], v[120:121], 0 op_sel_hi:[1,0]
	s_nop 0
	v_pk_add_f32 v[20:21], v[122:123], v[20:21]
	s_nop 0
	v_pk_add_f32 v[20:21], v[118:119], v[20:21]
	s_nop 0
	v_pk_add_f32 v[20:21], v[116:117], v[20:21]
	s_nop 0
	v_pk_add_f32 v[20:21], v[20:21], v[32:33]
	s_nop 0
	v_pk_add_f32 v[20:21], v[30:31], v[20:21]
	s_nop 0
	v_pk_add_f32 v[20:21], v[24:25], v[20:21]
	s_nop 0
	v_pk_add_f32 v[20:21], v[26:27], v[20:21]
	s_nop 0
	v_add_f32_e32 v20, v20, v21
	s_nop 1
	v_add_f32_dpp v20, v20, v20 quad_perm:[1,0,3,2] row_mask:0xf bank_mask:0xf
	s_nop 1
	v_add_f32_dpp v20, v20, v20 quad_perm:[2,3,0,1] row_mask:0xf bank_mask:0xf
	s_nop 1
	v_add_f32_dpp v20, v20, v20 row_half_mirror row_mask:0xf bank_mask:0xf
	s_nop 1
	v_add_f32_dpp v20, v20, v20 row_mirror row_mask:0xf bank_mask:0xf
	ds_bpermute_b32 v21, v55, v20
	s_waitcnt lgkmcnt(0)
	v_add_f32_e32 v20, v20, v21
	ds_bpermute_b32 v21, v76, v20
	s_waitcnt lgkmcnt(0)
	v_add_f32_e32 v20, v20, v21
	v_mul_f32_e32 v20, 0x3a800000, v20
	v_pk_add_f32 v[68:69], v[122:123], v[20:21] op_sel_hi:[1,0] neg_lo:[0,1] neg_hi:[0,1]
	v_pk_add_f32 v[70:71], v[120:121], v[20:21] op_sel_hi:[1,0] neg_lo:[0,1] neg_hi:[0,1]
	v_pk_mul_f32 v[36:37], v[68:69], v[68:69]
	v_pk_add_f32 v[64:65], v[118:119], v[20:21] op_sel_hi:[1,0] neg_lo:[0,1] neg_hi:[0,1]
	v_pk_fma_f32 v[36:37], v[70:71], v[70:71], v[36:37]
	v_pk_add_f32 v[60:61], v[116:117], v[20:21] op_sel_hi:[1,0] neg_lo:[0,1] neg_hi:[0,1]
	v_pk_fma_f32 v[36:37], v[64:65], v[64:65], v[36:37]
	v_pk_add_f32 v[32:33], v[32:33], v[20:21] op_sel_hi:[1,0] neg_lo:[0,1] neg_hi:[0,1]
	v_pk_fma_f32 v[36:37], v[60:61], v[60:61], v[36:37]
	v_pk_add_f32 v[30:31], v[30:31], v[20:21] op_sel_hi:[1,0] neg_lo:[0,1] neg_hi:[0,1]
	v_pk_fma_f32 v[36:37], v[32:33], v[32:33], v[36:37]
	v_pk_add_f32 v[24:25], v[24:25], v[20:21] op_sel_hi:[1,0] neg_lo:[0,1] neg_hi:[0,1]
	v_pk_fma_f32 v[36:37], v[30:31], v[30:31], v[36:37]
	v_pk_add_f32 v[20:21], v[26:27], v[20:21] op_sel_hi:[1,0] neg_lo:[0,1] neg_hi:[0,1]
	v_pk_fma_f32 v[36:37], v[24:25], v[24:25], v[36:37]
	s_nop 0
	v_pk_fma_f32 v[26:27], v[20:21], v[20:21], v[36:37]
	v_mov_b32_e32 v37, v2
	v_mov_b32_e32 v36, v26
	v_mov_b32_e32 v2, v27
	v_pk_add_f32 v[2:3], v[36:37], v[2:3]
	s_nop 1
	v_add_f32_dpp v2, v2, v2 quad_perm:[1,0,3,2] row_mask:0xf bank_mask:0xf
	v_add_f32_dpp v3, v3, v3 quad_perm:[1,0,3,2] row_mask:0xf bank_mask:0xf
	s_nop 1
	v_add_f32_dpp v2, v2, v2 quad_perm:[2,3,0,1] row_mask:0xf bank_mask:0xf
	v_add_f32_dpp v3, v3, v3 quad_perm:[2,3,0,1] row_mask:0xf bank_mask:0xf
	s_nop 1
	v_add_f32_dpp v2, v2, v2 row_half_mirror row_mask:0xf bank_mask:0xf
	v_add_f32_dpp v3, v3, v3 row_half_mirror row_mask:0xf bank_mask:0xf
	s_nop 1
	v_add_f32_dpp v2, v2, v2 row_mirror row_mask:0xf bank_mask:0xf
	v_add_f32_dpp v3, v3, v3 row_mirror row_mask:0xf bank_mask:0xf
	ds_bpermute_b32 v27, v55, v3
	ds_bpermute_b32 v26, v55, v2
	s_waitcnt lgkmcnt(0)
	v_pk_add_f32 v[2:3], v[2:3], v[26:27]
	ds_bpermute_b32 v27, v76, v3
	ds_bpermute_b32 v26, v76, v2
	s_waitcnt lgkmcnt(0)
	v_pk_add_f32 v[26:27], v[2:3], v[26:27]
	v_mov_b64_e32 v[2:3], s[4:5]
	s_mov_b32 s4, 0x3a800000
	v_pk_fma_f32 v[26:27], v[26:27], s[4:5], v[2:3] op_sel_hi:[1,0,0]
	s_nop 0
	v_mul_f32_e32 v36, 0x4b800000, v27
	v_cmp_gt_f32_e64 s[42:43], s7, v27
	v_cmp_gt_f32_e64 s[40:41], s7, v26
	s_nop 0
	v_cndmask_b32_e64 v27, v27, v36, s[42:43]
	v_rsq_f32_e32 v27, v27
	s_nop 0
	v_mul_f32_e32 v36, 0x45800000, v27
	v_cndmask_b32_e64 v40, v27, v36, s[42:43]
	v_pk_add_f32 v[36:37], v[112:113], 0 op_sel_hi:[1,0]
	v_mul_f32_e32 v27, 0x4b800000, v26
	v_pk_add_f32 v[36:37], v[114:115], v[36:37]
	v_cndmask_b32_e64 v26, v26, v27, s[40:41]
	v_pk_add_f32 v[36:37], v[110:111], v[36:37]
	v_rsq_f32_e32 v26, v26
	v_pk_add_f32 v[36:37], v[108:109], v[36:37]
	v_mul_f32_e32 v27, 0x45800000, v26
	v_pk_add_f32 v[36:37], v[36:37], v[34:35]
	v_cndmask_b32_e64 v26, v26, v27, s[40:41]
	v_pk_add_f32 v[36:37], v[14:15], v[36:37]
	s_nop 0
	v_pk_add_f32 v[36:37], v[12:13], v[36:37]
	s_nop 0
	v_pk_add_f32 v[36:37], v[10:11], v[36:37]
	s_nop 0
	v_add_f32_e32 v27, v36, v37
	s_nop 1
	v_add_f32_dpp v27, v27, v27 quad_perm:[1,0,3,2] row_mask:0xf bank_mask:0xf
	s_nop 1
	v_add_f32_dpp v27, v27, v27 quad_perm:[2,3,0,1] row_mask:0xf bank_mask:0xf
	s_nop 1
	v_add_f32_dpp v27, v27, v27 row_half_mirror row_mask:0xf bank_mask:0xf
	s_nop 1
	v_add_f32_dpp v27, v27, v27 row_mirror row_mask:0xf bank_mask:0xf
	ds_bpermute_b32 v36, v55, v27
	s_waitcnt lgkmcnt(0)
	v_add_f32_e32 v27, v27, v36
	ds_bpermute_b32 v36, v76, v27
	s_waitcnt lgkmcnt(0)
; __device__ __forceinline__ void conv_phase(LAS unsigned char* lds, const bf16_t* U, bf16_t* C, const float* wdw, const float* bdw, const float* lng, const float* lnb,
;                                            int first, int stride, int end, int tid, int wave, int lane) {
;     ...
;             mean[j] = wave_sum(s2.x + s2.y) * (1.f / D); f32x2 q2 = (f32x2){0.f, 0.f};
; #pragma unroll
;             for (int p = 0; p < 2; ++p)
; #pragma unroll
;                 for (int c = 0; c < 4; ++c) { const f32x2 d = acc[p][j][c] - mean[j]; q2 += d * d; }
;             rstd[j] = rsqrtf(wave_sum(q2.x + q2.y) * (1.f / D) + LN_EPS); }
; #pragma unroll
;         for (int p = 0; p < 2; ++p) {
;             const f32x4 g0 = *(const f32x4*)(lng + p * 512 + lane * 8), g1 = *(const f32x4*)(lng + p * 512 + lane * 8 + 4);
;             const f32x4 c0 = *(const f32x4*)(lnb + p * 512 + lane * 8), c1 = *(const f32x4*)(lnb + p * 512 + lane * 8 + 4);
;             const f32x2 gg2[4] = {(f32x2){g0.x, g0.y}, (f32x2){g0.z, g0.w}, (f32x2){g1.x, g1.y}, (f32x2){g1.z, g1.w}}, bb2[4] = {(f32x2){c0.x, c0.y}, (f32x2){c0.z, c0.w}, (f32x2){c1.x, c1.y}, (f32x2){c1.z, c1.w}};
; #pragma unroll
;             for (int j = 0; j < 4; ++j) { unsigned wv[4];
; #pragma unroll
;                 for (int c = 0; c < 4; ++c) {
;                     const f32x2 y = __builtin_elementwise_fma(acc[p][j][c] - mean[j], gg2[c] * rstd[j], bb2[c]);
	v_add_f32_e32 v27, v27, v36
	v_mul_f32_e32 v36, 0x3a800000, v27
	v_pk_add_f32 v[82:83], v[114:115], v[36:37] op_sel_hi:[1,0] neg_lo:[0,1] neg_hi:[0,1]
	v_pk_add_f32 v[112:113], v[112:113], v[36:37] op_sel_hi:[1,0] neg_lo:[0,1] neg_hi:[0,1]
	v_pk_mul_f32 v[38:39], v[82:83], v[82:83]
	v_pk_add_f32 v[78:79], v[110:111], v[36:37] op_sel_hi:[1,0] neg_lo:[0,1] neg_hi:[0,1]
	v_pk_fma_f32 v[38:39], v[112:113], v[112:113], v[38:39]
	v_pk_add_f32 v[72:73], v[108:109], v[36:37] op_sel_hi:[1,0] neg_lo:[0,1] neg_hi:[0,1]
	v_pk_fma_f32 v[38:39], v[78:79], v[78:79], v[38:39]
	v_pk_add_f32 v[50:51], v[34:35], v[36:37] op_sel_hi:[1,0] neg_lo:[0,1] neg_hi:[0,1]
	v_pk_fma_f32 v[38:39], v[72:73], v[72:73], v[38:39]
	v_pk_add_f32 v[46:47], v[14:15], v[36:37] op_sel_hi:[1,0] neg_lo:[0,1] neg_hi:[0,1]
	v_pk_fma_f32 v[34:35], v[50:51], v[50:51], v[38:39]
	v_pk_add_f32 v[38:39], v[12:13], v[36:37] op_sel_hi:[1,0] neg_lo:[0,1] neg_hi:[0,1]
	v_pk_fma_f32 v[14:15], v[46:47], v[46:47], v[34:35]
	v_pk_add_f32 v[34:35], v[10:11], v[36:37] op_sel_hi:[1,0] neg_lo:[0,1] neg_hi:[0,1]
	v_pk_fma_f32 v[12:13], v[38:39], v[38:39], v[14:15]
	s_nop 0
	v_pk_fma_f32 v[10:11], v[34:35], v[34:35], v[12:13]
	v_pk_add_f32 v[12:13], v[104:105], 0 op_sel_hi:[1,0]
	s_nop 0
	v_pk_add_f32 v[12:13], v[106:107], v[12:13]
	s_nop 0
	v_pk_add_f32 v[12:13], v[102:103], v[12:13]
	s_nop 0
	v_pk_add_f32 v[12:13], v[100:101], v[12:13]
	s_nop 0
	v_pk_add_f32 v[12:13], v[12:13], v[8:9]
	s_nop 0
	v_pk_add_f32 v[12:13], v[6:7], v[12:13]
	s_nop 0
	v_pk_add_f32 v[12:13], v[4:5], v[12:13]
	s_nop 0
	v_pk_add_f32 v[12:13], v[0:1], v[12:13]
	s_nop 0
	v_add_f32_e32 v12, v12, v13
	s_nop 1
	v_add_f32_dpp v12, v12, v12 quad_perm:[1,0,3,2] row_mask:0xf bank_mask:0xf
	s_nop 1
	v_add_f32_dpp v12, v12, v12 quad_perm:[2,3,0,1] row_mask:0xf bank_mask:0xf
	s_nop 1
	v_add_f32_dpp v12, v12, v12 row_half_mirror row_mask:0xf bank_mask:0xf
	s_nop 1
	v_add_f32_dpp v12, v12, v12 row_mirror row_mask:0xf bank_mask:0xf
	ds_bpermute_b32 v13, v55, v12
	s_waitcnt lgkmcnt(0)
	v_add_f32_e32 v12, v12, v13
	ds_bpermute_b32 v13, v76, v12
	s_waitcnt lgkmcnt(0)
	v_add_f32_e32 v12, v12, v13
	v_mul_f32_e32 v12, 0x3a800000, v12
	v_pk_add_f32 v[108:109], v[104:105], v[12:13] op_sel_hi:[1,0] neg_lo:[0,1] neg_hi:[0,1]
	v_pk_add_f32 v[104:105], v[106:107], v[12:13] op_sel_hi:[1,0] neg_lo:[0,1] neg_hi:[0,1]
	v_pk_add_f32 v[80:81], v[102:103], v[12:13] op_sel_hi:[1,0] neg_lo:[0,1] neg_hi:[0,1]
	v_pk_mul_f32 v[14:15], v[104:105], v[104:105]
	v_pk_add_f32 v[74:75], v[100:101], v[12:13] op_sel_hi:[1,0] neg_lo:[0,1] neg_hi:[0,1]
	v_pk_fma_f32 v[14:15], v[108:109], v[108:109], v[14:15]
	v_pk_add_f32 v[52:53], v[8:9], v[12:13] op_sel_hi:[1,0] neg_lo:[0,1] neg_hi:[0,1]
	v_pk_fma_f32 v[14:15], v[80:81], v[80:81], v[14:15]
	v_pk_add_f32 v[48:49], v[6:7], v[12:13] op_sel_hi:[1,0] neg_lo:[0,1] neg_hi:[0,1]
	v_pk_fma_f32 v[14:15], v[74:75], v[74:75], v[14:15]
	v_pk_add_f32 v[42:43], v[4:5], v[12:13] op_sel_hi:[1,0] neg_lo:[0,1] neg_hi:[0,1]
	v_pk_fma_f32 v[8:9], v[52:53], v[52:53], v[14:15]
	v_pk_add_f32 v[36:37], v[0:1], v[12:13] op_sel_hi:[1,0] neg_lo:[0,1] neg_hi:[0,1]
	v_pk_fma_f32 v[6:7], v[48:49], v[48:49], v[8:9]
	s_nop 0
	v_pk_fma_f32 v[4:5], v[42:43], v[42:43], v[6:7]
	s_nop 0
	v_pk_fma_f32 v[0:1], v[36:37], v[36:37], v[4:5]
	v_mov_b32_e32 v5, v10
	v_mov_b32_e32 v4, v0
	v_mov_b32_e32 v10, v1
	v_pk_add_f32 v[0:1], v[4:5], v[10:11]
	s_nop 1
	v_add_f32_dpp v0, v0, v0 quad_perm:[1,0,3,2] row_mask:0xf bank_mask:0xf
	v_add_f32_dpp v1, v1, v1 quad_perm:[1,0,3,2] row_mask:0xf bank_mask:0xf
	s_nop 1
	v_add_f32_dpp v0, v0, v0 quad_perm:[2,3,0,1] row_mask:0xf bank_mask:0xf
	v_add_f32_dpp v1, v1, v1 quad_perm:[2,3,0,1] row_mask:0xf bank_mask:0xf
	s_nop 1
	v_add_f32_dpp v0, v0, v0 row_half_mirror row_mask:0xf bank_mask:0xf
	v_add_f32_dpp v1, v1, v1 row_half_mirror row_mask:0xf bank_mask:0xf
	s_nop 1
	v_add_f32_dpp v0, v0, v0 row_mirror row_mask:0xf bank_mask:0xf
	v_add_f32_dpp v1, v1, v1 row_mirror row_mask:0xf bank_mask:0xf
	ds_bpermute_b32 v5, v55, v1
	ds_bpermute_b32 v4, v55, v0
	s_waitcnt lgkmcnt(0)
	v_pk_add_f32 v[0:1], v[0:1], v[4:5]
	ds_bpermute_b32 v5, v76, v1
	ds_bpermute_b32 v4, v76, v0
	v_add_u32_e32 v76, s48, v141
	v_ashrrev_i32_e32 v77, 31, v76
	s_waitcnt lgkmcnt(0)
	v_pk_add_f32 v[0:1], v[0:1], v[4:5]
	s_nop 0
	v_pk_fma_f32 v[0:1], v[0:1], s[4:5], v[2:3] op_sel_hi:[1,0,0]
	s_nop 0
	v_mul_f32_e32 v2, 0x4b800000, v1
	v_cmp_gt_f32_e64 s[42:43], s7, v1
	v_cmp_gt_f32_e64 s[40:41], s7, v0
	s_nop 0
	v_cndmask_b32_e64 v1, v1, v2, s[42:43]
	v_rsq_f32_e32 v1, v1
	s_nop 0
	v_mul_f32_e32 v2, 0x45800000, v1
	v_cndmask_b32_e64 v54, v1, v2, s[42:43]
	v_mul_f32_e32 v1, 0x4b800000, v0
	v_cndmask_b32_e64 v0, v0, v1, s[40:41]
	v_rsq_f32_e32 v0, v0
	s_nop 0
	v_mul_f32_e32 v1, 0x45800000, v0
	v_cndmask_b32_e64 v44, v0, v1, s[40:41]
	v_mov_b64_e32 v[0:1], v[196:197]
	v_mov_b64_e32 v[2:3], v[198:199]
	v_mov_b64_e32 v[8:9], v[200:201]
	v_mov_b64_e32 v[10:11], v[202:203]
	v_mov_b64_e32 v[4:5], v[204:205]
	v_mov_b64_e32 v[6:7], v[206:207]
	v_mov_b64_e32 v[12:13], v[208:209]
	v_mov_b64_e32 v[14:15], v[210:211]
	v_cmp_le_i32_e64 s[40:41], s37, v140
	s_or_b64 s[46:47], s[40:41], s[46:47]
	s_waitcnt vmcnt(2)
	v_pk_mul_f32 v[100:101], v[40:41], v[8:9] op_sel_hi:[0,1]
	s_waitcnt vmcnt(0)
; __device__ __forceinline__ unsigned cvt_pk_bf16(float lo, float hi) { unsigned r; asm volatile("v_cvt_pk_bf16_f32 %0, %1, %2" : "=v"(r) : "v"(lo), "v"(hi)); return r; }
; __device__ __forceinline__ void conv_phase(LAS unsigned char* lds, const bf16_t* U, bf16_t* C, const float* wdw, const float* bdw, const float* lng, const float* lnb,
;                                            int first, int stride, int end, int tid, int wave, int lane) {
;     ...
;         for (int p = 0; p < 2; ++p) {
;             const f32x4 g0 = *(const f32x4*)(lng + p * 512 + lane * 8), g1 = *(const f32x4*)(lng + p * 512 + lane * 8 + 4);
;             const f32x4 c0 = *(const f32x4*)(lnb + p * 512 + lane * 8), c1 = *(const f32x4*)(lnb + p * 512 + lane * 8 + 4);
;             const f32x2 gg2[4] = {(f32x2){g0.x, g0.y}, (f32x2){g0.z, g0.w}, (f32x2){g1.x, g1.y}, (f32x2){g1.z, g1.w}}, bb2[4] = {(f32x2){c0.x, c0.y}, (f32x2){c0.z, c0.w}, (f32x2){c1.x, c1.y}, (f32x2){c1.z, c1.w}};
; #pragma unroll
;             for (int j = 0; j < 4; ++j) { unsigned wv[4];
; #pragma unroll
;                 for (int c = 0; c < 4; ++c) {
;                     const f32x2 y = __builtin_elementwise_fma(acc[p][j][c] - mean[j], gg2[c] * rstd[j], bb2[c]);
;                     const f32x2 ne = y * (-LOG2E);
;                     const f32x2 dd = (f32x2){__builtin_amdgcn_exp2f(ne.x), __builtin_amdgcn_exp2f(ne.y)} + 1.0f;
;                     const f32x2 oo = y * (f32x2){__builtin_amdgcn_rcpf(dd.x), __builtin_amdgcn_rcpf(dd.y)};
;                     wv[c] = cvt_pk_bf16(oo.x, oo.y); }
;                 u32x4 w; w.x = wv[0]; w.y = wv[1]; w.z = wv[2]; w.w = wv[3];
;                 *(u32x4*)(C + (size_t)(t0 + 4 * wave + j) * D + p * 512 + lane * 8) = w; }
	v_pk_fma_f32 v[66:67], v[66:67], v[100:101], v[12:13]
	s_nop 0
	v_pk_mul_f32 v[100:101], v[66:67], s[8:9] op_sel_hi:[1,0]
	s_nop 0
	v_exp_f32_e32 v100, v100
	v_exp_f32_e32 v101, v101
	s_nop 0
	v_pk_add_f32 v[100:101], v[100:101], 1.0 op_sel_hi:[1,0]
	s_nop 0
	v_rcp_f32_e32 v100, v100
	v_rcp_f32_e32 v101, v101
	s_nop 0
	v_pk_mul_f32 v[66:67], v[66:67], v[100:101]
	s_nop 0
	v_cvt_pk_bf16_f32 v100, v66, v67
	v_pk_mul_f32 v[66:67], v[40:41], v[10:11] op_sel_hi:[0,1]
	v_pk_fma_f32 v[62:63], v[62:63], v[66:67], v[14:15]
	s_nop 0
	v_pk_mul_f32 v[66:67], v[62:63], s[8:9] op_sel_hi:[1,0]
	s_nop 0
	v_exp_f32_e32 v66, v66
	v_exp_f32_e32 v67, v67
	s_nop 0
	v_pk_add_f32 v[66:67], v[66:67], 1.0 op_sel_hi:[1,0]
	s_nop 0
	v_rcp_f32_e32 v66, v66
	v_rcp_f32_e32 v67, v67
	s_nop 0
	v_pk_mul_f32 v[62:63], v[62:63], v[66:67]
	s_nop 0
	v_cvt_pk_bf16_f32 v101, v62, v63
	v_pk_mul_f32 v[62:63], v[40:41], v[0:1] op_sel_hi:[0,1]
	v_pk_fma_f32 v[58:59], v[58:59], v[62:63], v[4:5]
	s_nop 0
	v_pk_mul_f32 v[62:63], v[58:59], s[8:9] op_sel_hi:[1,0]
	s_nop 0
	v_exp_f32_e32 v62, v62
	v_exp_f32_e32 v63, v63
	s_nop 0
	v_pk_add_f32 v[62:63], v[62:63], 1.0 op_sel_hi:[1,0]
	s_nop 0
	v_rcp_f32_e32 v62, v62
	v_rcp_f32_e32 v63, v63
	s_nop 0
	v_pk_mul_f32 v[58:59], v[58:59], v[62:63]
	s_nop 0
	v_cvt_pk_bf16_f32 v102, v58, v59
	v_pk_mul_f32 v[58:59], v[40:41], v[2:3] op_sel_hi:[0,1]
	v_pk_fma_f32 v[56:57], v[56:57], v[58:59], v[6:7]
	s_nop 0
	v_pk_mul_f32 v[58:59], v[56:57], s[8:9] op_sel_hi:[1,0]
	s_nop 0
	v_exp_f32_e32 v58, v58
	v_exp_f32_e32 v59, v59
	s_nop 0
	v_pk_add_f32 v[58:59], v[58:59], 1.0 op_sel_hi:[1,0]
	s_nop 0
	v_rcp_f32_e32 v58, v58
	v_rcp_f32_e32 v59, v59
	s_nop 0
	v_pk_mul_f32 v[56:57], v[56:57], v[58:59]
	v_pk_mul_f32 v[58:59], v[26:27], v[8:9] op_sel_hi:[0,1]
	v_pk_fma_f32 v[58:59], v[70:71], v[58:59], v[12:13]
	v_cvt_pk_bf16_f32 v103, v56, v57
	v_lshlrev_b64 v[56:57], 11, v[76:77]
	v_pk_mul_f32 v[62:63], v[58:59], s[8:9] op_sel_hi:[1,0]
	v_lshl_add_u64 v[56:57], v[92:93], 0, v[56:57]
	v_exp_f32_e32 v62, v62
	v_exp_f32_e32 v63, v63
	global_store_dwordx4 v[56:57], v[100:103], off
	v_pk_add_f32 v[62:63], v[62:63], 1.0 op_sel_hi:[1,0]
	s_nop 0
	v_rcp_f32_e32 v62, v62
	v_rcp_f32_e32 v63, v63
	s_nop 0
	v_pk_mul_f32 v[58:59], v[58:59], v[62:63]
	s_nop 0
	v_cvt_pk_bf16_f32 v62, v58, v59
	v_pk_mul_f32 v[58:59], v[26:27], v[10:11] op_sel_hi:[0,1]
	v_pk_fma_f32 v[58:59], v[68:69], v[58:59], v[14:15]
	s_nop 0
	v_pk_mul_f32 v[66:67], v[58:59], s[8:9] op_sel_hi:[1,0]
	s_nop 0
	v_exp_f32_e32 v66, v66
	v_exp_f32_e32 v67, v67
	s_nop 0
	v_pk_add_f32 v[66:67], v[66:67], 1.0 op_sel_hi:[1,0]
	s_nop 0
	v_rcp_f32_e32 v66, v66
	v_rcp_f32_e32 v67, v67
	s_nop 0
	v_pk_mul_f32 v[58:59], v[58:59], v[66:67]
	s_nop 0
	v_cvt_pk_bf16_f32 v63, v58, v59
	v_pk_mul_f32 v[58:59], v[26:27], v[0:1] op_sel_hi:[0,1]
	v_pk_fma_f32 v[58:59], v[64:65], v[58:59], v[4:5]
	s_nop 0
	v_pk_mul_f32 v[64:65], v[58:59], s[8:9] op_sel_hi:[1,0]
	s_nop 0
	v_exp_f32_e32 v64, v64
	v_exp_f32_e32 v65, v65
	s_nop 0
	v_pk_add_f32 v[64:65], v[64:65], 1.0 op_sel_hi:[1,0]
	s_nop 0
	v_rcp_f32_e32 v64, v64
	v_rcp_f32_e32 v65, v65
	s_nop 0
	v_pk_mul_f32 v[58:59], v[58:59], v[64:65]
	s_nop 0
	v_cvt_pk_bf16_f32 v64, v58, v59
	v_pk_mul_f32 v[58:59], v[26:27], v[2:3] op_sel_hi:[0,1]
	v_pk_fma_f32 v[58:59], v[60:61], v[58:59], v[6:7]
	s_nop 0
	v_pk_mul_f32 v[60:61], v[58:59], s[8:9] op_sel_hi:[1,0]
	s_nop 0
	v_exp_f32_e32 v60, v60
	v_exp_f32_e32 v61, v61
	s_nop 0
	v_pk_add_f32 v[60:61], v[60:61], 1.0 op_sel_hi:[1,0]
	s_nop 0
	v_rcp_f32_e32 v60, v60
	v_rcp_f32_e32 v61, v61
	s_nop 0
	v_pk_mul_f32 v[58:59], v[58:59], v[60:61]
	s_nop 0
	v_cvt_pk_bf16_f32 v65, v58, v59
	v_or_b32_e32 v58, 1, v76
	v_ashrrev_i32_e32 v59, 31, v58
	v_lshlrev_b64 v[58:59], 11, v[58:59]
	v_pk_mul_f32 v[60:61], v[8:9], v[54:55] op_sel_hi:[1,0]
	v_lshl_add_u64 v[58:59], v[92:93], 0, v[58:59]
	v_pk_fma_f32 v[60:61], v[112:113], v[60:61], v[12:13]
	global_store_dwordx4 v[58:59], v[62:65], off
	v_pk_mul_f32 v[8:9], v[8:9], v[44:45] op_sel_hi:[1,0]
	s_nop 0
	v_pk_mul_f32 v[62:63], v[60:61], s[8:9] op_sel_hi:[1,0]
	v_pk_fma_f32 v[8:9], v[108:109], v[8:9], v[12:13]
	v_exp_f32_e32 v62, v62
	v_exp_f32_e32 v63, v63
	v_pk_mul_f32 v[12:13], v[8:9], s[8:9] op_sel_hi:[1,0]
	v_pk_add_f32 v[62:63], v[62:63], 1.0 op_sel_hi:[1,0]
	s_nop 0
	v_rcp_f32_e32 v62, v62
	v_rcp_f32_e32 v63, v63
	v_exp_f32_e32 v12, v12
	v_exp_f32_e32 v13, v13
	v_pk_mul_f32 v[60:61], v[60:61], v[62:63]
	s_nop 0
	v_cvt_pk_bf16_f32 v62, v60, v61
	v_pk_mul_f32 v[60:61], v[10:11], v[54:55] op_sel_hi:[1,0]
	v_pk_add_f32 v[12:13], v[12:13], 1.0 op_sel_hi:[1,0]
	v_pk_fma_f32 v[60:61], v[82:83], v[60:61], v[14:15]
	v_rcp_f32_e32 v12, v12
	v_pk_mul_f32 v[64:65], v[60:61], s[8:9] op_sel_hi:[1,0]
	v_rcp_f32_e32 v13, v13
	v_exp_f32_e32 v64, v64
	v_exp_f32_e32 v65, v65
	v_pk_mul_f32 v[10:11], v[10:11], v[44:45] op_sel_hi:[1,0]
	v_pk_mul_f32 v[8:9], v[8:9], v[12:13]
	v_pk_fma_f32 v[10:11], v[104:105], v[10:11], v[14:15]
	v_pk_add_f32 v[64:65], v[64:65], 1.0 op_sel_hi:[1,0]
	v_pk_mul_f32 v[12:13], v[10:11], s[8:9] op_sel_hi:[1,0]
	v_rcp_f32_e32 v64, v64
	v_rcp_f32_e32 v65, v65
	v_exp_f32_e32 v12, v12
	v_exp_f32_e32 v13, v13
	v_pk_mul_f32 v[60:61], v[60:61], v[64:65]
	s_nop 0
	v_cvt_pk_bf16_f32 v63, v60, v61
	v_pk_mul_f32 v[60:61], v[0:1], v[54:55] op_sel_hi:[1,0]
	v_pk_mul_f32 v[0:1], v[0:1], v[44:45] op_sel_hi:[1,0]
	v_pk_fma_f32 v[60:61], v[78:79], v[60:61], v[4:5]
	v_pk_fma_f32 v[0:1], v[80:81], v[0:1], v[4:5]
	v_pk_mul_f32 v[64:65], v[60:61], s[8:9] op_sel_hi:[1,0]
	v_pk_mul_f32 v[4:5], v[0:1], s[8:9] op_sel_hi:[1,0]
	v_exp_f32_e32 v64, v64
	v_exp_f32_e32 v65, v65
	v_exp_f32_e32 v4, v4
	v_exp_f32_e32 v5, v5
; __device__ __forceinline__ unsigned cvt_pk_bf16(float lo, float hi) { unsigned r; asm volatile("v_cvt_pk_bf16_f32 %0, %1, %2" : "=v"(r) : "v"(lo), "v"(hi)); return r; }
; __device__ __forceinline__ void conv_phase(LAS unsigned char* lds, const bf16_t* U, bf16_t* C, const float* wdw, const float* bdw, const float* lng, const float* lnb,
;                                            int first, int stride, int end, int tid, int wave, int lane) {
;     ...
;             for (int j = 0; j < 4; ++j) { unsigned wv[4];
; #pragma unroll
;                 for (int c = 0; c < 4; ++c) {
;                     const f32x2 y = __builtin_elementwise_fma(acc[p][j][c] - mean[j], gg2[c] * rstd[j], bb2[c]);
;                     const f32x2 ne = y * (-LOG2E);
;                     const f32x2 dd = (f32x2){__builtin_amdgcn_exp2f(ne.x), __builtin_amdgcn_exp2f(ne.y)} + 1.0f;
;                     const f32x2 oo = y * (f32x2){__builtin_amdgcn_rcpf(dd.x), __builtin_amdgcn_rcpf(dd.y)};
;                     wv[c] = cvt_pk_bf16(oo.x, oo.y); }
;                 u32x4 w; w.x = wv[0]; w.y = wv[1]; w.z = wv[2]; w.w = wv[3];
;                 *(u32x4*)(C + (size_t)(t0 + 4 * wave + j) * D + p * 512 + lane * 8) = w; }
	v_pk_add_f32 v[12:13], v[12:13], 1.0 op_sel_hi:[1,0]
	v_pk_add_f32 v[64:65], v[64:65], 1.0 op_sel_hi:[1,0]
	v_rcp_f32_e32 v12, v12
	v_rcp_f32_e32 v64, v64
	v_rcp_f32_e32 v65, v65
	v_pk_add_f32 v[4:5], v[4:5], 1.0 op_sel_hi:[1,0]
	v_rcp_f32_e32 v13, v13
	v_rcp_f32_e32 v4, v4
	v_pk_mul_f32 v[60:61], v[60:61], v[64:65]
	v_rcp_f32_e32 v5, v5
	v_cvt_pk_bf16_f32 v64, v60, v61
	v_pk_mul_f32 v[60:61], v[2:3], v[54:55] op_sel_hi:[1,0]
	v_pk_mul_f32 v[10:11], v[10:11], v[12:13]
	v_pk_fma_f32 v[60:61], v[72:73], v[60:61], v[6:7]
	v_pk_mul_f32 v[0:1], v[0:1], v[4:5]
	v_pk_mul_f32 v[66:67], v[60:61], s[8:9] op_sel_hi:[1,0]
	s_nop 0
	v_exp_f32_e32 v66, v66
	v_exp_f32_e32 v67, v67
	s_nop 0
	v_pk_add_f32 v[66:67], v[66:67], 1.0 op_sel_hi:[1,0]
	s_nop 0
	v_rcp_f32_e32 v66, v66
	v_rcp_f32_e32 v67, v67
	s_nop 0
	v_pk_mul_f32 v[60:61], v[60:61], v[66:67]
	s_nop 0
	v_cvt_pk_bf16_f32 v65, v60, v61
	v_or_b32_e32 v60, 2, v76
	v_ashrrev_i32_e32 v61, 31, v60
	v_lshlrev_b64 v[60:61], 11, v[60:61]
	v_lshl_add_u64 v[60:61], v[92:93], 0, v[60:61]
	global_store_dwordx4 v[60:61], v[62:65], off
	v_cvt_pk_bf16_f32 v8, v8, v9
	v_cvt_pk_bf16_f32 v9, v10, v11
	v_cvt_pk_bf16_f32 v10, v0, v1
	v_pk_mul_f32 v[0:1], v[2:3], v[44:45] op_sel_hi:[1,0]
	s_nop 0
	v_pk_fma_f32 v[0:1], v[74:75], v[0:1], v[6:7]
	s_nop 0
	v_pk_mul_f32 v[2:3], v[0:1], s[8:9] op_sel_hi:[1,0]
	s_nop 0
	v_exp_f32_e32 v2, v2
	v_exp_f32_e32 v3, v3
	s_nop 0
	v_pk_add_f32 v[2:3], v[2:3], 1.0 op_sel_hi:[1,0]
	s_nop 0
	v_rcp_f32_e32 v2, v2
	v_rcp_f32_e32 v3, v3
	s_nop 0
	v_pk_mul_f32 v[0:1], v[0:1], v[2:3]
	s_nop 0
	v_cvt_pk_bf16_f32 v11, v0, v1
	v_or_b32_e32 v0, 3, v76
	v_ashrrev_i32_e32 v1, 31, v0
	v_lshlrev_b64 v[0:1], 11, v[0:1]
	v_lshl_add_u64 v[62:63], v[92:93], 0, v[0:1]
	global_store_dwordx4 v[62:63], v[8:11], off
	v_mov_b64_e32 v[0:1], v[212:213]
	v_mov_b64_e32 v[2:3], v[214:215]
	s_nop 0
	v_mov_b64_e32 v[8:9], v[236:237]
	v_mov_b64_e32 v[10:11], v[238:239]
	v_mov_b64_e32 v[4:5], v[240:241]
	v_mov_b64_e32 v[6:7], v[242:243]
	v_mov_b64_e32 v[12:13], v[244:245]
	v_mov_b64_e32 v[14:15], v[246:247]
	v_pk_mul_f32 v[64:65], v[40:41], v[8:9] op_sel_hi:[0,1]
	v_pk_fma_f32 v[28:29], v[28:29], v[64:65], v[12:13]
	s_nop 0
	v_pk_mul_f32 v[64:65], v[28:29], s[8:9] op_sel_hi:[1,0]
	s_nop 0
	v_exp_f32_e32 v64, v64
	v_exp_f32_e32 v65, v65
	s_nop 0
	v_pk_add_f32 v[64:65], v[64:65], 1.0 op_sel_hi:[1,0]
	s_nop 0
	v_rcp_f32_e32 v64, v64
	v_rcp_f32_e32 v65, v65
	s_nop 0
	v_pk_mul_f32 v[28:29], v[28:29], v[64:65]
	s_nop 0
	v_cvt_pk_bf16_f32 v64, v28, v29
	v_pk_mul_f32 v[28:29], v[40:41], v[10:11] op_sel_hi:[0,1]
	v_pk_fma_f32 v[22:23], v[22:23], v[28:29], v[14:15]
	s_nop 0
	v_pk_mul_f32 v[28:29], v[22:23], s[8:9] op_sel_hi:[1,0]
	s_nop 0
	v_exp_f32_e32 v28, v28
	v_exp_f32_e32 v29, v29
	s_nop 0
	v_pk_add_f32 v[28:29], v[28:29], 1.0 op_sel_hi:[1,0]
	s_nop 0
	v_rcp_f32_e32 v28, v28
	v_rcp_f32_e32 v29, v29
	s_nop 0
	v_pk_mul_f32 v[22:23], v[22:23], v[28:29]
	s_nop 0
	v_cvt_pk_bf16_f32 v65, v22, v23
	v_pk_mul_f32 v[22:23], v[40:41], v[0:1] op_sel_hi:[0,1]
	v_pk_fma_f32 v[18:19], v[18:19], v[22:23], v[4:5]
	s_nop 0
	v_pk_mul_f32 v[22:23], v[18:19], s[8:9] op_sel_hi:[1,0]
	s_nop 0
	v_exp_f32_e32 v22, v22
	v_exp_f32_e32 v23, v23
	s_nop 0
	v_pk_add_f32 v[22:23], v[22:23], 1.0 op_sel_hi:[1,0]
	s_nop 0
	v_rcp_f32_e32 v22, v22
	v_rcp_f32_e32 v23, v23
	s_nop 0
	v_pk_mul_f32 v[18:19], v[18:19], v[22:23]
	s_nop 0
	v_cvt_pk_bf16_f32 v66, v18, v19
	v_pk_mul_f32 v[18:19], v[40:41], v[2:3] op_sel_hi:[0,1]
	v_pk_fma_f32 v[16:17], v[16:17], v[18:19], v[6:7]
	s_nop 0
	v_pk_mul_f32 v[18:19], v[16:17], s[8:9] op_sel_hi:[1,0]
	s_nop 0
	v_exp_f32_e32 v18, v18
	v_exp_f32_e32 v19, v19
	s_nop 0
	v_pk_add_f32 v[18:19], v[18:19], 1.0 op_sel_hi:[1,0]
	s_nop 0
	v_rcp_f32_e32 v18, v18
	v_rcp_f32_e32 v19, v19
	s_nop 0
	v_pk_mul_f32 v[16:17], v[16:17], v[18:19]
	s_nop 0
	v_cvt_pk_bf16_f32 v67, v16, v17
	v_pk_mul_f32 v[16:17], v[26:27], v[8:9] op_sel_hi:[0,1]
	v_pk_fma_f32 v[16:17], v[32:33], v[16:17], v[12:13]
	global_store_dwordx4 v[56:57], v[64:67], off offset:1024
	v_pk_mul_f32 v[18:19], v[16:17], s[8:9] op_sel_hi:[1,0]
	s_nop 0
	v_exp_f32_e32 v18, v18
	v_exp_f32_e32 v19, v19
	s_nop 0
	v_pk_add_f32 v[18:19], v[18:19], 1.0 op_sel_hi:[1,0]
	s_nop 0
	v_rcp_f32_e32 v18, v18
	v_rcp_f32_e32 v19, v19
	s_nop 0
	v_pk_mul_f32 v[16:17], v[16:17], v[18:19]
	v_pk_mul_f32 v[18:19], v[26:27], v[10:11] op_sel_hi:[0,1]
	v_pk_fma_f32 v[18:19], v[30:31], v[18:19], v[14:15]
	v_cvt_pk_bf16_f32 v16, v16, v17
	s_nop 0
	v_pk_mul_f32 v[22:23], v[18:19], s[8:9] op_sel_hi:[1,0]
	s_nop 0
	v_exp_f32_e32 v22, v22
; __device__ __forceinline__ unsigned cvt_pk_bf16(float lo, float hi) { unsigned r; asm volatile("v_cvt_pk_bf16_f32 %0, %1, %2" : "=v"(r) : "v"(lo), "v"(hi)); return r; }
; __device__ __forceinline__ void conv_phase(LAS unsigned char* lds, const bf16_t* U, bf16_t* C, const float* wdw, const float* bdw, const float* lng, const float* lnb,
;                                            int first, int stride, int end, int tid, int wave, int lane) {
;     ...
;             for (int j = 0; j < 4; ++j) { unsigned wv[4];
; #pragma unroll
;                 for (int c = 0; c < 4; ++c) {
;                     const f32x2 y = __builtin_elementwise_fma(acc[p][j][c] - mean[j], gg2[c] * rstd[j], bb2[c]);
;                     const f32x2 ne = y * (-LOG2E);
;                     const f32x2 dd = (f32x2){__builtin_amdgcn_exp2f(ne.x), __builtin_amdgcn_exp2f(ne.y)} + 1.0f;
;                     const f32x2 oo = y * (f32x2){__builtin_amdgcn_rcpf(dd.x), __builtin_amdgcn_rcpf(dd.y)};
;                     wv[c] = cvt_pk_bf16(oo.x, oo.y); }
;                 u32x4 w; w.x = wv[0]; w.y = wv[1]; w.z = wv[2]; w.w = wv[3];
;                 *(u32x4*)(C + (size_t)(t0 + 4 * wave + j) * D + p * 512 + lane * 8) = w; }
;         }
;         asm volatile("s_waitcnt lgkmcnt(0)" ::: "memory"); __builtin_amdgcn_s_barrier(); asm volatile("" ::: "memory");
	v_exp_f32_e32 v23, v23
	s_nop 0
	v_pk_add_f32 v[22:23], v[22:23], 1.0 op_sel_hi:[1,0]
	s_nop 0
	v_rcp_f32_e32 v22, v22
	v_rcp_f32_e32 v23, v23
	s_nop 0
	v_pk_mul_f32 v[18:19], v[18:19], v[22:23]
	s_nop 0
	v_cvt_pk_bf16_f32 v17, v18, v19
	v_pk_mul_f32 v[18:19], v[26:27], v[0:1] op_sel_hi:[0,1]
	v_pk_fma_f32 v[18:19], v[24:25], v[18:19], v[4:5]
	s_nop 0
	v_pk_mul_f32 v[22:23], v[18:19], s[8:9] op_sel_hi:[1,0]
	s_nop 0
	v_exp_f32_e32 v22, v22
	v_exp_f32_e32 v23, v23
	s_nop 0
	v_pk_add_f32 v[22:23], v[22:23], 1.0 op_sel_hi:[1,0]
	s_nop 0
	v_rcp_f32_e32 v22, v22
	v_rcp_f32_e32 v23, v23
	s_nop 0
	v_pk_mul_f32 v[18:19], v[18:19], v[22:23]
	v_pk_mul_f32 v[22:23], v[26:27], v[2:3] op_sel_hi:[0,1]
	v_pk_fma_f32 v[20:21], v[20:21], v[22:23], v[6:7]
	v_cvt_pk_bf16_f32 v18, v18, v19
	s_nop 0
	v_pk_mul_f32 v[22:23], v[20:21], s[8:9] op_sel_hi:[1,0]
	s_nop 0
	v_exp_f32_e32 v22, v22
	v_exp_f32_e32 v23, v23
	s_nop 0
	v_pk_add_f32 v[22:23], v[22:23], 1.0 op_sel_hi:[1,0]
	s_nop 0
	v_rcp_f32_e32 v22, v22
	v_rcp_f32_e32 v23, v23
	s_nop 0
	v_pk_mul_f32 v[20:21], v[20:21], v[22:23]
	s_nop 0
	v_cvt_pk_bf16_f32 v19, v20, v21
	global_store_dwordx4 v[58:59], v[16:19], off offset:1024
	s_nop 1
	v_pk_mul_f32 v[16:17], v[54:55], v[8:9] op_sel_hi:[0,1]
	v_pk_fma_f32 v[16:17], v[50:51], v[16:17], v[12:13]
	v_pk_mul_f32 v[8:9], v[44:45], v[8:9] op_sel_hi:[0,1]
	v_pk_mul_f32 v[18:19], v[16:17], s[8:9] op_sel_hi:[1,0]
	v_pk_fma_f32 v[8:9], v[52:53], v[8:9], v[12:13]
	v_exp_f32_e32 v18, v18
	v_exp_f32_e32 v19, v19
	v_pk_mul_f32 v[12:13], v[8:9], s[8:9] op_sel_hi:[1,0]
	v_pk_add_f32 v[18:19], v[18:19], 1.0 op_sel_hi:[1,0]
	s_nop 0
	v_rcp_f32_e32 v18, v18
	v_rcp_f32_e32 v19, v19
	v_exp_f32_e32 v12, v12
	v_exp_f32_e32 v13, v13
	v_pk_mul_f32 v[16:17], v[16:17], v[18:19]
	v_pk_mul_f32 v[18:19], v[54:55], v[10:11] op_sel_hi:[0,1]
	v_pk_fma_f32 v[18:19], v[46:47], v[18:19], v[14:15]
	v_cvt_pk_bf16_f32 v16, v16, v17
	v_pk_add_f32 v[12:13], v[12:13], 1.0 op_sel_hi:[1,0]
	v_pk_mul_f32 v[20:21], v[18:19], s[8:9] op_sel_hi:[1,0]
	v_rcp_f32_e32 v12, v12
	v_exp_f32_e32 v20, v20
	v_exp_f32_e32 v21, v21
	v_rcp_f32_e32 v13, v13
	v_pk_mul_f32 v[10:11], v[44:45], v[10:11] op_sel_hi:[0,1]
	v_pk_fma_f32 v[10:11], v[48:49], v[10:11], v[14:15]
	v_pk_add_f32 v[20:21], v[20:21], 1.0 op_sel_hi:[1,0]
	v_pk_mul_f32 v[8:9], v[8:9], v[12:13]
	v_rcp_f32_e32 v20, v20
	v_rcp_f32_e32 v21, v21
	v_pk_mul_f32 v[12:13], v[10:11], s[8:9] op_sel_hi:[1,0]
	v_pk_mul_f32 v[18:19], v[18:19], v[20:21]
	s_nop 0
	v_cvt_pk_bf16_f32 v17, v18, v19
	v_pk_mul_f32 v[18:19], v[54:55], v[0:1] op_sel_hi:[0,1]
	v_pk_fma_f32 v[18:19], v[38:39], v[18:19], v[4:5]
	v_pk_mul_f32 v[0:1], v[44:45], v[0:1] op_sel_hi:[0,1]
	v_pk_mul_f32 v[20:21], v[18:19], s[8:9] op_sel_hi:[1,0]
	v_pk_fma_f32 v[0:1], v[42:43], v[0:1], v[4:5]
	v_exp_f32_e32 v20, v20
	v_exp_f32_e32 v21, v21
	v_pk_mul_f32 v[4:5], v[0:1], s[8:9] op_sel_hi:[1,0]
	v_exp_f32_e32 v12, v12
	v_exp_f32_e32 v13, v13
	v_pk_add_f32 v[20:21], v[20:21], 1.0 op_sel_hi:[1,0]
	v_exp_f32_e32 v4, v4
	v_rcp_f32_e32 v20, v20
	v_rcp_f32_e32 v21, v21
	v_exp_f32_e32 v5, v5
	v_pk_add_f32 v[12:13], v[12:13], 1.0 op_sel_hi:[1,0]
	v_pk_mul_f32 v[18:19], v[18:19], v[20:21]
	v_pk_mul_f32 v[20:21], v[54:55], v[2:3] op_sel_hi:[0,1]
	v_pk_fma_f32 v[20:21], v[34:35], v[20:21], v[6:7]
	v_pk_add_f32 v[4:5], v[4:5], 1.0 op_sel_hi:[1,0]
	v_pk_mul_f32 v[22:23], v[20:21], s[8:9] op_sel_hi:[1,0]
	v_rcp_f32_e32 v12, v12
	v_exp_f32_e32 v22, v22
	v_exp_f32_e32 v23, v23
	v_rcp_f32_e32 v13, v13
	v_rcp_f32_e32 v4, v4
	v_rcp_f32_e32 v5, v5
	v_pk_add_f32 v[22:23], v[22:23], 1.0 op_sel_hi:[1,0]
	v_pk_mul_f32 v[10:11], v[10:11], v[12:13]
	v_rcp_f32_e32 v22, v22
	v_rcp_f32_e32 v23, v23
	v_pk_mul_f32 v[0:1], v[0:1], v[4:5]
	v_cvt_pk_bf16_f32 v18, v18, v19
	v_pk_mul_f32 v[20:21], v[20:21], v[22:23]
	s_nop 0
	v_cvt_pk_bf16_f32 v19, v20, v21
	global_store_dwordx4 v[60:61], v[16:19], off offset:1024
	v_cvt_pk_bf16_f32 v8, v8, v9
	v_cvt_pk_bf16_f32 v9, v10, v11
	v_cvt_pk_bf16_f32 v10, v0, v1
	v_pk_mul_f32 v[0:1], v[44:45], v[2:3] op_sel_hi:[0,1]
	v_pk_fma_f32 v[0:1], v[36:37], v[0:1], v[6:7]
	s_nop 0
	v_pk_mul_f32 v[2:3], v[0:1], s[8:9] op_sel_hi:[1,0]
	s_nop 0
	v_exp_f32_e32 v2, v2
	v_exp_f32_e32 v3, v3
	s_nop 0
	v_pk_add_f32 v[2:3], v[2:3], 1.0 op_sel_hi:[1,0]
	s_nop 0
	v_rcp_f32_e32 v2, v2
	v_rcp_f32_e32 v3, v3
	s_nop 0
	v_pk_mul_f32 v[0:1], v[0:1], v[2:3]
	s_nop 0
	v_cvt_pk_bf16_f32 v11, v0, v1
	global_store_dwordx4 v[62:63], v[8:11], off offset:1024
	s_waitcnt lgkmcnt(0)
	s_barrier
	s_andn2_b64 exec, exec, s[46:47]
	s_cbranch_execz .LBB0_95
